# phase-0 adaLN GEMV item: 18 staging loads in flight; W stream in 4 double-buffered batches of 16 row loads (dead VGPRs) instead of 16 serialized groups of 4; plus transpose 32-in-flight
# speedup vs baseline: 1.0047x; 1.0044x over previous
.LBB0_73:
	s_andn2_b64 vcc, exec, s[6:7]
	s_cbranch_vccnz .LBB0_81
	v_mov_b64_e32 v[2:3], v[62:63]
	global_load_dword v122, v[2:3], off
	v_lshl_add_u64 v[2:3], v[2:3], 0, s[74:75]
	global_load_dword v123, v[2:3], off
	v_lshl_add_u64 v[2:3], v[2:3], 0, s[74:75]
	global_load_dword v124, v[2:3], off
	v_lshl_add_u64 v[2:3], v[2:3], 0, s[74:75]
	global_load_dword v125, v[2:3], off
	v_lshl_add_u64 v[2:3], v[2:3], 0, s[74:75]
	global_load_dword v126, v[2:3], off
	v_lshl_add_u64 v[2:3], v[2:3], 0, s[74:75]
	global_load_dword v127, v[2:3], off
	v_lshl_add_u64 v[2:3], v[2:3], 0, s[74:75]
	global_load_dword v128, v[2:3], off
	v_lshl_add_u64 v[2:3], v[2:3], 0, s[74:75]
	global_load_dword v129, v[2:3], off
	v_lshl_add_u64 v[2:3], v[2:3], 0, s[74:75]
	global_load_dword v130, v[2:3], off
	v_lshl_add_u64 v[2:3], v[2:3], 0, s[74:75]
	global_load_dword v131, v[2:3], off
	v_lshl_add_u64 v[2:3], v[2:3], 0, s[74:75]
	global_load_dword v132, v[2:3], off
	v_lshl_add_u64 v[2:3], v[2:3], 0, s[74:75]
	global_load_dword v133, v[2:3], off
	v_lshl_add_u64 v[2:3], v[2:3], 0, s[74:75]
	global_load_dword v134, v[2:3], off
	v_lshl_add_u64 v[2:3], v[2:3], 0, s[74:75]
	global_load_dword v135, v[2:3], off
	v_lshl_add_u64 v[2:3], v[2:3], 0, s[74:75]
	global_load_dword v136, v[2:3], off
	v_lshl_add_u64 v[2:3], v[2:3], 0, s[74:75]
	global_load_dword v137, v[2:3], off
	v_lshlrev_b32_e32 v56, 2, v1
	v_lshl_add_u64 v[6:7], s[42:43], 0, v[56:57]
	global_load_dword v138, v[6:7], off
	global_load_dword v139, v[6:7], off offset:2048
	s_waitcnt vmcnt(0)
	v_mul_f32_e32 v7, 0xbfb8aa3b, v122
	v_exp_f32_e32 v7, v7
	s_nop 0
	v_add_f32_e32 v7, 1.0, v7
	v_div_scale_f32 v8, s[14:15], v7, v7, v122
	v_rcp_f32_e32 v9, v8
	v_div_scale_f32 v10, vcc, v122, v7, v122
	v_fma_f32 v11, -v8, v9, 1.0
	v_fmac_f32_e32 v9, v11, v9
	v_mul_f32_e32 v11, v10, v9
	v_fma_f32 v12, -v8, v11, v10
	v_fmac_f32_e32 v11, v12, v9
	v_fma_f32 v8, -v8, v11, v10
	s_nop 1
	v_div_fmas_f32 v8, v8, v9, v11
	v_div_fixup_f32 v6, v8, v7, v122
	ds_write_b32 v55, v6
	v_mul_f32_e32 v7, 0xbfb8aa3b, v123
	v_exp_f32_e32 v7, v7
	s_nop 0
	v_add_f32_e32 v7, 1.0, v7
	v_div_scale_f32 v8, s[14:15], v7, v7, v123
	v_rcp_f32_e32 v9, v8
	v_div_scale_f32 v10, vcc, v123, v7, v123
	v_fma_f32 v11, -v8, v9, 1.0
	v_fmac_f32_e32 v9, v11, v9
	v_mul_f32_e32 v11, v10, v9
	v_fma_f32 v12, -v8, v11, v10
	v_fmac_f32_e32 v11, v12, v9
	v_fma_f32 v8, -v8, v11, v10
	s_nop 1
	v_div_fmas_f32 v8, v8, v9, v11
	v_div_fixup_f32 v6, v8, v7, v123
	ds_write_b32 v55, v6 offset:2048
	v_mul_f32_e32 v7, 0xbfb8aa3b, v124
	v_exp_f32_e32 v7, v7
	s_nop 0
	v_add_f32_e32 v7, 1.0, v7
	v_div_scale_f32 v8, s[14:15], v7, v7, v124
	v_rcp_f32_e32 v9, v8
	v_div_scale_f32 v10, vcc, v124, v7, v124
	v_fma_f32 v11, -v8, v9, 1.0
	v_fmac_f32_e32 v9, v11, v9
	v_mul_f32_e32 v11, v10, v9
	v_fma_f32 v12, -v8, v11, v10
	v_fmac_f32_e32 v11, v12, v9
	v_fma_f32 v8, -v8, v11, v10
	s_nop 1
	v_div_fmas_f32 v8, v8, v9, v11
	v_div_fixup_f32 v6, v8, v7, v124
	ds_write_b32 v55, v6 offset:4096
	v_mul_f32_e32 v7, 0xbfb8aa3b, v125
	v_exp_f32_e32 v7, v7
	s_nop 0
	v_add_f32_e32 v7, 1.0, v7
	v_div_scale_f32 v8, s[14:15], v7, v7, v125
	v_rcp_f32_e32 v9, v8
	v_div_scale_f32 v10, vcc, v125, v7, v125
	v_fma_f32 v11, -v8, v9, 1.0
	v_fmac_f32_e32 v9, v11, v9
	v_mul_f32_e32 v11, v10, v9
	v_fma_f32 v12, -v8, v11, v10
	v_fmac_f32_e32 v11, v12, v9
	v_fma_f32 v8, -v8, v11, v10
	s_nop 1
	v_div_fmas_f32 v8, v8, v9, v11
	v_div_fixup_f32 v6, v8, v7, v125
	ds_write_b32 v55, v6 offset:6144
	v_mul_f32_e32 v7, 0xbfb8aa3b, v126
	v_exp_f32_e32 v7, v7
	s_nop 0
	v_add_f32_e32 v7, 1.0, v7
	v_div_scale_f32 v8, s[14:15], v7, v7, v126
	v_rcp_f32_e32 v9, v8
	v_div_scale_f32 v10, vcc, v126, v7, v126
	v_fma_f32 v11, -v8, v9, 1.0
	v_fmac_f32_e32 v9, v11, v9
	v_mul_f32_e32 v11, v10, v9
	v_fma_f32 v12, -v8, v11, v10
	v_fmac_f32_e32 v11, v12, v9
	v_fma_f32 v8, -v8, v11, v10
	s_nop 1
	v_div_fmas_f32 v8, v8, v9, v11
	v_div_fixup_f32 v6, v8, v7, v126
	ds_write_b32 v55, v6 offset:8192
	v_mul_f32_e32 v7, 0xbfb8aa3b, v127
	v_exp_f32_e32 v7, v7
	s_nop 0
	v_add_f32_e32 v7, 1.0, v7
	v_div_scale_f32 v8, s[14:15], v7, v7, v127
	v_rcp_f32_e32 v9, v8
	v_div_scale_f32 v10, vcc, v127, v7, v127
	v_fma_f32 v11, -v8, v9, 1.0
	v_fmac_f32_e32 v9, v11, v9
	v_mul_f32_e32 v11, v10, v9
	v_fma_f32 v12, -v8, v11, v10
	v_fmac_f32_e32 v11, v12, v9
	v_fma_f32 v8, -v8, v11, v10
	s_nop 1
	v_div_fmas_f32 v8, v8, v9, v11
	v_div_fixup_f32 v6, v8, v7, v127
	ds_write_b32 v55, v6 offset:10240
	v_mul_f32_e32 v7, 0xbfb8aa3b, v128
	v_exp_f32_e32 v7, v7
	s_nop 0
	v_add_f32_e32 v7, 1.0, v7
	v_div_scale_f32 v8, s[14:15], v7, v7, v128
	v_rcp_f32_e32 v9, v8
	v_div_scale_f32 v10, vcc, v128, v7, v128
	v_fma_f32 v11, -v8, v9, 1.0
	v_fmac_f32_e32 v9, v11, v9
	v_mul_f32_e32 v11, v10, v9
	v_fma_f32 v12, -v8, v11, v10
	v_fmac_f32_e32 v11, v12, v9
	v_fma_f32 v8, -v8, v11, v10
	s_nop 1
	v_div_fmas_f32 v8, v8, v9, v11
	v_div_fixup_f32 v6, v8, v7, v128
	ds_write_b32 v55, v6 offset:12288
	v_mul_f32_e32 v7, 0xbfb8aa3b, v129
	v_exp_f32_e32 v7, v7
	s_nop 0
	v_add_f32_e32 v7, 1.0, v7
	v_div_scale_f32 v8, s[14:15], v7, v7, v129
	v_rcp_f32_e32 v9, v8
	v_div_scale_f32 v10, vcc, v129, v7, v129
	v_fma_f32 v11, -v8, v9, 1.0
	v_fmac_f32_e32 v9, v11, v9
	v_mul_f32_e32 v11, v10, v9
	v_fma_f32 v12, -v8, v11, v10
	v_fmac_f32_e32 v11, v12, v9
	v_fma_f32 v8, -v8, v11, v10
	s_nop 1
	v_div_fmas_f32 v8, v8, v9, v11
	v_div_fixup_f32 v6, v8, v7, v129
	ds_write_b32 v55, v6 offset:14336
	v_mul_f32_e32 v7, 0xbfb8aa3b, v130
	v_exp_f32_e32 v7, v7
	s_nop 0
	v_add_f32_e32 v7, 1.0, v7
	v_div_scale_f32 v8, s[14:15], v7, v7, v130
	v_rcp_f32_e32 v9, v8
	v_div_scale_f32 v10, vcc, v130, v7, v130
	v_fma_f32 v11, -v8, v9, 1.0
	v_fmac_f32_e32 v9, v11, v9
	v_mul_f32_e32 v11, v10, v9
	v_fma_f32 v12, -v8, v11, v10
	v_fmac_f32_e32 v11, v12, v9
	v_fma_f32 v8, -v8, v11, v10
	s_nop 1
	v_div_fmas_f32 v8, v8, v9, v11
	v_div_fixup_f32 v6, v8, v7, v130
	ds_write_b32 v55, v6 offset:16384
	v_mul_f32_e32 v7, 0xbfb8aa3b, v131
	v_exp_f32_e32 v7, v7
	s_nop 0
	v_add_f32_e32 v7, 1.0, v7
	v_div_scale_f32 v8, s[14:15], v7, v7, v131
	v_rcp_f32_e32 v9, v8
	v_div_scale_f32 v10, vcc, v131, v7, v131
	v_fma_f32 v11, -v8, v9, 1.0
	v_fmac_f32_e32 v9, v11, v9
	v_mul_f32_e32 v11, v10, v9
	v_fma_f32 v12, -v8, v11, v10
	v_fmac_f32_e32 v11, v12, v9
	v_fma_f32 v8, -v8, v11, v10
	s_nop 1
	v_div_fmas_f32 v8, v8, v9, v11
	v_div_fixup_f32 v6, v8, v7, v131
	ds_write_b32 v55, v6 offset:18432
	v_mul_f32_e32 v7, 0xbfb8aa3b, v132
	v_exp_f32_e32 v7, v7
	s_nop 0
	v_add_f32_e32 v7, 1.0, v7
	v_div_scale_f32 v8, s[14:15], v7, v7, v132
	v_rcp_f32_e32 v9, v8
	v_div_scale_f32 v10, vcc, v132, v7, v132
	v_fma_f32 v11, -v8, v9, 1.0
	v_fmac_f32_e32 v9, v11, v9
	v_mul_f32_e32 v11, v10, v9
	v_fma_f32 v12, -v8, v11, v10
	v_fmac_f32_e32 v11, v12, v9
	v_fma_f32 v8, -v8, v11, v10
	s_nop 1
	v_div_fmas_f32 v8, v8, v9, v11
	v_div_fixup_f32 v6, v8, v7, v132
	ds_write_b32 v55, v6 offset:20480
	v_mul_f32_e32 v7, 0xbfb8aa3b, v133
	v_exp_f32_e32 v7, v7
	s_nop 0
	v_add_f32_e32 v7, 1.0, v7
	v_div_scale_f32 v8, s[14:15], v7, v7, v133
	v_rcp_f32_e32 v9, v8
	v_div_scale_f32 v10, vcc, v133, v7, v133
	v_fma_f32 v11, -v8, v9, 1.0
	v_fmac_f32_e32 v9, v11, v9
	v_mul_f32_e32 v11, v10, v9
	v_fma_f32 v12, -v8, v11, v10
	v_fmac_f32_e32 v11, v12, v9
	v_fma_f32 v8, -v8, v11, v10
	s_nop 1
	v_div_fmas_f32 v8, v8, v9, v11
	v_div_fixup_f32 v6, v8, v7, v133
	ds_write_b32 v55, v6 offset:22528
	v_mul_f32_e32 v7, 0xbfb8aa3b, v134
	v_exp_f32_e32 v7, v7
	s_nop 0
	v_add_f32_e32 v7, 1.0, v7
	v_div_scale_f32 v8, s[14:15], v7, v7, v134
	v_rcp_f32_e32 v9, v8
	v_div_scale_f32 v10, vcc, v134, v7, v134
	v_fma_f32 v11, -v8, v9, 1.0
	v_fmac_f32_e32 v9, v11, v9
	v_mul_f32_e32 v11, v10, v9
	v_fma_f32 v12, -v8, v11, v10
	v_fmac_f32_e32 v11, v12, v9
	v_fma_f32 v8, -v8, v11, v10
	s_nop 1
	v_div_fmas_f32 v8, v8, v9, v11
	v_div_fixup_f32 v6, v8, v7, v134
	ds_write_b32 v55, v6 offset:24576
	v_mul_f32_e32 v7, 0xbfb8aa3b, v135
	v_exp_f32_e32 v7, v7
	s_nop 0
	v_add_f32_e32 v7, 1.0, v7
	v_div_scale_f32 v8, s[14:15], v7, v7, v135
	v_rcp_f32_e32 v9, v8
	v_div_scale_f32 v10, vcc, v135, v7, v135
	v_fma_f32 v11, -v8, v9, 1.0
	v_fmac_f32_e32 v9, v11, v9
	v_mul_f32_e32 v11, v10, v9
	v_fma_f32 v12, -v8, v11, v10
	v_fmac_f32_e32 v11, v12, v9
	v_fma_f32 v8, -v8, v11, v10
	s_nop 1
	v_div_fmas_f32 v8, v8, v9, v11
	v_div_fixup_f32 v6, v8, v7, v135
	ds_write_b32 v55, v6 offset:26624
	v_mul_f32_e32 v7, 0xbfb8aa3b, v136
	v_exp_f32_e32 v7, v7
	s_nop 0
	v_add_f32_e32 v7, 1.0, v7
	v_div_scale_f32 v8, s[14:15], v7, v7, v136
	v_rcp_f32_e32 v9, v8
	v_div_scale_f32 v10, vcc, v136, v7, v136
	v_fma_f32 v11, -v8, v9, 1.0
	v_fmac_f32_e32 v9, v11, v9
	v_mul_f32_e32 v11, v10, v9
	v_fma_f32 v12, -v8, v11, v10
	v_fmac_f32_e32 v11, v12, v9
	v_fma_f32 v8, -v8, v11, v10
	s_nop 1
	v_div_fmas_f32 v8, v8, v9, v11
	v_div_fixup_f32 v6, v8, v7, v136
	ds_write_b32 v55, v6 offset:28672
	v_mul_f32_e32 v7, 0xbfb8aa3b, v137
	v_exp_f32_e32 v7, v7
	s_nop 0
	v_add_f32_e32 v7, 1.0, v7
	v_div_scale_f32 v8, s[14:15], v7, v7, v137
	v_rcp_f32_e32 v9, v8
	v_div_scale_f32 v10, vcc, v137, v7, v137
	v_fma_f32 v11, -v8, v9, 1.0
	v_fmac_f32_e32 v9, v11, v9
	v_mul_f32_e32 v11, v10, v9
	v_fma_f32 v12, -v8, v11, v10
	v_fmac_f32_e32 v11, v12, v9
	v_fma_f32 v8, -v8, v11, v10
	s_nop 1
	v_div_fmas_f32 v8, v8, v9, v11
	v_div_fixup_f32 v6, v8, v7, v137
	ds_write_b32 v55, v6 offset:30720
	v_mul_f32_e32 v7, 0xbfb8aa3b, v138
	v_exp_f32_e32 v7, v7
	s_nop 0
	v_add_f32_e32 v7, 1.0, v7
	v_div_scale_f32 v8, s[14:15], v7, v7, v138
	v_rcp_f32_e32 v9, v8
	v_div_scale_f32 v10, vcc, v138, v7, v138
	v_fma_f32 v11, -v8, v9, 1.0
	v_fmac_f32_e32 v9, v11, v9
	v_mul_f32_e32 v11, v10, v9
	v_fma_f32 v12, -v8, v11, v10
	v_fmac_f32_e32 v11, v12, v9
	v_fma_f32 v8, -v8, v11, v10
	s_nop 1
	v_div_fmas_f32 v8, v8, v9, v11
	v_div_fixup_f32 v6, v8, v7, v138
	ds_write_b32 v55, v6 offset:32768
	v_mul_f32_e32 v7, 0xbfb8aa3b, v139
	v_exp_f32_e32 v7, v7
	s_nop 0
	v_add_f32_e32 v7, 1.0, v7
	v_div_scale_f32 v8, s[14:15], v7, v7, v139
	v_rcp_f32_e32 v9, v8
	v_div_scale_f32 v10, vcc, v139, v7, v139
	v_fma_f32 v11, -v8, v9, 1.0
	v_fmac_f32_e32 v9, v11, v9
	v_mul_f32_e32 v11, v10, v9
	v_fma_f32 v12, -v8, v11, v10
	v_fmac_f32_e32 v11, v12, v9
	v_fma_f32 v8, -v8, v11, v10
	s_nop 1
	v_div_fmas_f32 v8, v8, v9, v11
	v_div_fixup_f32 v6, v8, v7, v139
	ds_write_b32 v55, v6 offset:34816
	s_mul_hi_i32 s6, s94, 0x2aaaaaab
	s_lshr_b32 s7, s6, 31
	s_ashr_i32 s38, s6, 3
	s_add_i32 s38, s38, s7
	s_mul_i32 s6, s38, 48
	s_sub_i32 s6, s94, s6
	s_lshl_b32 s6, s6, 7
	s_ashr_i32 s7, s6, 31
	s_mul_i32 s14, s38, 0x1800000
	s_lshl_b64 s[78:79], s[6:7], 2
	s_mul_hi_i32 s15, s38, 0x1800000
	s_add_u32 s14, s14, s78
	s_addc_u32 s15, s15, s79
	v_mov_b32_e32 v34, 0
	v_lshl_add_u64 v[72:73], v[64:65], 0, s[14:15]
	s_mov_b64 s[80:81], 0
	v_mov_b32_e32 v56, v96
	v_mov_b32_e32 v35, v34
	v_mov_b32_e32 v36, v34
	v_mov_b32_e32 v37, v34
	v_mov_b32_e32 v30, v34
	v_mov_b32_e32 v31, v34
	v_mov_b32_e32 v32, v34
	v_mov_b32_e32 v33, v34
	v_mov_b32_e32 v26, v34
	v_mov_b32_e32 v27, v34
	v_mov_b32_e32 v28, v34
	v_mov_b32_e32 v29, v34
	v_mov_b32_e32 v22, v34
	v_mov_b32_e32 v23, v34
	v_mov_b32_e32 v24, v34
	v_mov_b32_e32 v25, v34
	v_mov_b32_e32 v18, v34
	v_mov_b32_e32 v19, v34
	v_mov_b32_e32 v20, v34
	v_mov_b32_e32 v21, v34
	v_mov_b32_e32 v14, v34
	v_mov_b32_e32 v15, v34
	v_mov_b32_e32 v16, v34
	v_mov_b32_e32 v17, v34
	v_mov_b32_e32 v10, v34
	v_mov_b32_e32 v11, v34
	v_mov_b32_e32 v12, v34
	v_mov_b32_e32 v13, v34
	v_mov_b32_e32 v6, v34
	v_mov_b32_e32 v7, v34
	v_mov_b32_e32 v8, v34
	v_mov_b32_e32 v9, v34
	v_mov_b32_e32 v2, v34
	v_mov_b32_e32 v3, v34
	v_mov_b32_e32 v4, v34
	v_mov_b32_e32 v5, v34
	s_waitcnt lgkmcnt(0)
	s_barrier
	global_load_dwordx4 v[122:125], v[72:73], off
	v_add_co_u32_e32 v250, vcc, 0x6000, v72
	s_nop 1
	v_addc_co_u32_e32 v251, vcc, 0, v73, vcc
	global_load_dwordx4 v[126:129], v[250:251], off
	v_add_co_u32_e32 v252, vcc, 0xc000, v72
	s_nop 1
	v_addc_co_u32_e32 v253, vcc, 0, v73, vcc
	global_load_dwordx4 v[130:133], v[252:253], off
	v_add_co_u32_e32 v250, vcc, 0x12000, v72
	s_nop 1
	v_addc_co_u32_e32 v251, vcc, 0, v73, vcc
	global_load_dwordx4 v[134:137], v[250:251], off
	v_add_co_u32_e32 v252, vcc, 0x18000, v72
	s_nop 1
	v_addc_co_u32_e32 v253, vcc, 0, v73, vcc
	global_load_dwordx4 v[138:141], v[252:253], off
	v_add_co_u32_e32 v250, vcc, 0x1e000, v72
	s_nop 1
	v_addc_co_u32_e32 v251, vcc, 0, v73, vcc
	global_load_dwordx4 v[142:145], v[250:251], off
	v_add_co_u32_e32 v252, vcc, 0x24000, v72
	s_nop 1
	v_addc_co_u32_e32 v253, vcc, 0, v73, vcc
	global_load_dwordx4 v[146:149], v[252:253], off
	v_add_co_u32_e32 v250, vcc, 0x2a000, v72
	s_nop 1
	v_addc_co_u32_e32 v251, vcc, 0, v73, vcc
	global_load_dwordx4 v[150:153], v[250:251], off
	v_add_co_u32_e32 v252, vcc, 0x30000, v72
	s_nop 1
	v_addc_co_u32_e32 v253, vcc, 0, v73, vcc
	global_load_dwordx4 v[154:157], v[252:253], off
	v_add_co_u32_e32 v250, vcc, 0x36000, v72
	s_nop 1
	v_addc_co_u32_e32 v251, vcc, 0, v73, vcc
	global_load_dwordx4 v[158:161], v[250:251], off
	v_add_co_u32_e32 v252, vcc, 0x3c000, v72
	s_nop 1
	v_addc_co_u32_e32 v253, vcc, 0, v73, vcc
	global_load_dwordx4 v[162:165], v[252:253], off
	v_add_co_u32_e32 v250, vcc, 0x42000, v72
	s_nop 1
	v_addc_co_u32_e32 v251, vcc, 0, v73, vcc
	global_load_dwordx4 v[166:169], v[250:251], off
	v_add_co_u32_e32 v252, vcc, 0x48000, v72
	s_nop 1
	v_addc_co_u32_e32 v253, vcc, 0, v73, vcc
	global_load_dwordx4 v[170:173], v[252:253], off
	v_add_co_u32_e32 v250, vcc, 0x4e000, v72
	s_nop 1
	v_addc_co_u32_e32 v251, vcc, 0, v73, vcc
	global_load_dwordx4 v[174:177], v[250:251], off
	v_add_co_u32_e32 v252, vcc, 0x54000, v72
	s_nop 1
	v_addc_co_u32_e32 v253, vcc, 0, v73, vcc
	global_load_dwordx4 v[178:181], v[252:253], off
	v_add_co_u32_e32 v250, vcc, 0x5a000, v72
	s_nop 1
	v_addc_co_u32_e32 v251, vcc, 0, v73, vcc
	global_load_dwordx4 v[182:185], v[250:251], off
	v_add_co_u32_e32 v250, vcc, 0x60000, v72
	s_nop 1
	v_addc_co_u32_e32 v251, vcc, 0, v73, vcc
	global_load_dwordx4 v[186:189], v[250:251], off
	v_add_co_u32_e32 v252, vcc, 0x66000, v72
	s_nop 1
	v_addc_co_u32_e32 v253, vcc, 0, v73, vcc
	global_load_dwordx4 v[190:193], v[252:253], off
	v_add_co_u32_e32 v250, vcc, 0x6c000, v72
	s_nop 1
	v_addc_co_u32_e32 v251, vcc, 0, v73, vcc
	global_load_dwordx4 v[194:197], v[250:251], off
	v_add_co_u32_e32 v252, vcc, 0x72000, v72
	s_nop 1
	v_addc_co_u32_e32 v253, vcc, 0, v73, vcc
	global_load_dwordx4 v[198:201], v[252:253], off
	v_add_co_u32_e32 v250, vcc, 0x78000, v72
	s_nop 1
	v_addc_co_u32_e32 v251, vcc, 0, v73, vcc
	global_load_dwordx4 v[202:205], v[250:251], off
	v_add_co_u32_e32 v252, vcc, 0x7e000, v72
	s_nop 1
	v_addc_co_u32_e32 v253, vcc, 0, v73, vcc
	global_load_dwordx4 v[206:209], v[252:253], off
	v_add_co_u32_e32 v250, vcc, 0x84000, v72
	s_nop 1
	v_addc_co_u32_e32 v251, vcc, 0, v73, vcc
	global_load_dwordx4 v[210:213], v[250:251], off
	v_add_co_u32_e32 v252, vcc, 0x8a000, v72
	s_nop 1
	v_addc_co_u32_e32 v253, vcc, 0, v73, vcc
	global_load_dwordx4 v[214:217], v[252:253], off
	v_add_co_u32_e32 v250, vcc, 0x90000, v72
	s_nop 1
	v_addc_co_u32_e32 v251, vcc, 0, v73, vcc
	global_load_dwordx4 v[218:221], v[250:251], off
	v_add_co_u32_e32 v252, vcc, 0x96000, v72
	s_nop 1
	v_addc_co_u32_e32 v253, vcc, 0, v73, vcc
	global_load_dwordx4 v[222:225], v[252:253], off
	v_add_co_u32_e32 v250, vcc, 0x9c000, v72
	s_nop 1
	v_addc_co_u32_e32 v251, vcc, 0, v73, vcc
	global_load_dwordx4 v[226:229], v[250:251], off
	v_add_co_u32_e32 v252, vcc, 0xa2000, v72
	s_nop 1
	v_addc_co_u32_e32 v253, vcc, 0, v73, vcc
	global_load_dwordx4 v[230:233], v[252:253], off
	v_add_co_u32_e32 v250, vcc, 0xa8000, v72
	s_nop 1
	v_addc_co_u32_e32 v251, vcc, 0, v73, vcc
	global_load_dwordx4 v[234:237], v[250:251], off
	v_add_co_u32_e32 v252, vcc, 0xae000, v72
	s_nop 1
	v_addc_co_u32_e32 v253, vcc, 0, v73, vcc
	global_load_dwordx4 v[238:241], v[252:253], off
	v_add_co_u32_e32 v250, vcc, 0xb4000, v72
	s_nop 1
	v_addc_co_u32_e32 v251, vcc, 0, v73, vcc
	global_load_dwordx4 v[242:245], v[250:251], off
	v_add_co_u32_e32 v252, vcc, 0xba000, v72
	s_nop 1
	v_addc_co_u32_e32 v253, vcc, 0, v73, vcc
	global_load_dwordx4 v[246:249], v[252:253], off
	s_waitcnt vmcnt(16)
	v_pk_mov_b32 v[38:39], v[122:123], v[122:123] op_sel:[0,1]
	v_pk_mov_b32 v[40:41], v[124:125], v[124:125] op_sel:[0,1]
	v_pk_mov_b32 v[42:43], v[126:127], v[126:127] op_sel:[0,1]
	v_pk_mov_b32 v[44:45], v[128:129], v[128:129] op_sel:[0,1]
	v_pk_mov_b32 v[74:75], v[130:131], v[130:131] op_sel:[0,1]
	v_pk_mov_b32 v[76:77], v[132:133], v[132:133] op_sel:[0,1]
	v_pk_mov_b32 v[102:103], v[134:135], v[134:135] op_sel:[0,1]
	v_pk_mov_b32 v[104:105], v[136:137], v[136:137] op_sel:[0,1]
	ds_read_b128 v[106:109], v56
	ds_read_b128 v[50:53], v56 offset:16
	s_waitcnt lgkmcnt(1)
	v_pk_mul_f32 v[48:49], v[44:45], v[106:107] op_sel:[0,1]
	v_pk_mul_f32 v[110:111], v[42:43], v[106:107] op_sel:[0,1]
	v_pk_fma_f32 v[48:49], v[40:41], v[106:107], v[48:49] op_sel_hi:[1,0,1]
	v_pk_fma_f32 v[106:107], v[38:39], v[106:107], v[110:111] op_sel_hi:[1,0,1]
	v_mov_b32_e32 v110, v109
	v_pk_mul_f32 v[112:113], v[104:105], v[110:111] op_sel_hi:[1,0]
	v_pk_mul_f32 v[110:111], v[102:103], v[110:111] op_sel_hi:[1,0]
	v_pk_fma_f32 v[112:113], v[76:77], v[108:109], v[112:113] op_sel_hi:[1,0,1]
	v_pk_fma_f32 v[108:109], v[74:75], v[108:109], v[110:111] op_sel_hi:[1,0,1]
	v_pk_add_f32 v[48:49], v[48:49], v[112:113]
	v_pk_add_f32 v[106:107], v[106:107], v[108:109]
	v_pk_add_f32 v[4:5], v[4:5], v[48:49]
	v_pk_add_f32 v[2:3], v[2:3], v[106:107]
	ds_read_b128 v[106:109], v56 offset:4096
	s_waitcnt lgkmcnt(0)
	v_pk_mul_f32 v[48:49], v[44:45], v[106:107] op_sel:[0,1]
	v_pk_mul_f32 v[110:111], v[42:43], v[106:107] op_sel:[0,1]
	v_pk_fma_f32 v[48:49], v[40:41], v[106:107], v[48:49] op_sel_hi:[1,0,1]
	v_pk_fma_f32 v[106:107], v[38:39], v[106:107], v[110:111] op_sel_hi:[1,0,1]
	v_mov_b32_e32 v110, v109
	v_pk_mul_f32 v[112:113], v[104:105], v[110:111] op_sel_hi:[1,0]
	v_pk_mul_f32 v[110:111], v[102:103], v[110:111] op_sel_hi:[1,0]
	v_pk_fma_f32 v[112:113], v[76:77], v[108:109], v[112:113] op_sel_hi:[1,0,1]
	v_pk_fma_f32 v[108:109], v[74:75], v[108:109], v[110:111] op_sel_hi:[1,0,1]
	v_pk_add_f32 v[48:49], v[48:49], v[112:113]
	v_pk_add_f32 v[106:107], v[106:107], v[108:109]
	v_pk_add_f32 v[8:9], v[8:9], v[48:49]
	v_pk_add_f32 v[6:7], v[6:7], v[106:107]
	ds_read_b128 v[106:109], v56 offset:8192
	s_waitcnt lgkmcnt(0)
	v_pk_mul_f32 v[48:49], v[44:45], v[106:107] op_sel:[0,1]
	v_pk_mul_f32 v[110:111], v[42:43], v[106:107] op_sel:[0,1]
	v_pk_fma_f32 v[48:49], v[40:41], v[106:107], v[48:49] op_sel_hi:[1,0,1]
	v_pk_fma_f32 v[106:107], v[38:39], v[106:107], v[110:111] op_sel_hi:[1,0,1]
	v_mov_b32_e32 v110, v109
	v_pk_mul_f32 v[112:113], v[104:105], v[110:111] op_sel_hi:[1,0]
	v_pk_mul_f32 v[110:111], v[102:103], v[110:111] op_sel_hi:[1,0]
	v_pk_fma_f32 v[112:113], v[76:77], v[108:109], v[112:113] op_sel_hi:[1,0,1]
	v_pk_fma_f32 v[108:109], v[74:75], v[108:109], v[110:111] op_sel_hi:[1,0,1]
	v_pk_add_f32 v[48:49], v[48:49], v[112:113]
	v_pk_add_f32 v[106:107], v[106:107], v[108:109]
	v_pk_add_f32 v[12:13], v[12:13], v[48:49]
	v_pk_add_f32 v[10:11], v[10:11], v[106:107]
	ds_read_b128 v[106:109], v56 offset:12288
	s_waitcnt lgkmcnt(0)
	v_pk_mul_f32 v[48:49], v[44:45], v[106:107] op_sel:[0,1]
	v_pk_mul_f32 v[110:111], v[42:43], v[106:107] op_sel:[0,1]
	v_pk_fma_f32 v[48:49], v[40:41], v[106:107], v[48:49] op_sel_hi:[1,0,1]
	v_pk_fma_f32 v[106:107], v[38:39], v[106:107], v[110:111] op_sel_hi:[1,0,1]
	v_mov_b32_e32 v110, v109
	v_pk_mul_f32 v[112:113], v[104:105], v[110:111] op_sel_hi:[1,0]
	v_pk_mul_f32 v[110:111], v[102:103], v[110:111] op_sel_hi:[1,0]
	v_pk_fma_f32 v[112:113], v[76:77], v[108:109], v[112:113] op_sel_hi:[1,0,1]
	v_pk_fma_f32 v[108:109], v[74:75], v[108:109], v[110:111] op_sel_hi:[1,0,1]
	v_pk_add_f32 v[48:49], v[48:49], v[112:113]
	v_pk_add_f32 v[106:107], v[106:107], v[108:109]
	v_pk_add_f32 v[16:17], v[16:17], v[48:49]
	v_pk_add_f32 v[14:15], v[14:15], v[106:107]
	ds_read_b128 v[106:109], v56 offset:16384
	s_waitcnt lgkmcnt(0)
	v_pk_mul_f32 v[48:49], v[44:45], v[106:107] op_sel:[0,1]
	v_pk_mul_f32 v[110:111], v[42:43], v[106:107] op_sel:[0,1]
	v_pk_fma_f32 v[48:49], v[40:41], v[106:107], v[48:49] op_sel_hi:[1,0,1]
	v_pk_fma_f32 v[106:107], v[38:39], v[106:107], v[110:111] op_sel_hi:[1,0,1]
	v_mov_b32_e32 v110, v109
	v_pk_mul_f32 v[112:113], v[104:105], v[110:111] op_sel_hi:[1,0]
	v_pk_mul_f32 v[110:111], v[102:103], v[110:111] op_sel_hi:[1,0]
	v_pk_fma_f32 v[112:113], v[76:77], v[108:109], v[112:113] op_sel_hi:[1,0,1]
	v_pk_fma_f32 v[108:109], v[74:75], v[108:109], v[110:111] op_sel_hi:[1,0,1]
	v_pk_add_f32 v[48:49], v[48:49], v[112:113]
	v_pk_add_f32 v[106:107], v[106:107], v[108:109]
	v_pk_add_f32 v[20:21], v[20:21], v[48:49]
	v_pk_add_f32 v[18:19], v[18:19], v[106:107]
	ds_read_b128 v[106:109], v56 offset:20480
	s_waitcnt lgkmcnt(0)
	v_pk_mul_f32 v[48:49], v[44:45], v[106:107] op_sel:[0,1]
	v_pk_mul_f32 v[110:111], v[42:43], v[106:107] op_sel:[0,1]
	v_pk_fma_f32 v[48:49], v[40:41], v[106:107], v[48:49] op_sel_hi:[1,0,1]
	v_pk_fma_f32 v[106:107], v[38:39], v[106:107], v[110:111] op_sel_hi:[1,0,1]
	v_mov_b32_e32 v110, v109
	v_pk_mul_f32 v[112:113], v[104:105], v[110:111] op_sel_hi:[1,0]
	v_pk_mul_f32 v[110:111], v[102:103], v[110:111] op_sel_hi:[1,0]
	v_pk_fma_f32 v[112:113], v[76:77], v[108:109], v[112:113] op_sel_hi:[1,0,1]
	v_pk_fma_f32 v[108:109], v[74:75], v[108:109], v[110:111] op_sel_hi:[1,0,1]
	v_pk_add_f32 v[48:49], v[48:49], v[112:113]
	v_pk_add_f32 v[106:107], v[106:107], v[108:109]
	v_pk_add_f32 v[24:25], v[24:25], v[48:49]
	v_pk_add_f32 v[22:23], v[22:23], v[106:107]
	ds_read_b128 v[106:109], v56 offset:24576
	s_waitcnt lgkmcnt(0)
	v_pk_mul_f32 v[48:49], v[44:45], v[106:107] op_sel:[0,1]
	v_pk_mul_f32 v[110:111], v[42:43], v[106:107] op_sel:[0,1]
	v_pk_fma_f32 v[48:49], v[40:41], v[106:107], v[48:49] op_sel_hi:[1,0,1]
	v_pk_fma_f32 v[106:107], v[38:39], v[106:107], v[110:111] op_sel_hi:[1,0,1]
	v_mov_b32_e32 v110, v109
	v_pk_mul_f32 v[112:113], v[104:105], v[110:111] op_sel_hi:[1,0]
	v_pk_mul_f32 v[110:111], v[102:103], v[110:111] op_sel_hi:[1,0]
	v_pk_fma_f32 v[112:113], v[76:77], v[108:109], v[112:113] op_sel_hi:[1,0,1]
	v_pk_fma_f32 v[108:109], v[74:75], v[108:109], v[110:111] op_sel_hi:[1,0,1]
	v_pk_add_f32 v[48:49], v[48:49], v[112:113]
	v_pk_add_f32 v[106:107], v[106:107], v[108:109]
	v_pk_add_f32 v[28:29], v[28:29], v[48:49]
	v_pk_add_f32 v[26:27], v[26:27], v[106:107]
	ds_read_b128 v[106:109], v56 offset:28672
	s_waitcnt lgkmcnt(0)
	v_pk_mul_f32 v[48:49], v[44:45], v[106:107] op_sel:[0,1]
	v_pk_mul_f32 v[110:111], v[42:43], v[106:107] op_sel:[0,1]
	v_pk_fma_f32 v[48:49], v[40:41], v[106:107], v[48:49] op_sel_hi:[1,0,1]
	v_pk_fma_f32 v[106:107], v[38:39], v[106:107], v[110:111] op_sel_hi:[1,0,1]
	v_mov_b32_e32 v110, v109
	v_pk_mul_f32 v[112:113], v[104:105], v[110:111] op_sel_hi:[1,0]
	v_pk_mul_f32 v[110:111], v[102:103], v[110:111] op_sel_hi:[1,0]
	v_pk_fma_f32 v[112:113], v[76:77], v[108:109], v[112:113] op_sel_hi:[1,0,1]
	v_pk_fma_f32 v[108:109], v[74:75], v[108:109], v[110:111] op_sel_hi:[1,0,1]
	v_pk_add_f32 v[48:49], v[48:49], v[112:113]
	v_pk_add_f32 v[106:107], v[106:107], v[108:109]
	v_pk_add_f32 v[32:33], v[32:33], v[48:49]
	v_pk_add_f32 v[30:31], v[30:31], v[106:107]
	ds_read_b128 v[106:109], v56 offset:32768
	s_waitcnt lgkmcnt(0)
	v_pk_mul_f32 v[42:43], v[42:43], v[106:107] op_sel:[0,1]
	v_pk_mul_f32 v[44:45], v[44:45], v[106:107] op_sel:[0,1]
	v_pk_fma_f32 v[38:39], v[38:39], v[106:107], v[42:43] op_sel_hi:[1,0,1]
	v_mov_b32_e32 v42, v109
	v_pk_fma_f32 v[40:41], v[40:41], v[106:107], v[44:45] op_sel_hi:[1,0,1]
	v_pk_mul_f32 v[44:45], v[104:105], v[42:43] op_sel_hi:[1,0]
	v_pk_mul_f32 v[42:43], v[102:103], v[42:43] op_sel_hi:[1,0]
	v_pk_fma_f32 v[44:45], v[76:77], v[108:109], v[44:45] op_sel_hi:[1,0,1]
	v_pk_fma_f32 v[42:43], v[74:75], v[108:109], v[42:43] op_sel_hi:[1,0,1]
	v_pk_add_f32 v[40:41], v[40:41], v[44:45]
	v_pk_add_f32 v[38:39], v[38:39], v[42:43]
	v_pk_add_f32 v[74:75], v[36:37], v[40:41]
	v_pk_add_f32 v[76:77], v[34:35], v[38:39]
	v_pk_mov_b32 v[34:35], v[138:139], v[138:139] op_sel:[0,1]
	v_pk_mov_b32 v[36:37], v[140:141], v[140:141] op_sel:[0,1]
	v_pk_mov_b32 v[38:39], v[142:143], v[142:143] op_sel:[0,1]
	v_pk_mov_b32 v[40:41], v[144:145], v[144:145] op_sel:[0,1]
	v_pk_mov_b32 v[42:43], v[146:147], v[146:147] op_sel:[0,1]
	v_pk_mov_b32 v[44:45], v[148:149], v[148:149] op_sel:[0,1]
	v_pk_mov_b32 v[46:47], v[150:151], v[150:151] op_sel:[0,1]
	v_pk_mov_b32 v[48:49], v[152:153], v[152:153] op_sel:[0,1]
	v_pk_mul_f32 v[102:103], v[40:41], v[50:51] op_sel:[0,1]
	v_pk_mul_f32 v[104:105], v[38:39], v[50:51] op_sel:[0,1]
	v_pk_fma_f32 v[102:103], v[36:37], v[50:51], v[102:103] op_sel_hi:[1,0,1]
	v_pk_fma_f32 v[50:51], v[34:35], v[50:51], v[104:105] op_sel_hi:[1,0,1]
	v_mov_b32_e32 v104, v53
	v_pk_mul_f32 v[106:107], v[48:49], v[104:105] op_sel_hi:[1,0]
	v_pk_mul_f32 v[104:105], v[46:47], v[104:105] op_sel_hi:[1,0]
	v_pk_fma_f32 v[106:107], v[44:45], v[52:53], v[106:107] op_sel_hi:[1,0,1]
	v_pk_fma_f32 v[52:53], v[42:43], v[52:53], v[104:105] op_sel_hi:[1,0,1]
	v_pk_add_f32 v[102:103], v[102:103], v[106:107]
	v_pk_add_f32 v[50:51], v[50:51], v[52:53]
	v_pk_add_f32 v[4:5], v[4:5], v[102:103]
	v_pk_add_f32 v[2:3], v[2:3], v[50:51]
	ds_read_b128 v[50:53], v56 offset:4112
	s_waitcnt lgkmcnt(0)
	v_pk_mul_f32 v[102:103], v[40:41], v[50:51] op_sel:[0,1]
	v_pk_mul_f32 v[104:105], v[38:39], v[50:51] op_sel:[0,1]
	v_pk_fma_f32 v[102:103], v[36:37], v[50:51], v[102:103] op_sel_hi:[1,0,1]
	v_pk_fma_f32 v[50:51], v[34:35], v[50:51], v[104:105] op_sel_hi:[1,0,1]
	v_mov_b32_e32 v104, v53
	v_pk_mul_f32 v[106:107], v[48:49], v[104:105] op_sel_hi:[1,0]
	v_pk_mul_f32 v[104:105], v[46:47], v[104:105] op_sel_hi:[1,0]
	v_pk_fma_f32 v[106:107], v[44:45], v[52:53], v[106:107] op_sel_hi:[1,0,1]
	v_pk_fma_f32 v[52:53], v[42:43], v[52:53], v[104:105] op_sel_hi:[1,0,1]
	v_pk_add_f32 v[102:103], v[102:103], v[106:107]
	v_pk_add_f32 v[50:51], v[50:51], v[52:53]
	v_pk_add_f32 v[8:9], v[8:9], v[102:103]
	v_pk_add_f32 v[6:7], v[6:7], v[50:51]
	ds_read_b128 v[50:53], v56 offset:8208
	s_waitcnt lgkmcnt(0)
	v_pk_mul_f32 v[102:103], v[40:41], v[50:51] op_sel:[0,1]
	v_pk_mul_f32 v[104:105], v[38:39], v[50:51] op_sel:[0,1]
	v_pk_fma_f32 v[102:103], v[36:37], v[50:51], v[102:103] op_sel_hi:[1,0,1]
	v_pk_fma_f32 v[50:51], v[34:35], v[50:51], v[104:105] op_sel_hi:[1,0,1]
	v_mov_b32_e32 v104, v53
	v_pk_mul_f32 v[106:107], v[48:49], v[104:105] op_sel_hi:[1,0]
	v_pk_mul_f32 v[104:105], v[46:47], v[104:105] op_sel_hi:[1,0]
	v_pk_fma_f32 v[106:107], v[44:45], v[52:53], v[106:107] op_sel_hi:[1,0,1]
	v_pk_fma_f32 v[52:53], v[42:43], v[52:53], v[104:105] op_sel_hi:[1,0,1]
	v_pk_add_f32 v[102:103], v[102:103], v[106:107]
	v_pk_add_f32 v[50:51], v[50:51], v[52:53]
	v_pk_add_f32 v[12:13], v[12:13], v[102:103]
	v_pk_add_f32 v[10:11], v[10:11], v[50:51]
	ds_read_b128 v[50:53], v56 offset:12304
	s_waitcnt lgkmcnt(0)
	v_pk_mul_f32 v[102:103], v[40:41], v[50:51] op_sel:[0,1]
	v_pk_mul_f32 v[104:105], v[38:39], v[50:51] op_sel:[0,1]
	v_pk_fma_f32 v[102:103], v[36:37], v[50:51], v[102:103] op_sel_hi:[1,0,1]
	v_pk_fma_f32 v[50:51], v[34:35], v[50:51], v[104:105] op_sel_hi:[1,0,1]
	v_mov_b32_e32 v104, v53
	v_pk_mul_f32 v[106:107], v[48:49], v[104:105] op_sel_hi:[1,0]
	v_pk_mul_f32 v[104:105], v[46:47], v[104:105] op_sel_hi:[1,0]
	v_pk_fma_f32 v[106:107], v[44:45], v[52:53], v[106:107] op_sel_hi:[1,0,1]
	v_pk_fma_f32 v[52:53], v[42:43], v[52:53], v[104:105] op_sel_hi:[1,0,1]
	v_pk_add_f32 v[102:103], v[102:103], v[106:107]
	v_pk_add_f32 v[50:51], v[50:51], v[52:53]
	v_pk_add_f32 v[16:17], v[16:17], v[102:103]
	v_pk_add_f32 v[14:15], v[14:15], v[50:51]
	ds_read_b128 v[50:53], v56 offset:16400
	s_waitcnt lgkmcnt(0)
	v_pk_mul_f32 v[102:103], v[40:41], v[50:51] op_sel:[0,1]
	v_pk_mul_f32 v[104:105], v[38:39], v[50:51] op_sel:[0,1]
	v_pk_fma_f32 v[102:103], v[36:37], v[50:51], v[102:103] op_sel_hi:[1,0,1]
	v_pk_fma_f32 v[50:51], v[34:35], v[50:51], v[104:105] op_sel_hi:[1,0,1]
	v_mov_b32_e32 v104, v53
	v_pk_mul_f32 v[106:107], v[48:49], v[104:105] op_sel_hi:[1,0]
	v_pk_mul_f32 v[104:105], v[46:47], v[104:105] op_sel_hi:[1,0]
	v_pk_fma_f32 v[106:107], v[44:45], v[52:53], v[106:107] op_sel_hi:[1,0,1]
	v_pk_fma_f32 v[52:53], v[42:43], v[52:53], v[104:105] op_sel_hi:[1,0,1]
	v_pk_add_f32 v[102:103], v[102:103], v[106:107]
	v_pk_add_f32 v[50:51], v[50:51], v[52:53]
	v_pk_add_f32 v[20:21], v[20:21], v[102:103]
	v_pk_add_f32 v[18:19], v[18:19], v[50:51]
	ds_read_b128 v[50:53], v56 offset:20496
	s_waitcnt lgkmcnt(0)
	v_pk_mul_f32 v[102:103], v[40:41], v[50:51] op_sel:[0,1]
	v_pk_mul_f32 v[104:105], v[38:39], v[50:51] op_sel:[0,1]
	v_pk_fma_f32 v[102:103], v[36:37], v[50:51], v[102:103] op_sel_hi:[1,0,1]
	v_pk_fma_f32 v[50:51], v[34:35], v[50:51], v[104:105] op_sel_hi:[1,0,1]
	v_mov_b32_e32 v104, v53
	v_pk_mul_f32 v[106:107], v[48:49], v[104:105] op_sel_hi:[1,0]
	v_pk_mul_f32 v[104:105], v[46:47], v[104:105] op_sel_hi:[1,0]
	v_pk_fma_f32 v[106:107], v[44:45], v[52:53], v[106:107] op_sel_hi:[1,0,1]
	v_pk_fma_f32 v[52:53], v[42:43], v[52:53], v[104:105] op_sel_hi:[1,0,1]
	v_pk_add_f32 v[102:103], v[102:103], v[106:107]
	v_pk_add_f32 v[50:51], v[50:51], v[52:53]
	v_pk_add_f32 v[24:25], v[24:25], v[102:103]
	v_pk_add_f32 v[22:23], v[22:23], v[50:51]
	ds_read_b128 v[50:53], v56 offset:24592
	s_waitcnt lgkmcnt(0)
	v_pk_mul_f32 v[102:103], v[40:41], v[50:51] op_sel:[0,1]
	v_pk_mul_f32 v[104:105], v[38:39], v[50:51] op_sel:[0,1]
	v_pk_fma_f32 v[102:103], v[36:37], v[50:51], v[102:103] op_sel_hi:[1,0,1]
	v_pk_fma_f32 v[50:51], v[34:35], v[50:51], v[104:105] op_sel_hi:[1,0,1]
	v_mov_b32_e32 v104, v53
	v_pk_mul_f32 v[106:107], v[48:49], v[104:105] op_sel_hi:[1,0]
	v_pk_mul_f32 v[104:105], v[46:47], v[104:105] op_sel_hi:[1,0]
	v_pk_fma_f32 v[106:107], v[44:45], v[52:53], v[106:107] op_sel_hi:[1,0,1]
	v_pk_fma_f32 v[52:53], v[42:43], v[52:53], v[104:105] op_sel_hi:[1,0,1]
	v_pk_add_f32 v[102:103], v[102:103], v[106:107]
	v_pk_add_f32 v[50:51], v[50:51], v[52:53]
	v_pk_add_f32 v[28:29], v[28:29], v[102:103]
	v_pk_add_f32 v[26:27], v[26:27], v[50:51]
	ds_read_b128 v[50:53], v56 offset:28688
	s_waitcnt lgkmcnt(0)
	v_pk_mul_f32 v[102:103], v[40:41], v[50:51] op_sel:[0,1]
	v_pk_mul_f32 v[104:105], v[38:39], v[50:51] op_sel:[0,1]
	v_pk_fma_f32 v[102:103], v[36:37], v[50:51], v[102:103] op_sel_hi:[1,0,1]
	v_pk_fma_f32 v[50:51], v[34:35], v[50:51], v[104:105] op_sel_hi:[1,0,1]
	v_mov_b32_e32 v104, v53
	v_pk_mul_f32 v[106:107], v[48:49], v[104:105] op_sel_hi:[1,0]
	v_pk_mul_f32 v[104:105], v[46:47], v[104:105] op_sel_hi:[1,0]
	v_pk_fma_f32 v[106:107], v[44:45], v[52:53], v[106:107] op_sel_hi:[1,0,1]
	v_pk_fma_f32 v[52:53], v[42:43], v[52:53], v[104:105] op_sel_hi:[1,0,1]
	v_pk_add_f32 v[102:103], v[102:103], v[106:107]
	v_pk_add_f32 v[50:51], v[50:51], v[52:53]
	v_pk_add_f32 v[32:33], v[32:33], v[102:103]
	v_pk_add_f32 v[30:31], v[30:31], v[50:51]
	ds_read_b128 v[50:53], v56 offset:32784
	v_add_u32_e32 v56, 32, v56
	s_waitcnt lgkmcnt(0)
	v_pk_mul_f32 v[38:39], v[38:39], v[50:51] op_sel:[0,1]
	v_pk_mul_f32 v[40:41], v[40:41], v[50:51] op_sel:[0,1]
	v_pk_fma_f32 v[34:35], v[34:35], v[50:51], v[38:39] op_sel_hi:[1,0,1]
	v_mov_b32_e32 v38, v53
	v_pk_fma_f32 v[36:37], v[36:37], v[50:51], v[40:41] op_sel_hi:[1,0,1]
	v_pk_mul_f32 v[40:41], v[48:49], v[38:39] op_sel_hi:[1,0]
	v_pk_mul_f32 v[38:39], v[46:47], v[38:39] op_sel_hi:[1,0]
	v_pk_fma_f32 v[40:41], v[44:45], v[52:53], v[40:41] op_sel_hi:[1,0,1]
	v_pk_fma_f32 v[38:39], v[42:43], v[52:53], v[38:39] op_sel_hi:[1,0,1]
	v_pk_add_f32 v[36:37], v[36:37], v[40:41]
	v_pk_add_f32 v[34:35], v[34:35], v[38:39]
	v_pk_add_f32 v[36:37], v[74:75], v[36:37]
	v_pk_add_f32 v[34:35], v[76:77], v[34:35]
	v_pk_mov_b32 v[38:39], v[154:155], v[154:155] op_sel:[0,1]
	v_pk_mov_b32 v[40:41], v[156:157], v[156:157] op_sel:[0,1]
	v_pk_mov_b32 v[42:43], v[158:159], v[158:159] op_sel:[0,1]
	v_pk_mov_b32 v[44:45], v[160:161], v[160:161] op_sel:[0,1]
	v_pk_mov_b32 v[74:75], v[162:163], v[162:163] op_sel:[0,1]
	v_pk_mov_b32 v[76:77], v[164:165], v[164:165] op_sel:[0,1]
	v_pk_mov_b32 v[102:103], v[166:167], v[166:167] op_sel:[0,1]
	v_pk_mov_b32 v[104:105], v[168:169], v[168:169] op_sel:[0,1]
	ds_read_b128 v[106:109], v56
	ds_read_b128 v[50:53], v56 offset:16
	s_waitcnt lgkmcnt(1)
	v_pk_mul_f32 v[48:49], v[44:45], v[106:107] op_sel:[0,1]
	v_pk_mul_f32 v[110:111], v[42:43], v[106:107] op_sel:[0,1]
	v_pk_fma_f32 v[48:49], v[40:41], v[106:107], v[48:49] op_sel_hi:[1,0,1]
	v_pk_fma_f32 v[106:107], v[38:39], v[106:107], v[110:111] op_sel_hi:[1,0,1]
	v_mov_b32_e32 v110, v109
	v_pk_mul_f32 v[112:113], v[104:105], v[110:111] op_sel_hi:[1,0]
	v_pk_mul_f32 v[110:111], v[102:103], v[110:111] op_sel_hi:[1,0]
	v_pk_fma_f32 v[112:113], v[76:77], v[108:109], v[112:113] op_sel_hi:[1,0,1]
	v_pk_fma_f32 v[108:109], v[74:75], v[108:109], v[110:111] op_sel_hi:[1,0,1]
	v_pk_add_f32 v[48:49], v[48:49], v[112:113]
	v_pk_add_f32 v[106:107], v[106:107], v[108:109]
	v_pk_add_f32 v[4:5], v[4:5], v[48:49]
	v_pk_add_f32 v[2:3], v[2:3], v[106:107]
	ds_read_b128 v[106:109], v56 offset:4096
	s_waitcnt lgkmcnt(0)
	v_pk_mul_f32 v[48:49], v[44:45], v[106:107] op_sel:[0,1]
	v_pk_mul_f32 v[110:111], v[42:43], v[106:107] op_sel:[0,1]
	v_pk_fma_f32 v[48:49], v[40:41], v[106:107], v[48:49] op_sel_hi:[1,0,1]
	v_pk_fma_f32 v[106:107], v[38:39], v[106:107], v[110:111] op_sel_hi:[1,0,1]
	v_mov_b32_e32 v110, v109
	v_pk_mul_f32 v[112:113], v[104:105], v[110:111] op_sel_hi:[1,0]
	v_pk_mul_f32 v[110:111], v[102:103], v[110:111] op_sel_hi:[1,0]
	v_pk_fma_f32 v[112:113], v[76:77], v[108:109], v[112:113] op_sel_hi:[1,0,1]
	v_pk_fma_f32 v[108:109], v[74:75], v[108:109], v[110:111] op_sel_hi:[1,0,1]
	v_pk_add_f32 v[48:49], v[48:49], v[112:113]
	v_pk_add_f32 v[106:107], v[106:107], v[108:109]
	v_pk_add_f32 v[8:9], v[8:9], v[48:49]
	v_pk_add_f32 v[6:7], v[6:7], v[106:107]
	ds_read_b128 v[106:109], v56 offset:8192
	s_waitcnt lgkmcnt(0)
	v_pk_mul_f32 v[48:49], v[44:45], v[106:107] op_sel:[0,1]
	v_pk_mul_f32 v[110:111], v[42:43], v[106:107] op_sel:[0,1]
	v_pk_fma_f32 v[48:49], v[40:41], v[106:107], v[48:49] op_sel_hi:[1,0,1]
	v_pk_fma_f32 v[106:107], v[38:39], v[106:107], v[110:111] op_sel_hi:[1,0,1]
	v_mov_b32_e32 v110, v109
	v_pk_mul_f32 v[112:113], v[104:105], v[110:111] op_sel_hi:[1,0]
	v_pk_mul_f32 v[110:111], v[102:103], v[110:111] op_sel_hi:[1,0]
	v_pk_fma_f32 v[112:113], v[76:77], v[108:109], v[112:113] op_sel_hi:[1,0,1]
	v_pk_fma_f32 v[108:109], v[74:75], v[108:109], v[110:111] op_sel_hi:[1,0,1]
	v_pk_add_f32 v[48:49], v[48:49], v[112:113]
	v_pk_add_f32 v[106:107], v[106:107], v[108:109]
	v_pk_add_f32 v[12:13], v[12:13], v[48:49]
	v_pk_add_f32 v[10:11], v[10:11], v[106:107]
	ds_read_b128 v[106:109], v56 offset:12288
	s_waitcnt lgkmcnt(0)
	v_pk_mul_f32 v[48:49], v[44:45], v[106:107] op_sel:[0,1]
	v_pk_mul_f32 v[110:111], v[42:43], v[106:107] op_sel:[0,1]
	v_pk_fma_f32 v[48:49], v[40:41], v[106:107], v[48:49] op_sel_hi:[1,0,1]
	v_pk_fma_f32 v[106:107], v[38:39], v[106:107], v[110:111] op_sel_hi:[1,0,1]
	v_mov_b32_e32 v110, v109
	v_pk_mul_f32 v[112:113], v[104:105], v[110:111] op_sel_hi:[1,0]
	v_pk_mul_f32 v[110:111], v[102:103], v[110:111] op_sel_hi:[1,0]
	v_pk_fma_f32 v[112:113], v[76:77], v[108:109], v[112:113] op_sel_hi:[1,0,1]
	v_pk_fma_f32 v[108:109], v[74:75], v[108:109], v[110:111] op_sel_hi:[1,0,1]
	v_pk_add_f32 v[48:49], v[48:49], v[112:113]
	v_pk_add_f32 v[106:107], v[106:107], v[108:109]
	v_pk_add_f32 v[16:17], v[16:17], v[48:49]
	v_pk_add_f32 v[14:15], v[14:15], v[106:107]
	ds_read_b128 v[106:109], v56 offset:16384
	s_waitcnt lgkmcnt(0)
	v_pk_mul_f32 v[48:49], v[44:45], v[106:107] op_sel:[0,1]
	v_pk_mul_f32 v[110:111], v[42:43], v[106:107] op_sel:[0,1]
	v_pk_fma_f32 v[48:49], v[40:41], v[106:107], v[48:49] op_sel_hi:[1,0,1]
	v_pk_fma_f32 v[106:107], v[38:39], v[106:107], v[110:111] op_sel_hi:[1,0,1]
	v_mov_b32_e32 v110, v109
	v_pk_mul_f32 v[112:113], v[104:105], v[110:111] op_sel_hi:[1,0]
	v_pk_mul_f32 v[110:111], v[102:103], v[110:111] op_sel_hi:[1,0]
	v_pk_fma_f32 v[112:113], v[76:77], v[108:109], v[112:113] op_sel_hi:[1,0,1]
	v_pk_fma_f32 v[108:109], v[74:75], v[108:109], v[110:111] op_sel_hi:[1,0,1]
	v_pk_add_f32 v[48:49], v[48:49], v[112:113]
	v_pk_add_f32 v[106:107], v[106:107], v[108:109]
	v_pk_add_f32 v[20:21], v[20:21], v[48:49]
	v_pk_add_f32 v[18:19], v[18:19], v[106:107]
	ds_read_b128 v[106:109], v56 offset:20480
	s_waitcnt lgkmcnt(0)
	v_pk_mul_f32 v[48:49], v[44:45], v[106:107] op_sel:[0,1]
	v_pk_mul_f32 v[110:111], v[42:43], v[106:107] op_sel:[0,1]
	v_pk_fma_f32 v[48:49], v[40:41], v[106:107], v[48:49] op_sel_hi:[1,0,1]
	v_pk_fma_f32 v[106:107], v[38:39], v[106:107], v[110:111] op_sel_hi:[1,0,1]
	v_mov_b32_e32 v110, v109
	v_pk_mul_f32 v[112:113], v[104:105], v[110:111] op_sel_hi:[1,0]
	v_pk_mul_f32 v[110:111], v[102:103], v[110:111] op_sel_hi:[1,0]
	v_pk_fma_f32 v[112:113], v[76:77], v[108:109], v[112:113] op_sel_hi:[1,0,1]
	v_pk_fma_f32 v[108:109], v[74:75], v[108:109], v[110:111] op_sel_hi:[1,0,1]
	v_pk_add_f32 v[48:49], v[48:49], v[112:113]
	v_pk_add_f32 v[106:107], v[106:107], v[108:109]
	v_pk_add_f32 v[24:25], v[24:25], v[48:49]
	v_pk_add_f32 v[22:23], v[22:23], v[106:107]
	ds_read_b128 v[106:109], v56 offset:24576
	s_waitcnt lgkmcnt(0)
	v_pk_mul_f32 v[48:49], v[44:45], v[106:107] op_sel:[0,1]
	v_pk_mul_f32 v[110:111], v[42:43], v[106:107] op_sel:[0,1]
	v_pk_fma_f32 v[48:49], v[40:41], v[106:107], v[48:49] op_sel_hi:[1,0,1]
	v_pk_fma_f32 v[106:107], v[38:39], v[106:107], v[110:111] op_sel_hi:[1,0,1]
	v_mov_b32_e32 v110, v109
	v_pk_mul_f32 v[112:113], v[104:105], v[110:111] op_sel_hi:[1,0]
	v_pk_mul_f32 v[110:111], v[102:103], v[110:111] op_sel_hi:[1,0]
	v_pk_fma_f32 v[112:113], v[76:77], v[108:109], v[112:113] op_sel_hi:[1,0,1]
	v_pk_fma_f32 v[108:109], v[74:75], v[108:109], v[110:111] op_sel_hi:[1,0,1]
	v_pk_add_f32 v[48:49], v[48:49], v[112:113]
	v_pk_add_f32 v[106:107], v[106:107], v[108:109]
	v_pk_add_f32 v[28:29], v[28:29], v[48:49]
	v_pk_add_f32 v[26:27], v[26:27], v[106:107]
	ds_read_b128 v[106:109], v56 offset:28672
	s_waitcnt lgkmcnt(0)
	v_pk_mul_f32 v[48:49], v[44:45], v[106:107] op_sel:[0,1]
	v_pk_mul_f32 v[110:111], v[42:43], v[106:107] op_sel:[0,1]
	v_pk_fma_f32 v[48:49], v[40:41], v[106:107], v[48:49] op_sel_hi:[1,0,1]
	v_pk_fma_f32 v[106:107], v[38:39], v[106:107], v[110:111] op_sel_hi:[1,0,1]
	v_mov_b32_e32 v110, v109
	v_pk_mul_f32 v[112:113], v[104:105], v[110:111] op_sel_hi:[1,0]
	v_pk_mul_f32 v[110:111], v[102:103], v[110:111] op_sel_hi:[1,0]
	v_pk_fma_f32 v[112:113], v[76:77], v[108:109], v[112:113] op_sel_hi:[1,0,1]
	v_pk_fma_f32 v[108:109], v[74:75], v[108:109], v[110:111] op_sel_hi:[1,0,1]
	v_pk_add_f32 v[48:49], v[48:49], v[112:113]
	v_pk_add_f32 v[106:107], v[106:107], v[108:109]
	v_pk_add_f32 v[32:33], v[32:33], v[48:49]
	v_pk_add_f32 v[30:31], v[30:31], v[106:107]
	ds_read_b128 v[106:109], v56 offset:32768
	s_waitcnt lgkmcnt(0)
	v_pk_mul_f32 v[42:43], v[42:43], v[106:107] op_sel:[0,1]
	v_pk_mul_f32 v[44:45], v[44:45], v[106:107] op_sel:[0,1]
	v_pk_fma_f32 v[38:39], v[38:39], v[106:107], v[42:43] op_sel_hi:[1,0,1]
	v_mov_b32_e32 v42, v109
	v_pk_fma_f32 v[40:41], v[40:41], v[106:107], v[44:45] op_sel_hi:[1,0,1]
	v_pk_mul_f32 v[44:45], v[104:105], v[42:43] op_sel_hi:[1,0]
	v_pk_mul_f32 v[42:43], v[102:103], v[42:43] op_sel_hi:[1,0]
	v_pk_fma_f32 v[44:45], v[76:77], v[108:109], v[44:45] op_sel_hi:[1,0,1]
	v_pk_fma_f32 v[42:43], v[74:75], v[108:109], v[42:43] op_sel_hi:[1,0,1]
	v_pk_add_f32 v[40:41], v[40:41], v[44:45]
	v_pk_add_f32 v[38:39], v[38:39], v[42:43]
	v_pk_add_f32 v[74:75], v[36:37], v[40:41]
	v_pk_add_f32 v[76:77], v[34:35], v[38:39]
	v_pk_mov_b32 v[34:35], v[170:171], v[170:171] op_sel:[0,1]
	v_pk_mov_b32 v[36:37], v[172:173], v[172:173] op_sel:[0,1]
	v_pk_mov_b32 v[38:39], v[174:175], v[174:175] op_sel:[0,1]
	v_pk_mov_b32 v[40:41], v[176:177], v[176:177] op_sel:[0,1]
	v_pk_mov_b32 v[42:43], v[178:179], v[178:179] op_sel:[0,1]
	v_pk_mov_b32 v[44:45], v[180:181], v[180:181] op_sel:[0,1]
	v_pk_mov_b32 v[46:47], v[182:183], v[182:183] op_sel:[0,1]
	v_pk_mov_b32 v[48:49], v[184:185], v[184:185] op_sel:[0,1]
	v_pk_mul_f32 v[102:103], v[40:41], v[50:51] op_sel:[0,1]
	v_pk_mul_f32 v[104:105], v[38:39], v[50:51] op_sel:[0,1]
	v_pk_fma_f32 v[102:103], v[36:37], v[50:51], v[102:103] op_sel_hi:[1,0,1]
	v_pk_fma_f32 v[50:51], v[34:35], v[50:51], v[104:105] op_sel_hi:[1,0,1]
	v_mov_b32_e32 v104, v53
	v_pk_mul_f32 v[106:107], v[48:49], v[104:105] op_sel_hi:[1,0]
	v_pk_mul_f32 v[104:105], v[46:47], v[104:105] op_sel_hi:[1,0]
	v_pk_fma_f32 v[106:107], v[44:45], v[52:53], v[106:107] op_sel_hi:[1,0,1]
	v_pk_fma_f32 v[52:53], v[42:43], v[52:53], v[104:105] op_sel_hi:[1,0,1]
	v_pk_add_f32 v[102:103], v[102:103], v[106:107]
	v_pk_add_f32 v[50:51], v[50:51], v[52:53]
	v_pk_add_f32 v[4:5], v[4:5], v[102:103]
	v_pk_add_f32 v[2:3], v[2:3], v[50:51]
	ds_read_b128 v[50:53], v56 offset:4112
	s_waitcnt lgkmcnt(0)
	v_pk_mul_f32 v[102:103], v[40:41], v[50:51] op_sel:[0,1]
	v_pk_mul_f32 v[104:105], v[38:39], v[50:51] op_sel:[0,1]
	v_pk_fma_f32 v[102:103], v[36:37], v[50:51], v[102:103] op_sel_hi:[1,0,1]
	v_pk_fma_f32 v[50:51], v[34:35], v[50:51], v[104:105] op_sel_hi:[1,0,1]
	v_mov_b32_e32 v104, v53
	v_pk_mul_f32 v[106:107], v[48:49], v[104:105] op_sel_hi:[1,0]
	v_pk_mul_f32 v[104:105], v[46:47], v[104:105] op_sel_hi:[1,0]
	v_pk_fma_f32 v[106:107], v[44:45], v[52:53], v[106:107] op_sel_hi:[1,0,1]
	v_pk_fma_f32 v[52:53], v[42:43], v[52:53], v[104:105] op_sel_hi:[1,0,1]
	v_pk_add_f32 v[102:103], v[102:103], v[106:107]
	v_pk_add_f32 v[50:51], v[50:51], v[52:53]
	v_pk_add_f32 v[8:9], v[8:9], v[102:103]
	v_pk_add_f32 v[6:7], v[6:7], v[50:51]
	ds_read_b128 v[50:53], v56 offset:8208
	s_waitcnt lgkmcnt(0)
	v_pk_mul_f32 v[102:103], v[40:41], v[50:51] op_sel:[0,1]
	v_pk_mul_f32 v[104:105], v[38:39], v[50:51] op_sel:[0,1]
	v_pk_fma_f32 v[102:103], v[36:37], v[50:51], v[102:103] op_sel_hi:[1,0,1]
	v_pk_fma_f32 v[50:51], v[34:35], v[50:51], v[104:105] op_sel_hi:[1,0,1]
	v_mov_b32_e32 v104, v53
	v_pk_mul_f32 v[106:107], v[48:49], v[104:105] op_sel_hi:[1,0]
	v_pk_mul_f32 v[104:105], v[46:47], v[104:105] op_sel_hi:[1,0]
	v_pk_fma_f32 v[106:107], v[44:45], v[52:53], v[106:107] op_sel_hi:[1,0,1]
	v_pk_fma_f32 v[52:53], v[42:43], v[52:53], v[104:105] op_sel_hi:[1,0,1]
	v_pk_add_f32 v[102:103], v[102:103], v[106:107]
	v_pk_add_f32 v[50:51], v[50:51], v[52:53]
	v_pk_add_f32 v[12:13], v[12:13], v[102:103]
	v_pk_add_f32 v[10:11], v[10:11], v[50:51]
	ds_read_b128 v[50:53], v56 offset:12304
	s_waitcnt lgkmcnt(0)
	v_pk_mul_f32 v[102:103], v[40:41], v[50:51] op_sel:[0,1]
	v_pk_mul_f32 v[104:105], v[38:39], v[50:51] op_sel:[0,1]
	v_pk_fma_f32 v[102:103], v[36:37], v[50:51], v[102:103] op_sel_hi:[1,0,1]
	v_pk_fma_f32 v[50:51], v[34:35], v[50:51], v[104:105] op_sel_hi:[1,0,1]
	v_mov_b32_e32 v104, v53
	v_pk_mul_f32 v[106:107], v[48:49], v[104:105] op_sel_hi:[1,0]
	v_pk_mul_f32 v[104:105], v[46:47], v[104:105] op_sel_hi:[1,0]
	v_pk_fma_f32 v[106:107], v[44:45], v[52:53], v[106:107] op_sel_hi:[1,0,1]
	v_pk_fma_f32 v[52:53], v[42:43], v[52:53], v[104:105] op_sel_hi:[1,0,1]
	v_pk_add_f32 v[102:103], v[102:103], v[106:107]
	v_pk_add_f32 v[50:51], v[50:51], v[52:53]
	v_pk_add_f32 v[16:17], v[16:17], v[102:103]
	v_pk_add_f32 v[14:15], v[14:15], v[50:51]
	ds_read_b128 v[50:53], v56 offset:16400
	s_waitcnt lgkmcnt(0)
	v_pk_mul_f32 v[102:103], v[40:41], v[50:51] op_sel:[0,1]
	v_pk_mul_f32 v[104:105], v[38:39], v[50:51] op_sel:[0,1]
	v_pk_fma_f32 v[102:103], v[36:37], v[50:51], v[102:103] op_sel_hi:[1,0,1]
	v_pk_fma_f32 v[50:51], v[34:35], v[50:51], v[104:105] op_sel_hi:[1,0,1]
	v_mov_b32_e32 v104, v53
	v_pk_mul_f32 v[106:107], v[48:49], v[104:105] op_sel_hi:[1,0]
	v_pk_mul_f32 v[104:105], v[46:47], v[104:105] op_sel_hi:[1,0]
	v_pk_fma_f32 v[106:107], v[44:45], v[52:53], v[106:107] op_sel_hi:[1,0,1]
	v_pk_fma_f32 v[52:53], v[42:43], v[52:53], v[104:105] op_sel_hi:[1,0,1]
	v_pk_add_f32 v[102:103], v[102:103], v[106:107]
	v_pk_add_f32 v[50:51], v[50:51], v[52:53]
	v_pk_add_f32 v[20:21], v[20:21], v[102:103]
	v_pk_add_f32 v[18:19], v[18:19], v[50:51]
	ds_read_b128 v[50:53], v56 offset:20496
	s_waitcnt lgkmcnt(0)
	v_pk_mul_f32 v[102:103], v[40:41], v[50:51] op_sel:[0,1]
	v_pk_mul_f32 v[104:105], v[38:39], v[50:51] op_sel:[0,1]
	v_pk_fma_f32 v[102:103], v[36:37], v[50:51], v[102:103] op_sel_hi:[1,0,1]
	v_pk_fma_f32 v[50:51], v[34:35], v[50:51], v[104:105] op_sel_hi:[1,0,1]
	v_mov_b32_e32 v104, v53
	v_pk_mul_f32 v[106:107], v[48:49], v[104:105] op_sel_hi:[1,0]
	v_pk_mul_f32 v[104:105], v[46:47], v[104:105] op_sel_hi:[1,0]
	v_pk_fma_f32 v[106:107], v[44:45], v[52:53], v[106:107] op_sel_hi:[1,0,1]
	v_pk_fma_f32 v[52:53], v[42:43], v[52:53], v[104:105] op_sel_hi:[1,0,1]
	v_pk_add_f32 v[102:103], v[102:103], v[106:107]
	v_pk_add_f32 v[50:51], v[50:51], v[52:53]
	v_pk_add_f32 v[24:25], v[24:25], v[102:103]
	v_pk_add_f32 v[22:23], v[22:23], v[50:51]
	ds_read_b128 v[50:53], v56 offset:24592
	s_waitcnt lgkmcnt(0)
	v_pk_mul_f32 v[102:103], v[40:41], v[50:51] op_sel:[0,1]
	v_pk_mul_f32 v[104:105], v[38:39], v[50:51] op_sel:[0,1]
	v_pk_fma_f32 v[102:103], v[36:37], v[50:51], v[102:103] op_sel_hi:[1,0,1]
	v_pk_fma_f32 v[50:51], v[34:35], v[50:51], v[104:105] op_sel_hi:[1,0,1]
	v_mov_b32_e32 v104, v53
	v_pk_mul_f32 v[106:107], v[48:49], v[104:105] op_sel_hi:[1,0]
	v_pk_mul_f32 v[104:105], v[46:47], v[104:105] op_sel_hi:[1,0]
	v_pk_fma_f32 v[106:107], v[44:45], v[52:53], v[106:107] op_sel_hi:[1,0,1]
	v_pk_fma_f32 v[52:53], v[42:43], v[52:53], v[104:105] op_sel_hi:[1,0,1]
	v_pk_add_f32 v[102:103], v[102:103], v[106:107]
	v_pk_add_f32 v[50:51], v[50:51], v[52:53]
	v_pk_add_f32 v[28:29], v[28:29], v[102:103]
	v_pk_add_f32 v[26:27], v[26:27], v[50:51]
	ds_read_b128 v[50:53], v56 offset:28688
	s_waitcnt lgkmcnt(0)
	v_pk_mul_f32 v[102:103], v[40:41], v[50:51] op_sel:[0,1]
	v_pk_mul_f32 v[104:105], v[38:39], v[50:51] op_sel:[0,1]
	v_pk_fma_f32 v[102:103], v[36:37], v[50:51], v[102:103] op_sel_hi:[1,0,1]
	v_pk_fma_f32 v[50:51], v[34:35], v[50:51], v[104:105] op_sel_hi:[1,0,1]
	v_mov_b32_e32 v104, v53
	v_pk_mul_f32 v[106:107], v[48:49], v[104:105] op_sel_hi:[1,0]
	v_pk_mul_f32 v[104:105], v[46:47], v[104:105] op_sel_hi:[1,0]
	v_pk_fma_f32 v[106:107], v[44:45], v[52:53], v[106:107] op_sel_hi:[1,0,1]
	v_pk_fma_f32 v[52:53], v[42:43], v[52:53], v[104:105] op_sel_hi:[1,0,1]
	v_pk_add_f32 v[102:103], v[102:103], v[106:107]
	v_pk_add_f32 v[50:51], v[50:51], v[52:53]
	v_pk_add_f32 v[32:33], v[32:33], v[102:103]
	v_pk_add_f32 v[30:31], v[30:31], v[50:51]
	ds_read_b128 v[50:53], v56 offset:32784
	v_add_u32_e32 v56, 32, v56
	s_waitcnt lgkmcnt(0)
	v_pk_mul_f32 v[38:39], v[38:39], v[50:51] op_sel:[0,1]
	v_pk_mul_f32 v[40:41], v[40:41], v[50:51] op_sel:[0,1]
	v_pk_fma_f32 v[34:35], v[34:35], v[50:51], v[38:39] op_sel_hi:[1,0,1]
	v_mov_b32_e32 v38, v53
	v_pk_fma_f32 v[36:37], v[36:37], v[50:51], v[40:41] op_sel_hi:[1,0,1]
	v_pk_mul_f32 v[40:41], v[48:49], v[38:39] op_sel_hi:[1,0]
	v_pk_mul_f32 v[38:39], v[46:47], v[38:39] op_sel_hi:[1,0]
	v_pk_fma_f32 v[40:41], v[44:45], v[52:53], v[40:41] op_sel_hi:[1,0,1]
	v_pk_fma_f32 v[38:39], v[42:43], v[52:53], v[38:39] op_sel_hi:[1,0,1]
	v_pk_add_f32 v[36:37], v[36:37], v[40:41]
	v_pk_add_f32 v[34:35], v[34:35], v[38:39]
	v_pk_add_f32 v[36:37], v[74:75], v[36:37]
	v_pk_add_f32 v[34:35], v[76:77], v[34:35]
	v_add_co_u32_e32 v250, vcc, 0xc0000, v72
	s_nop 1
	v_addc_co_u32_e32 v251, vcc, 0, v73, vcc
	global_load_dwordx4 v[122:125], v[250:251], off
	v_add_co_u32_e32 v252, vcc, 0xc6000, v72
	s_nop 1
	v_addc_co_u32_e32 v253, vcc, 0, v73, vcc
	global_load_dwordx4 v[126:129], v[252:253], off
	v_add_co_u32_e32 v250, vcc, 0xcc000, v72
	s_nop 1
	v_addc_co_u32_e32 v251, vcc, 0, v73, vcc
	global_load_dwordx4 v[130:133], v[250:251], off
	v_add_co_u32_e32 v252, vcc, 0xd2000, v72
	s_nop 1
	v_addc_co_u32_e32 v253, vcc, 0, v73, vcc
	global_load_dwordx4 v[134:137], v[252:253], off
	v_add_co_u32_e32 v250, vcc, 0xd8000, v72
	s_nop 1
	v_addc_co_u32_e32 v251, vcc, 0, v73, vcc
	global_load_dwordx4 v[138:141], v[250:251], off
	v_add_co_u32_e32 v252, vcc, 0xde000, v72
	s_nop 1
	v_addc_co_u32_e32 v253, vcc, 0, v73, vcc
	global_load_dwordx4 v[142:145], v[252:253], off
	v_add_co_u32_e32 v250, vcc, 0xe4000, v72
	s_nop 1
	v_addc_co_u32_e32 v251, vcc, 0, v73, vcc
	global_load_dwordx4 v[146:149], v[250:251], off
	v_add_co_u32_e32 v252, vcc, 0xea000, v72
	s_nop 1
	v_addc_co_u32_e32 v253, vcc, 0, v73, vcc
	global_load_dwordx4 v[150:153], v[252:253], off
	v_add_co_u32_e32 v250, vcc, 0xf0000, v72
	s_nop 1
	v_addc_co_u32_e32 v251, vcc, 0, v73, vcc
	global_load_dwordx4 v[154:157], v[250:251], off
	v_add_co_u32_e32 v252, vcc, 0xf6000, v72
	s_nop 1
	v_addc_co_u32_e32 v253, vcc, 0, v73, vcc
	global_load_dwordx4 v[158:161], v[252:253], off
	v_add_co_u32_e32 v250, vcc, 0xfc000, v72
	s_nop 1
	v_addc_co_u32_e32 v251, vcc, 0, v73, vcc
	global_load_dwordx4 v[162:165], v[250:251], off
	v_add_co_u32_e32 v252, vcc, 0x102000, v72
	s_nop 1
	v_addc_co_u32_e32 v253, vcc, 0, v73, vcc
	global_load_dwordx4 v[166:169], v[252:253], off
	v_add_co_u32_e32 v250, vcc, 0x108000, v72
	s_nop 1
	v_addc_co_u32_e32 v251, vcc, 0, v73, vcc
	global_load_dwordx4 v[170:173], v[250:251], off
	v_add_co_u32_e32 v252, vcc, 0x10e000, v72
	s_nop 1
	v_addc_co_u32_e32 v253, vcc, 0, v73, vcc
	global_load_dwordx4 v[174:177], v[252:253], off
	v_add_co_u32_e32 v250, vcc, 0x114000, v72
	s_nop 1
	v_addc_co_u32_e32 v251, vcc, 0, v73, vcc
	global_load_dwordx4 v[178:181], v[250:251], off
	v_add_co_u32_e32 v252, vcc, 0x11a000, v72
	s_nop 1
	v_addc_co_u32_e32 v253, vcc, 0, v73, vcc
	global_load_dwordx4 v[182:185], v[252:253], off
	s_waitcnt vmcnt(16)
	v_pk_mov_b32 v[38:39], v[186:187], v[186:187] op_sel:[0,1]
	v_pk_mov_b32 v[40:41], v[188:189], v[188:189] op_sel:[0,1]
	v_pk_mov_b32 v[42:43], v[190:191], v[190:191] op_sel:[0,1]
	v_pk_mov_b32 v[44:45], v[192:193], v[192:193] op_sel:[0,1]
	v_pk_mov_b32 v[74:75], v[194:195], v[194:195] op_sel:[0,1]
	v_pk_mov_b32 v[76:77], v[196:197], v[196:197] op_sel:[0,1]
	v_pk_mov_b32 v[102:103], v[198:199], v[198:199] op_sel:[0,1]
	v_pk_mov_b32 v[104:105], v[200:201], v[200:201] op_sel:[0,1]
	ds_read_b128 v[106:109], v56
	ds_read_b128 v[50:53], v56 offset:16
	s_waitcnt lgkmcnt(1)
	v_pk_mul_f32 v[48:49], v[44:45], v[106:107] op_sel:[0,1]
	v_pk_mul_f32 v[110:111], v[42:43], v[106:107] op_sel:[0,1]
	v_pk_fma_f32 v[48:49], v[40:41], v[106:107], v[48:49] op_sel_hi:[1,0,1]
	v_pk_fma_f32 v[106:107], v[38:39], v[106:107], v[110:111] op_sel_hi:[1,0,1]
	v_mov_b32_e32 v110, v109
	v_pk_mul_f32 v[112:113], v[104:105], v[110:111] op_sel_hi:[1,0]
	v_pk_mul_f32 v[110:111], v[102:103], v[110:111] op_sel_hi:[1,0]
	v_pk_fma_f32 v[112:113], v[76:77], v[108:109], v[112:113] op_sel_hi:[1,0,1]
	v_pk_fma_f32 v[108:109], v[74:75], v[108:109], v[110:111] op_sel_hi:[1,0,1]
	v_pk_add_f32 v[48:49], v[48:49], v[112:113]
	v_pk_add_f32 v[106:107], v[106:107], v[108:109]
	v_pk_add_f32 v[4:5], v[4:5], v[48:49]
	v_pk_add_f32 v[2:3], v[2:3], v[106:107]
	ds_read_b128 v[106:109], v56 offset:4096
	s_waitcnt lgkmcnt(0)
	v_pk_mul_f32 v[48:49], v[44:45], v[106:107] op_sel:[0,1]
	v_pk_mul_f32 v[110:111], v[42:43], v[106:107] op_sel:[0,1]
	v_pk_fma_f32 v[48:49], v[40:41], v[106:107], v[48:49] op_sel_hi:[1,0,1]
	v_pk_fma_f32 v[106:107], v[38:39], v[106:107], v[110:111] op_sel_hi:[1,0,1]
	v_mov_b32_e32 v110, v109
	v_pk_mul_f32 v[112:113], v[104:105], v[110:111] op_sel_hi:[1,0]
	v_pk_mul_f32 v[110:111], v[102:103], v[110:111] op_sel_hi:[1,0]
	v_pk_fma_f32 v[112:113], v[76:77], v[108:109], v[112:113] op_sel_hi:[1,0,1]
	v_pk_fma_f32 v[108:109], v[74:75], v[108:109], v[110:111] op_sel_hi:[1,0,1]
	v_pk_add_f32 v[48:49], v[48:49], v[112:113]
	v_pk_add_f32 v[106:107], v[106:107], v[108:109]
	v_pk_add_f32 v[8:9], v[8:9], v[48:49]
	v_pk_add_f32 v[6:7], v[6:7], v[106:107]
	ds_read_b128 v[106:109], v56 offset:8192
	s_waitcnt lgkmcnt(0)
	v_pk_mul_f32 v[48:49], v[44:45], v[106:107] op_sel:[0,1]
	v_pk_mul_f32 v[110:111], v[42:43], v[106:107] op_sel:[0,1]
	v_pk_fma_f32 v[48:49], v[40:41], v[106:107], v[48:49] op_sel_hi:[1,0,1]
	v_pk_fma_f32 v[106:107], v[38:39], v[106:107], v[110:111] op_sel_hi:[1,0,1]
	v_mov_b32_e32 v110, v109
	v_pk_mul_f32 v[112:113], v[104:105], v[110:111] op_sel_hi:[1,0]
	v_pk_mul_f32 v[110:111], v[102:103], v[110:111] op_sel_hi:[1,0]
	v_pk_fma_f32 v[112:113], v[76:77], v[108:109], v[112:113] op_sel_hi:[1,0,1]
	v_pk_fma_f32 v[108:109], v[74:75], v[108:109], v[110:111] op_sel_hi:[1,0,1]
	v_pk_add_f32 v[48:49], v[48:49], v[112:113]
	v_pk_add_f32 v[106:107], v[106:107], v[108:109]
	v_pk_add_f32 v[12:13], v[12:13], v[48:49]
	v_pk_add_f32 v[10:11], v[10:11], v[106:107]
	ds_read_b128 v[106:109], v56 offset:12288
	s_waitcnt lgkmcnt(0)
	v_pk_mul_f32 v[48:49], v[44:45], v[106:107] op_sel:[0,1]
	v_pk_mul_f32 v[110:111], v[42:43], v[106:107] op_sel:[0,1]
	v_pk_fma_f32 v[48:49], v[40:41], v[106:107], v[48:49] op_sel_hi:[1,0,1]
	v_pk_fma_f32 v[106:107], v[38:39], v[106:107], v[110:111] op_sel_hi:[1,0,1]
	v_mov_b32_e32 v110, v109
	v_pk_mul_f32 v[112:113], v[104:105], v[110:111] op_sel_hi:[1,0]
	v_pk_mul_f32 v[110:111], v[102:103], v[110:111] op_sel_hi:[1,0]
	v_pk_fma_f32 v[112:113], v[76:77], v[108:109], v[112:113] op_sel_hi:[1,0,1]
	v_pk_fma_f32 v[108:109], v[74:75], v[108:109], v[110:111] op_sel_hi:[1,0,1]
	v_pk_add_f32 v[48:49], v[48:49], v[112:113]
	v_pk_add_f32 v[106:107], v[106:107], v[108:109]
	v_pk_add_f32 v[16:17], v[16:17], v[48:49]
	v_pk_add_f32 v[14:15], v[14:15], v[106:107]
	ds_read_b128 v[106:109], v56 offset:16384
	s_waitcnt lgkmcnt(0)
	v_pk_mul_f32 v[48:49], v[44:45], v[106:107] op_sel:[0,1]
	v_pk_mul_f32 v[110:111], v[42:43], v[106:107] op_sel:[0,1]
	v_pk_fma_f32 v[48:49], v[40:41], v[106:107], v[48:49] op_sel_hi:[1,0,1]
	v_pk_fma_f32 v[106:107], v[38:39], v[106:107], v[110:111] op_sel_hi:[1,0,1]
	v_mov_b32_e32 v110, v109
	v_pk_mul_f32 v[112:113], v[104:105], v[110:111] op_sel_hi:[1,0]
	v_pk_mul_f32 v[110:111], v[102:103], v[110:111] op_sel_hi:[1,0]
	v_pk_fma_f32 v[112:113], v[76:77], v[108:109], v[112:113] op_sel_hi:[1,0,1]
	v_pk_fma_f32 v[108:109], v[74:75], v[108:109], v[110:111] op_sel_hi:[1,0,1]
	v_pk_add_f32 v[48:49], v[48:49], v[112:113]
	v_pk_add_f32 v[106:107], v[106:107], v[108:109]
	v_pk_add_f32 v[20:21], v[20:21], v[48:49]
	v_pk_add_f32 v[18:19], v[18:19], v[106:107]
	ds_read_b128 v[106:109], v56 offset:20480
	s_waitcnt lgkmcnt(0)
	v_pk_mul_f32 v[48:49], v[44:45], v[106:107] op_sel:[0,1]
	v_pk_mul_f32 v[110:111], v[42:43], v[106:107] op_sel:[0,1]
	v_pk_fma_f32 v[48:49], v[40:41], v[106:107], v[48:49] op_sel_hi:[1,0,1]
	v_pk_fma_f32 v[106:107], v[38:39], v[106:107], v[110:111] op_sel_hi:[1,0,1]
	v_mov_b32_e32 v110, v109
	v_pk_mul_f32 v[112:113], v[104:105], v[110:111] op_sel_hi:[1,0]
	v_pk_mul_f32 v[110:111], v[102:103], v[110:111] op_sel_hi:[1,0]
	v_pk_fma_f32 v[112:113], v[76:77], v[108:109], v[112:113] op_sel_hi:[1,0,1]
	v_pk_fma_f32 v[108:109], v[74:75], v[108:109], v[110:111] op_sel_hi:[1,0,1]
	v_pk_add_f32 v[48:49], v[48:49], v[112:113]
	v_pk_add_f32 v[106:107], v[106:107], v[108:109]
	v_pk_add_f32 v[24:25], v[24:25], v[48:49]
	v_pk_add_f32 v[22:23], v[22:23], v[106:107]
	ds_read_b128 v[106:109], v56 offset:24576
	s_waitcnt lgkmcnt(0)
	v_pk_mul_f32 v[48:49], v[44:45], v[106:107] op_sel:[0,1]
	v_pk_mul_f32 v[110:111], v[42:43], v[106:107] op_sel:[0,1]
	v_pk_fma_f32 v[48:49], v[40:41], v[106:107], v[48:49] op_sel_hi:[1,0,1]
	v_pk_fma_f32 v[106:107], v[38:39], v[106:107], v[110:111] op_sel_hi:[1,0,1]
	v_mov_b32_e32 v110, v109
	v_pk_mul_f32 v[112:113], v[104:105], v[110:111] op_sel_hi:[1,0]
	v_pk_mul_f32 v[110:111], v[102:103], v[110:111] op_sel_hi:[1,0]
	v_pk_fma_f32 v[112:113], v[76:77], v[108:109], v[112:113] op_sel_hi:[1,0,1]
	v_pk_fma_f32 v[108:109], v[74:75], v[108:109], v[110:111] op_sel_hi:[1,0,1]
	v_pk_add_f32 v[48:49], v[48:49], v[112:113]
	v_pk_add_f32 v[106:107], v[106:107], v[108:109]
	v_pk_add_f32 v[28:29], v[28:29], v[48:49]
	v_pk_add_f32 v[26:27], v[26:27], v[106:107]
	ds_read_b128 v[106:109], v56 offset:28672
	s_waitcnt lgkmcnt(0)
	v_pk_mul_f32 v[48:49], v[44:45], v[106:107] op_sel:[0,1]
	v_pk_mul_f32 v[110:111], v[42:43], v[106:107] op_sel:[0,1]
	v_pk_fma_f32 v[48:49], v[40:41], v[106:107], v[48:49] op_sel_hi:[1,0,1]
	v_pk_fma_f32 v[106:107], v[38:39], v[106:107], v[110:111] op_sel_hi:[1,0,1]
	v_mov_b32_e32 v110, v109
	v_pk_mul_f32 v[112:113], v[104:105], v[110:111] op_sel_hi:[1,0]
	v_pk_mul_f32 v[110:111], v[102:103], v[110:111] op_sel_hi:[1,0]
	v_pk_fma_f32 v[112:113], v[76:77], v[108:109], v[112:113] op_sel_hi:[1,0,1]
	v_pk_fma_f32 v[108:109], v[74:75], v[108:109], v[110:111] op_sel_hi:[1,0,1]
	v_pk_add_f32 v[48:49], v[48:49], v[112:113]
	v_pk_add_f32 v[106:107], v[106:107], v[108:109]
	v_pk_add_f32 v[32:33], v[32:33], v[48:49]
	v_pk_add_f32 v[30:31], v[30:31], v[106:107]
	ds_read_b128 v[106:109], v56 offset:32768
	s_waitcnt lgkmcnt(0)
	v_pk_mul_f32 v[42:43], v[42:43], v[106:107] op_sel:[0,1]
	v_pk_mul_f32 v[44:45], v[44:45], v[106:107] op_sel:[0,1]
	v_pk_fma_f32 v[38:39], v[38:39], v[106:107], v[42:43] op_sel_hi:[1,0,1]
	v_mov_b32_e32 v42, v109
	v_pk_fma_f32 v[40:41], v[40:41], v[106:107], v[44:45] op_sel_hi:[1,0,1]
	v_pk_mul_f32 v[44:45], v[104:105], v[42:43] op_sel_hi:[1,0]
	v_pk_mul_f32 v[42:43], v[102:103], v[42:43] op_sel_hi:[1,0]
	v_pk_fma_f32 v[44:45], v[76:77], v[108:109], v[44:45] op_sel_hi:[1,0,1]
	v_pk_fma_f32 v[42:43], v[74:75], v[108:109], v[42:43] op_sel_hi:[1,0,1]
	v_pk_add_f32 v[40:41], v[40:41], v[44:45]
	v_pk_add_f32 v[38:39], v[38:39], v[42:43]
	v_pk_add_f32 v[74:75], v[36:37], v[40:41]
	v_pk_add_f32 v[76:77], v[34:35], v[38:39]
	v_pk_mov_b32 v[34:35], v[202:203], v[202:203] op_sel:[0,1]
	v_pk_mov_b32 v[36:37], v[204:205], v[204:205] op_sel:[0,1]
	v_pk_mov_b32 v[38:39], v[206:207], v[206:207] op_sel:[0,1]
	v_pk_mov_b32 v[40:41], v[208:209], v[208:209] op_sel:[0,1]
	v_pk_mov_b32 v[42:43], v[210:211], v[210:211] op_sel:[0,1]
	v_pk_mov_b32 v[44:45], v[212:213], v[212:213] op_sel:[0,1]
	v_pk_mov_b32 v[46:47], v[214:215], v[214:215] op_sel:[0,1]
	v_pk_mov_b32 v[48:49], v[216:217], v[216:217] op_sel:[0,1]
	v_pk_mul_f32 v[102:103], v[40:41], v[50:51] op_sel:[0,1]
	v_pk_mul_f32 v[104:105], v[38:39], v[50:51] op_sel:[0,1]
	v_pk_fma_f32 v[102:103], v[36:37], v[50:51], v[102:103] op_sel_hi:[1,0,1]
	v_pk_fma_f32 v[50:51], v[34:35], v[50:51], v[104:105] op_sel_hi:[1,0,1]
	v_mov_b32_e32 v104, v53
	v_pk_mul_f32 v[106:107], v[48:49], v[104:105] op_sel_hi:[1,0]
	v_pk_mul_f32 v[104:105], v[46:47], v[104:105] op_sel_hi:[1,0]
	v_pk_fma_f32 v[106:107], v[44:45], v[52:53], v[106:107] op_sel_hi:[1,0,1]
	v_pk_fma_f32 v[52:53], v[42:43], v[52:53], v[104:105] op_sel_hi:[1,0,1]
	v_pk_add_f32 v[102:103], v[102:103], v[106:107]
	v_pk_add_f32 v[50:51], v[50:51], v[52:53]
	v_pk_add_f32 v[4:5], v[4:5], v[102:103]
	v_pk_add_f32 v[2:3], v[2:3], v[50:51]
	ds_read_b128 v[50:53], v56 offset:4112
	s_waitcnt lgkmcnt(0)
	v_pk_mul_f32 v[102:103], v[40:41], v[50:51] op_sel:[0,1]
	v_pk_mul_f32 v[104:105], v[38:39], v[50:51] op_sel:[0,1]
	v_pk_fma_f32 v[102:103], v[36:37], v[50:51], v[102:103] op_sel_hi:[1,0,1]
	v_pk_fma_f32 v[50:51], v[34:35], v[50:51], v[104:105] op_sel_hi:[1,0,1]
	v_mov_b32_e32 v104, v53
	v_pk_mul_f32 v[106:107], v[48:49], v[104:105] op_sel_hi:[1,0]
	v_pk_mul_f32 v[104:105], v[46:47], v[104:105] op_sel_hi:[1,0]
	v_pk_fma_f32 v[106:107], v[44:45], v[52:53], v[106:107] op_sel_hi:[1,0,1]
	v_pk_fma_f32 v[52:53], v[42:43], v[52:53], v[104:105] op_sel_hi:[1,0,1]
	v_pk_add_f32 v[102:103], v[102:103], v[106:107]
	v_pk_add_f32 v[50:51], v[50:51], v[52:53]
	v_pk_add_f32 v[8:9], v[8:9], v[102:103]
	v_pk_add_f32 v[6:7], v[6:7], v[50:51]
	ds_read_b128 v[50:53], v56 offset:8208
	s_waitcnt lgkmcnt(0)
	v_pk_mul_f32 v[102:103], v[40:41], v[50:51] op_sel:[0,1]
	v_pk_mul_f32 v[104:105], v[38:39], v[50:51] op_sel:[0,1]
	v_pk_fma_f32 v[102:103], v[36:37], v[50:51], v[102:103] op_sel_hi:[1,0,1]
	v_pk_fma_f32 v[50:51], v[34:35], v[50:51], v[104:105] op_sel_hi:[1,0,1]
	v_mov_b32_e32 v104, v53
	v_pk_mul_f32 v[106:107], v[48:49], v[104:105] op_sel_hi:[1,0]
	v_pk_mul_f32 v[104:105], v[46:47], v[104:105] op_sel_hi:[1,0]
	v_pk_fma_f32 v[106:107], v[44:45], v[52:53], v[106:107] op_sel_hi:[1,0,1]
	v_pk_fma_f32 v[52:53], v[42:43], v[52:53], v[104:105] op_sel_hi:[1,0,1]
	v_pk_add_f32 v[102:103], v[102:103], v[106:107]
	v_pk_add_f32 v[50:51], v[50:51], v[52:53]
	v_pk_add_f32 v[12:13], v[12:13], v[102:103]
	v_pk_add_f32 v[10:11], v[10:11], v[50:51]
	ds_read_b128 v[50:53], v56 offset:12304
	s_waitcnt lgkmcnt(0)
	v_pk_mul_f32 v[102:103], v[40:41], v[50:51] op_sel:[0,1]
	v_pk_mul_f32 v[104:105], v[38:39], v[50:51] op_sel:[0,1]
	v_pk_fma_f32 v[102:103], v[36:37], v[50:51], v[102:103] op_sel_hi:[1,0,1]
	v_pk_fma_f32 v[50:51], v[34:35], v[50:51], v[104:105] op_sel_hi:[1,0,1]
	v_mov_b32_e32 v104, v53
	v_pk_mul_f32 v[106:107], v[48:49], v[104:105] op_sel_hi:[1,0]
	v_pk_mul_f32 v[104:105], v[46:47], v[104:105] op_sel_hi:[1,0]
	v_pk_fma_f32 v[106:107], v[44:45], v[52:53], v[106:107] op_sel_hi:[1,0,1]
	v_pk_fma_f32 v[52:53], v[42:43], v[52:53], v[104:105] op_sel_hi:[1,0,1]
	v_pk_add_f32 v[102:103], v[102:103], v[106:107]
	v_pk_add_f32 v[50:51], v[50:51], v[52:53]
	v_pk_add_f32 v[16:17], v[16:17], v[102:103]
	v_pk_add_f32 v[14:15], v[14:15], v[50:51]
	ds_read_b128 v[50:53], v56 offset:16400
	s_waitcnt lgkmcnt(0)
	v_pk_mul_f32 v[102:103], v[40:41], v[50:51] op_sel:[0,1]
	v_pk_mul_f32 v[104:105], v[38:39], v[50:51] op_sel:[0,1]
	v_pk_fma_f32 v[102:103], v[36:37], v[50:51], v[102:103] op_sel_hi:[1,0,1]
	v_pk_fma_f32 v[50:51], v[34:35], v[50:51], v[104:105] op_sel_hi:[1,0,1]
	v_mov_b32_e32 v104, v53
	v_pk_mul_f32 v[106:107], v[48:49], v[104:105] op_sel_hi:[1,0]
	v_pk_mul_f32 v[104:105], v[46:47], v[104:105] op_sel_hi:[1,0]
	v_pk_fma_f32 v[106:107], v[44:45], v[52:53], v[106:107] op_sel_hi:[1,0,1]
	v_pk_fma_f32 v[52:53], v[42:43], v[52:53], v[104:105] op_sel_hi:[1,0,1]
	v_pk_add_f32 v[102:103], v[102:103], v[106:107]
	v_pk_add_f32 v[50:51], v[50:51], v[52:53]
	v_pk_add_f32 v[20:21], v[20:21], v[102:103]
	v_pk_add_f32 v[18:19], v[18:19], v[50:51]
	ds_read_b128 v[50:53], v56 offset:20496
	s_waitcnt lgkmcnt(0)
	v_pk_mul_f32 v[102:103], v[40:41], v[50:51] op_sel:[0,1]
	v_pk_mul_f32 v[104:105], v[38:39], v[50:51] op_sel:[0,1]
	v_pk_fma_f32 v[102:103], v[36:37], v[50:51], v[102:103] op_sel_hi:[1,0,1]
	v_pk_fma_f32 v[50:51], v[34:35], v[50:51], v[104:105] op_sel_hi:[1,0,1]
	v_mov_b32_e32 v104, v53
	v_pk_mul_f32 v[106:107], v[48:49], v[104:105] op_sel_hi:[1,0]
	v_pk_mul_f32 v[104:105], v[46:47], v[104:105] op_sel_hi:[1,0]
	v_pk_fma_f32 v[106:107], v[44:45], v[52:53], v[106:107] op_sel_hi:[1,0,1]
	v_pk_fma_f32 v[52:53], v[42:43], v[52:53], v[104:105] op_sel_hi:[1,0,1]
	v_pk_add_f32 v[102:103], v[102:103], v[106:107]
	v_pk_add_f32 v[50:51], v[50:51], v[52:53]
	v_pk_add_f32 v[24:25], v[24:25], v[102:103]
	v_pk_add_f32 v[22:23], v[22:23], v[50:51]
	ds_read_b128 v[50:53], v56 offset:24592
	s_waitcnt lgkmcnt(0)
	v_pk_mul_f32 v[102:103], v[40:41], v[50:51] op_sel:[0,1]
	v_pk_mul_f32 v[104:105], v[38:39], v[50:51] op_sel:[0,1]
	v_pk_fma_f32 v[102:103], v[36:37], v[50:51], v[102:103] op_sel_hi:[1,0,1]
	v_pk_fma_f32 v[50:51], v[34:35], v[50:51], v[104:105] op_sel_hi:[1,0,1]
	v_mov_b32_e32 v104, v53
	v_pk_mul_f32 v[106:107], v[48:49], v[104:105] op_sel_hi:[1,0]
	v_pk_mul_f32 v[104:105], v[46:47], v[104:105] op_sel_hi:[1,0]
	v_pk_fma_f32 v[106:107], v[44:45], v[52:53], v[106:107] op_sel_hi:[1,0,1]
	v_pk_fma_f32 v[52:53], v[42:43], v[52:53], v[104:105] op_sel_hi:[1,0,1]
	v_pk_add_f32 v[102:103], v[102:103], v[106:107]
	v_pk_add_f32 v[50:51], v[50:51], v[52:53]
	v_pk_add_f32 v[28:29], v[28:29], v[102:103]
	v_pk_add_f32 v[26:27], v[26:27], v[50:51]
	ds_read_b128 v[50:53], v56 offset:28688
	s_waitcnt lgkmcnt(0)
	v_pk_mul_f32 v[102:103], v[40:41], v[50:51] op_sel:[0,1]
	v_pk_mul_f32 v[104:105], v[38:39], v[50:51] op_sel:[0,1]
	v_pk_fma_f32 v[102:103], v[36:37], v[50:51], v[102:103] op_sel_hi:[1,0,1]
	v_pk_fma_f32 v[50:51], v[34:35], v[50:51], v[104:105] op_sel_hi:[1,0,1]
	v_mov_b32_e32 v104, v53
	v_pk_mul_f32 v[106:107], v[48:49], v[104:105] op_sel_hi:[1,0]
	v_pk_mul_f32 v[104:105], v[46:47], v[104:105] op_sel_hi:[1,0]
	v_pk_fma_f32 v[106:107], v[44:45], v[52:53], v[106:107] op_sel_hi:[1,0,1]
	v_pk_fma_f32 v[52:53], v[42:43], v[52:53], v[104:105] op_sel_hi:[1,0,1]
	v_pk_add_f32 v[102:103], v[102:103], v[106:107]
	v_pk_add_f32 v[50:51], v[50:51], v[52:53]
	v_pk_add_f32 v[32:33], v[32:33], v[102:103]
	v_pk_add_f32 v[30:31], v[30:31], v[50:51]
	ds_read_b128 v[50:53], v56 offset:32784
	v_add_u32_e32 v56, 32, v56
	s_waitcnt lgkmcnt(0)
	v_pk_mul_f32 v[38:39], v[38:39], v[50:51] op_sel:[0,1]
	v_pk_mul_f32 v[40:41], v[40:41], v[50:51] op_sel:[0,1]
	v_pk_fma_f32 v[34:35], v[34:35], v[50:51], v[38:39] op_sel_hi:[1,0,1]
	v_mov_b32_e32 v38, v53
	v_pk_fma_f32 v[36:37], v[36:37], v[50:51], v[40:41] op_sel_hi:[1,0,1]
	v_pk_mul_f32 v[40:41], v[48:49], v[38:39] op_sel_hi:[1,0]
	v_pk_mul_f32 v[38:39], v[46:47], v[38:39] op_sel_hi:[1,0]
	v_pk_fma_f32 v[40:41], v[44:45], v[52:53], v[40:41] op_sel_hi:[1,0,1]
	v_pk_fma_f32 v[38:39], v[42:43], v[52:53], v[38:39] op_sel_hi:[1,0,1]
	v_pk_add_f32 v[36:37], v[36:37], v[40:41]
	v_pk_add_f32 v[34:35], v[34:35], v[38:39]
	v_pk_add_f32 v[36:37], v[74:75], v[36:37]
	v_pk_add_f32 v[34:35], v[76:77], v[34:35]
	v_pk_mov_b32 v[38:39], v[218:219], v[218:219] op_sel:[0,1]
	v_pk_mov_b32 v[40:41], v[220:221], v[220:221] op_sel:[0,1]
	v_pk_mov_b32 v[42:43], v[222:223], v[222:223] op_sel:[0,1]
	v_pk_mov_b32 v[44:45], v[224:225], v[224:225] op_sel:[0,1]
	v_pk_mov_b32 v[74:75], v[226:227], v[226:227] op_sel:[0,1]
	v_pk_mov_b32 v[76:77], v[228:229], v[228:229] op_sel:[0,1]
	v_pk_mov_b32 v[102:103], v[230:231], v[230:231] op_sel:[0,1]
	v_pk_mov_b32 v[104:105], v[232:233], v[232:233] op_sel:[0,1]
	ds_read_b128 v[106:109], v56
	ds_read_b128 v[50:53], v56 offset:16
	s_waitcnt lgkmcnt(1)
	v_pk_mul_f32 v[48:49], v[44:45], v[106:107] op_sel:[0,1]
	v_pk_mul_f32 v[110:111], v[42:43], v[106:107] op_sel:[0,1]
	v_pk_fma_f32 v[48:49], v[40:41], v[106:107], v[48:49] op_sel_hi:[1,0,1]
	v_pk_fma_f32 v[106:107], v[38:39], v[106:107], v[110:111] op_sel_hi:[1,0,1]
	v_mov_b32_e32 v110, v109
	v_pk_mul_f32 v[112:113], v[104:105], v[110:111] op_sel_hi:[1,0]
	v_pk_mul_f32 v[110:111], v[102:103], v[110:111] op_sel_hi:[1,0]
	v_pk_fma_f32 v[112:113], v[76:77], v[108:109], v[112:113] op_sel_hi:[1,0,1]
	v_pk_fma_f32 v[108:109], v[74:75], v[108:109], v[110:111] op_sel_hi:[1,0,1]
	v_pk_add_f32 v[48:49], v[48:49], v[112:113]
	v_pk_add_f32 v[106:107], v[106:107], v[108:109]
	v_pk_add_f32 v[4:5], v[4:5], v[48:49]
	v_pk_add_f32 v[2:3], v[2:3], v[106:107]
	ds_read_b128 v[106:109], v56 offset:4096
	s_waitcnt lgkmcnt(0)
	v_pk_mul_f32 v[48:49], v[44:45], v[106:107] op_sel:[0,1]
	v_pk_mul_f32 v[110:111], v[42:43], v[106:107] op_sel:[0,1]
	v_pk_fma_f32 v[48:49], v[40:41], v[106:107], v[48:49] op_sel_hi:[1,0,1]
	v_pk_fma_f32 v[106:107], v[38:39], v[106:107], v[110:111] op_sel_hi:[1,0,1]
	v_mov_b32_e32 v110, v109
	v_pk_mul_f32 v[112:113], v[104:105], v[110:111] op_sel_hi:[1,0]
	v_pk_mul_f32 v[110:111], v[102:103], v[110:111] op_sel_hi:[1,0]
	v_pk_fma_f32 v[112:113], v[76:77], v[108:109], v[112:113] op_sel_hi:[1,0,1]
	v_pk_fma_f32 v[108:109], v[74:75], v[108:109], v[110:111] op_sel_hi:[1,0,1]
	v_pk_add_f32 v[48:49], v[48:49], v[112:113]
	v_pk_add_f32 v[106:107], v[106:107], v[108:109]
	v_pk_add_f32 v[8:9], v[8:9], v[48:49]
	v_pk_add_f32 v[6:7], v[6:7], v[106:107]
	ds_read_b128 v[106:109], v56 offset:8192
	s_waitcnt lgkmcnt(0)
	v_pk_mul_f32 v[48:49], v[44:45], v[106:107] op_sel:[0,1]
	v_pk_mul_f32 v[110:111], v[42:43], v[106:107] op_sel:[0,1]
	v_pk_fma_f32 v[48:49], v[40:41], v[106:107], v[48:49] op_sel_hi:[1,0,1]
	v_pk_fma_f32 v[106:107], v[38:39], v[106:107], v[110:111] op_sel_hi:[1,0,1]
	v_mov_b32_e32 v110, v109
	v_pk_mul_f32 v[112:113], v[104:105], v[110:111] op_sel_hi:[1,0]
	v_pk_mul_f32 v[110:111], v[102:103], v[110:111] op_sel_hi:[1,0]
	v_pk_fma_f32 v[112:113], v[76:77], v[108:109], v[112:113] op_sel_hi:[1,0,1]
	v_pk_fma_f32 v[108:109], v[74:75], v[108:109], v[110:111] op_sel_hi:[1,0,1]
	v_pk_add_f32 v[48:49], v[48:49], v[112:113]
	v_pk_add_f32 v[106:107], v[106:107], v[108:109]
	v_pk_add_f32 v[12:13], v[12:13], v[48:49]
	v_pk_add_f32 v[10:11], v[10:11], v[106:107]
	ds_read_b128 v[106:109], v56 offset:12288
	s_waitcnt lgkmcnt(0)
	v_pk_mul_f32 v[48:49], v[44:45], v[106:107] op_sel:[0,1]
	v_pk_mul_f32 v[110:111], v[42:43], v[106:107] op_sel:[0,1]
	v_pk_fma_f32 v[48:49], v[40:41], v[106:107], v[48:49] op_sel_hi:[1,0,1]
	v_pk_fma_f32 v[106:107], v[38:39], v[106:107], v[110:111] op_sel_hi:[1,0,1]
	v_mov_b32_e32 v110, v109
	v_pk_mul_f32 v[112:113], v[104:105], v[110:111] op_sel_hi:[1,0]
	v_pk_mul_f32 v[110:111], v[102:103], v[110:111] op_sel_hi:[1,0]
	v_pk_fma_f32 v[112:113], v[76:77], v[108:109], v[112:113] op_sel_hi:[1,0,1]
	v_pk_fma_f32 v[108:109], v[74:75], v[108:109], v[110:111] op_sel_hi:[1,0,1]
	v_pk_add_f32 v[48:49], v[48:49], v[112:113]
	v_pk_add_f32 v[106:107], v[106:107], v[108:109]
	v_pk_add_f32 v[16:17], v[16:17], v[48:49]
	v_pk_add_f32 v[14:15], v[14:15], v[106:107]
	ds_read_b128 v[106:109], v56 offset:16384
	s_waitcnt lgkmcnt(0)
	v_pk_mul_f32 v[48:49], v[44:45], v[106:107] op_sel:[0,1]
	v_pk_mul_f32 v[110:111], v[42:43], v[106:107] op_sel:[0,1]
	v_pk_fma_f32 v[48:49], v[40:41], v[106:107], v[48:49] op_sel_hi:[1,0,1]
	v_pk_fma_f32 v[106:107], v[38:39], v[106:107], v[110:111] op_sel_hi:[1,0,1]
	v_mov_b32_e32 v110, v109
	v_pk_mul_f32 v[112:113], v[104:105], v[110:111] op_sel_hi:[1,0]
	v_pk_mul_f32 v[110:111], v[102:103], v[110:111] op_sel_hi:[1,0]
	v_pk_fma_f32 v[112:113], v[76:77], v[108:109], v[112:113] op_sel_hi:[1,0,1]
	v_pk_fma_f32 v[108:109], v[74:75], v[108:109], v[110:111] op_sel_hi:[1,0,1]
	v_pk_add_f32 v[48:49], v[48:49], v[112:113]
	v_pk_add_f32 v[106:107], v[106:107], v[108:109]
	v_pk_add_f32 v[20:21], v[20:21], v[48:49]
	v_pk_add_f32 v[18:19], v[18:19], v[106:107]
	ds_read_b128 v[106:109], v56 offset:20480
	s_waitcnt lgkmcnt(0)
	v_pk_mul_f32 v[48:49], v[44:45], v[106:107] op_sel:[0,1]
	v_pk_mul_f32 v[110:111], v[42:43], v[106:107] op_sel:[0,1]
	v_pk_fma_f32 v[48:49], v[40:41], v[106:107], v[48:49] op_sel_hi:[1,0,1]
	v_pk_fma_f32 v[106:107], v[38:39], v[106:107], v[110:111] op_sel_hi:[1,0,1]
	v_mov_b32_e32 v110, v109
	v_pk_mul_f32 v[112:113], v[104:105], v[110:111] op_sel_hi:[1,0]
	v_pk_mul_f32 v[110:111], v[102:103], v[110:111] op_sel_hi:[1,0]
	v_pk_fma_f32 v[112:113], v[76:77], v[108:109], v[112:113] op_sel_hi:[1,0,1]
	v_pk_fma_f32 v[108:109], v[74:75], v[108:109], v[110:111] op_sel_hi:[1,0,1]
	v_pk_add_f32 v[48:49], v[48:49], v[112:113]
	v_pk_add_f32 v[106:107], v[106:107], v[108:109]
	v_pk_add_f32 v[24:25], v[24:25], v[48:49]
	v_pk_add_f32 v[22:23], v[22:23], v[106:107]
	ds_read_b128 v[106:109], v56 offset:24576
	s_waitcnt lgkmcnt(0)
	v_pk_mul_f32 v[48:49], v[44:45], v[106:107] op_sel:[0,1]
	v_pk_mul_f32 v[110:111], v[42:43], v[106:107] op_sel:[0,1]
	v_pk_fma_f32 v[48:49], v[40:41], v[106:107], v[48:49] op_sel_hi:[1,0,1]
	v_pk_fma_f32 v[106:107], v[38:39], v[106:107], v[110:111] op_sel_hi:[1,0,1]
	v_mov_b32_e32 v110, v109
	v_pk_mul_f32 v[112:113], v[104:105], v[110:111] op_sel_hi:[1,0]
	v_pk_mul_f32 v[110:111], v[102:103], v[110:111] op_sel_hi:[1,0]
	v_pk_fma_f32 v[112:113], v[76:77], v[108:109], v[112:113] op_sel_hi:[1,0,1]
	v_pk_fma_f32 v[108:109], v[74:75], v[108:109], v[110:111] op_sel_hi:[1,0,1]
	v_pk_add_f32 v[48:49], v[48:49], v[112:113]
	v_pk_add_f32 v[106:107], v[106:107], v[108:109]
	v_pk_add_f32 v[28:29], v[28:29], v[48:49]
	v_pk_add_f32 v[26:27], v[26:27], v[106:107]
	ds_read_b128 v[106:109], v56 offset:28672
	s_waitcnt lgkmcnt(0)
	v_pk_mul_f32 v[48:49], v[44:45], v[106:107] op_sel:[0,1]
	v_pk_mul_f32 v[110:111], v[42:43], v[106:107] op_sel:[0,1]
	v_pk_fma_f32 v[48:49], v[40:41], v[106:107], v[48:49] op_sel_hi:[1,0,1]
	v_pk_fma_f32 v[106:107], v[38:39], v[106:107], v[110:111] op_sel_hi:[1,0,1]
	v_mov_b32_e32 v110, v109
	v_pk_mul_f32 v[112:113], v[104:105], v[110:111] op_sel_hi:[1,0]
	v_pk_mul_f32 v[110:111], v[102:103], v[110:111] op_sel_hi:[1,0]
	v_pk_fma_f32 v[112:113], v[76:77], v[108:109], v[112:113] op_sel_hi:[1,0,1]
	v_pk_fma_f32 v[108:109], v[74:75], v[108:109], v[110:111] op_sel_hi:[1,0,1]
	v_pk_add_f32 v[48:49], v[48:49], v[112:113]
	v_pk_add_f32 v[106:107], v[106:107], v[108:109]
	v_pk_add_f32 v[32:33], v[32:33], v[48:49]
	v_pk_add_f32 v[30:31], v[30:31], v[106:107]
	ds_read_b128 v[106:109], v56 offset:32768
	s_waitcnt lgkmcnt(0)
	v_pk_mul_f32 v[42:43], v[42:43], v[106:107] op_sel:[0,1]
	v_pk_mul_f32 v[44:45], v[44:45], v[106:107] op_sel:[0,1]
	v_pk_fma_f32 v[38:39], v[38:39], v[106:107], v[42:43] op_sel_hi:[1,0,1]
	v_mov_b32_e32 v42, v109
	v_pk_fma_f32 v[40:41], v[40:41], v[106:107], v[44:45] op_sel_hi:[1,0,1]
	v_pk_mul_f32 v[44:45], v[104:105], v[42:43] op_sel_hi:[1,0]
	v_pk_mul_f32 v[42:43], v[102:103], v[42:43] op_sel_hi:[1,0]
	v_pk_fma_f32 v[44:45], v[76:77], v[108:109], v[44:45] op_sel_hi:[1,0,1]
	v_pk_fma_f32 v[42:43], v[74:75], v[108:109], v[42:43] op_sel_hi:[1,0,1]
	v_pk_add_f32 v[40:41], v[40:41], v[44:45]
	v_pk_add_f32 v[38:39], v[38:39], v[42:43]
	v_pk_add_f32 v[74:75], v[36:37], v[40:41]
	v_pk_add_f32 v[76:77], v[34:35], v[38:39]
	v_pk_mov_b32 v[34:35], v[234:235], v[234:235] op_sel:[0,1]
	v_pk_mov_b32 v[36:37], v[236:237], v[236:237] op_sel:[0,1]
	v_pk_mov_b32 v[38:39], v[238:239], v[238:239] op_sel:[0,1]
	v_pk_mov_b32 v[40:41], v[240:241], v[240:241] op_sel:[0,1]
	v_pk_mov_b32 v[42:43], v[242:243], v[242:243] op_sel:[0,1]
	v_pk_mov_b32 v[44:45], v[244:245], v[244:245] op_sel:[0,1]
	v_pk_mov_b32 v[46:47], v[246:247], v[246:247] op_sel:[0,1]
	v_pk_mov_b32 v[48:49], v[248:249], v[248:249] op_sel:[0,1]
	v_pk_mul_f32 v[102:103], v[40:41], v[50:51] op_sel:[0,1]
	v_pk_mul_f32 v[104:105], v[38:39], v[50:51] op_sel:[0,1]
	v_pk_fma_f32 v[102:103], v[36:37], v[50:51], v[102:103] op_sel_hi:[1,0,1]
	v_pk_fma_f32 v[50:51], v[34:35], v[50:51], v[104:105] op_sel_hi:[1,0,1]
	v_mov_b32_e32 v104, v53
	v_pk_mul_f32 v[106:107], v[48:49], v[104:105] op_sel_hi:[1,0]
	v_pk_mul_f32 v[104:105], v[46:47], v[104:105] op_sel_hi:[1,0]
	v_pk_fma_f32 v[106:107], v[44:45], v[52:53], v[106:107] op_sel_hi:[1,0,1]
	v_pk_fma_f32 v[52:53], v[42:43], v[52:53], v[104:105] op_sel_hi:[1,0,1]
	v_pk_add_f32 v[102:103], v[102:103], v[106:107]
	v_pk_add_f32 v[50:51], v[50:51], v[52:53]
	v_pk_add_f32 v[4:5], v[4:5], v[102:103]
	v_pk_add_f32 v[2:3], v[2:3], v[50:51]
	ds_read_b128 v[50:53], v56 offset:4112
	s_waitcnt lgkmcnt(0)
	v_pk_mul_f32 v[102:103], v[40:41], v[50:51] op_sel:[0,1]
	v_pk_mul_f32 v[104:105], v[38:39], v[50:51] op_sel:[0,1]
	v_pk_fma_f32 v[102:103], v[36:37], v[50:51], v[102:103] op_sel_hi:[1,0,1]
	v_pk_fma_f32 v[50:51], v[34:35], v[50:51], v[104:105] op_sel_hi:[1,0,1]
	v_mov_b32_e32 v104, v53
	v_pk_mul_f32 v[106:107], v[48:49], v[104:105] op_sel_hi:[1,0]
	v_pk_mul_f32 v[104:105], v[46:47], v[104:105] op_sel_hi:[1,0]
	v_pk_fma_f32 v[106:107], v[44:45], v[52:53], v[106:107] op_sel_hi:[1,0,1]
	v_pk_fma_f32 v[52:53], v[42:43], v[52:53], v[104:105] op_sel_hi:[1,0,1]
	v_pk_add_f32 v[102:103], v[102:103], v[106:107]
	v_pk_add_f32 v[50:51], v[50:51], v[52:53]
	v_pk_add_f32 v[8:9], v[8:9], v[102:103]
	v_pk_add_f32 v[6:7], v[6:7], v[50:51]
	ds_read_b128 v[50:53], v56 offset:8208
	s_waitcnt lgkmcnt(0)
	v_pk_mul_f32 v[102:103], v[40:41], v[50:51] op_sel:[0,1]
	v_pk_mul_f32 v[104:105], v[38:39], v[50:51] op_sel:[0,1]
	v_pk_fma_f32 v[102:103], v[36:37], v[50:51], v[102:103] op_sel_hi:[1,0,1]
	v_pk_fma_f32 v[50:51], v[34:35], v[50:51], v[104:105] op_sel_hi:[1,0,1]
	v_mov_b32_e32 v104, v53
	v_pk_mul_f32 v[106:107], v[48:49], v[104:105] op_sel_hi:[1,0]
	v_pk_mul_f32 v[104:105], v[46:47], v[104:105] op_sel_hi:[1,0]
	v_pk_fma_f32 v[106:107], v[44:45], v[52:53], v[106:107] op_sel_hi:[1,0,1]
	v_pk_fma_f32 v[52:53], v[42:43], v[52:53], v[104:105] op_sel_hi:[1,0,1]
	v_pk_add_f32 v[102:103], v[102:103], v[106:107]
	v_pk_add_f32 v[50:51], v[50:51], v[52:53]
	v_pk_add_f32 v[12:13], v[12:13], v[102:103]
	v_pk_add_f32 v[10:11], v[10:11], v[50:51]
	ds_read_b128 v[50:53], v56 offset:12304
	s_waitcnt lgkmcnt(0)
	v_pk_mul_f32 v[102:103], v[40:41], v[50:51] op_sel:[0,1]
	v_pk_mul_f32 v[104:105], v[38:39], v[50:51] op_sel:[0,1]
	v_pk_fma_f32 v[102:103], v[36:37], v[50:51], v[102:103] op_sel_hi:[1,0,1]
	v_pk_fma_f32 v[50:51], v[34:35], v[50:51], v[104:105] op_sel_hi:[1,0,1]
	v_mov_b32_e32 v104, v53
	v_pk_mul_f32 v[106:107], v[48:49], v[104:105] op_sel_hi:[1,0]
	v_pk_mul_f32 v[104:105], v[46:47], v[104:105] op_sel_hi:[1,0]
	v_pk_fma_f32 v[106:107], v[44:45], v[52:53], v[106:107] op_sel_hi:[1,0,1]
	v_pk_fma_f32 v[52:53], v[42:43], v[52:53], v[104:105] op_sel_hi:[1,0,1]
	v_pk_add_f32 v[102:103], v[102:103], v[106:107]
	v_pk_add_f32 v[50:51], v[50:51], v[52:53]
	v_pk_add_f32 v[16:17], v[16:17], v[102:103]
	v_pk_add_f32 v[14:15], v[14:15], v[50:51]
	ds_read_b128 v[50:53], v56 offset:16400
	s_waitcnt lgkmcnt(0)
	v_pk_mul_f32 v[102:103], v[40:41], v[50:51] op_sel:[0,1]
	v_pk_mul_f32 v[104:105], v[38:39], v[50:51] op_sel:[0,1]
	v_pk_fma_f32 v[102:103], v[36:37], v[50:51], v[102:103] op_sel_hi:[1,0,1]
	v_pk_fma_f32 v[50:51], v[34:35], v[50:51], v[104:105] op_sel_hi:[1,0,1]
	v_mov_b32_e32 v104, v53
	v_pk_mul_f32 v[106:107], v[48:49], v[104:105] op_sel_hi:[1,0]
	v_pk_mul_f32 v[104:105], v[46:47], v[104:105] op_sel_hi:[1,0]
	v_pk_fma_f32 v[106:107], v[44:45], v[52:53], v[106:107] op_sel_hi:[1,0,1]
	v_pk_fma_f32 v[52:53], v[42:43], v[52:53], v[104:105] op_sel_hi:[1,0,1]
	v_pk_add_f32 v[102:103], v[102:103], v[106:107]
	v_pk_add_f32 v[50:51], v[50:51], v[52:53]
	v_pk_add_f32 v[20:21], v[20:21], v[102:103]
	v_pk_add_f32 v[18:19], v[18:19], v[50:51]
	ds_read_b128 v[50:53], v56 offset:20496
	s_waitcnt lgkmcnt(0)
	v_pk_mul_f32 v[102:103], v[40:41], v[50:51] op_sel:[0,1]
	v_pk_mul_f32 v[104:105], v[38:39], v[50:51] op_sel:[0,1]
	v_pk_fma_f32 v[102:103], v[36:37], v[50:51], v[102:103] op_sel_hi:[1,0,1]
	v_pk_fma_f32 v[50:51], v[34:35], v[50:51], v[104:105] op_sel_hi:[1,0,1]
	v_mov_b32_e32 v104, v53
	v_pk_mul_f32 v[106:107], v[48:49], v[104:105] op_sel_hi:[1,0]
	v_pk_mul_f32 v[104:105], v[46:47], v[104:105] op_sel_hi:[1,0]
	v_pk_fma_f32 v[106:107], v[44:45], v[52:53], v[106:107] op_sel_hi:[1,0,1]
	v_pk_fma_f32 v[52:53], v[42:43], v[52:53], v[104:105] op_sel_hi:[1,0,1]
	v_pk_add_f32 v[102:103], v[102:103], v[106:107]
	v_pk_add_f32 v[50:51], v[50:51], v[52:53]
	v_pk_add_f32 v[24:25], v[24:25], v[102:103]
	v_pk_add_f32 v[22:23], v[22:23], v[50:51]
	ds_read_b128 v[50:53], v56 offset:24592
	s_waitcnt lgkmcnt(0)
	v_pk_mul_f32 v[102:103], v[40:41], v[50:51] op_sel:[0,1]
	v_pk_mul_f32 v[104:105], v[38:39], v[50:51] op_sel:[0,1]
	v_pk_fma_f32 v[102:103], v[36:37], v[50:51], v[102:103] op_sel_hi:[1,0,1]
	v_pk_fma_f32 v[50:51], v[34:35], v[50:51], v[104:105] op_sel_hi:[1,0,1]
	v_mov_b32_e32 v104, v53
	v_pk_mul_f32 v[106:107], v[48:49], v[104:105] op_sel_hi:[1,0]
	v_pk_mul_f32 v[104:105], v[46:47], v[104:105] op_sel_hi:[1,0]
	v_pk_fma_f32 v[106:107], v[44:45], v[52:53], v[106:107] op_sel_hi:[1,0,1]
	v_pk_fma_f32 v[52:53], v[42:43], v[52:53], v[104:105] op_sel_hi:[1,0,1]
	v_pk_add_f32 v[102:103], v[102:103], v[106:107]
	v_pk_add_f32 v[50:51], v[50:51], v[52:53]
	v_pk_add_f32 v[28:29], v[28:29], v[102:103]
	v_pk_add_f32 v[26:27], v[26:27], v[50:51]
	ds_read_b128 v[50:53], v56 offset:28688
	s_waitcnt lgkmcnt(0)
	v_pk_mul_f32 v[102:103], v[40:41], v[50:51] op_sel:[0,1]
	v_pk_mul_f32 v[104:105], v[38:39], v[50:51] op_sel:[0,1]
	v_pk_fma_f32 v[102:103], v[36:37], v[50:51], v[102:103] op_sel_hi:[1,0,1]
	v_pk_fma_f32 v[50:51], v[34:35], v[50:51], v[104:105] op_sel_hi:[1,0,1]
	v_mov_b32_e32 v104, v53
	v_pk_mul_f32 v[106:107], v[48:49], v[104:105] op_sel_hi:[1,0]
	v_pk_mul_f32 v[104:105], v[46:47], v[104:105] op_sel_hi:[1,0]
	v_pk_fma_f32 v[106:107], v[44:45], v[52:53], v[106:107] op_sel_hi:[1,0,1]
	v_pk_fma_f32 v[52:53], v[42:43], v[52:53], v[104:105] op_sel_hi:[1,0,1]
	v_pk_add_f32 v[102:103], v[102:103], v[106:107]
	v_pk_add_f32 v[50:51], v[50:51], v[52:53]
	v_pk_add_f32 v[32:33], v[32:33], v[102:103]
	v_pk_add_f32 v[30:31], v[30:31], v[50:51]
	ds_read_b128 v[50:53], v56 offset:32784
	v_add_u32_e32 v56, 32, v56
	s_waitcnt lgkmcnt(0)
	v_pk_mul_f32 v[38:39], v[38:39], v[50:51] op_sel:[0,1]
	v_pk_mul_f32 v[40:41], v[40:41], v[50:51] op_sel:[0,1]
	v_pk_fma_f32 v[34:35], v[34:35], v[50:51], v[38:39] op_sel_hi:[1,0,1]
	v_mov_b32_e32 v38, v53
	v_pk_fma_f32 v[36:37], v[36:37], v[50:51], v[40:41] op_sel_hi:[1,0,1]
	v_pk_mul_f32 v[40:41], v[48:49], v[38:39] op_sel_hi:[1,0]
	v_pk_mul_f32 v[38:39], v[46:47], v[38:39] op_sel_hi:[1,0]
	v_pk_fma_f32 v[40:41], v[44:45], v[52:53], v[40:41] op_sel_hi:[1,0,1]
	v_pk_fma_f32 v[38:39], v[42:43], v[52:53], v[38:39] op_sel_hi:[1,0,1]
	v_pk_add_f32 v[36:37], v[36:37], v[40:41]
	v_pk_add_f32 v[34:35], v[34:35], v[38:39]
	v_pk_add_f32 v[36:37], v[74:75], v[36:37]
	v_pk_add_f32 v[34:35], v[76:77], v[34:35]
	v_add_co_u32_e32 v250, vcc, 0x120000, v72
	s_nop 1
	v_addc_co_u32_e32 v251, vcc, 0, v73, vcc
	global_load_dwordx4 v[186:189], v[250:251], off
	v_add_co_u32_e32 v252, vcc, 0x126000, v72
	s_nop 1
	v_addc_co_u32_e32 v253, vcc, 0, v73, vcc
	global_load_dwordx4 v[190:193], v[252:253], off
	v_add_co_u32_e32 v250, vcc, 0x12c000, v72
	s_nop 1
	v_addc_co_u32_e32 v251, vcc, 0, v73, vcc
	global_load_dwordx4 v[194:197], v[250:251], off
	v_add_co_u32_e32 v252, vcc, 0x132000, v72
	s_nop 1
	v_addc_co_u32_e32 v253, vcc, 0, v73, vcc
	global_load_dwordx4 v[198:201], v[252:253], off
	v_add_co_u32_e32 v250, vcc, 0x138000, v72
	s_nop 1
	v_addc_co_u32_e32 v251, vcc, 0, v73, vcc
	global_load_dwordx4 v[202:205], v[250:251], off
	v_add_co_u32_e32 v252, vcc, 0x13e000, v72
	s_nop 1
	v_addc_co_u32_e32 v253, vcc, 0, v73, vcc
	global_load_dwordx4 v[206:209], v[252:253], off
	v_add_co_u32_e32 v250, vcc, 0x144000, v72
	s_nop 1
	v_addc_co_u32_e32 v251, vcc, 0, v73, vcc
	global_load_dwordx4 v[210:213], v[250:251], off
	v_add_co_u32_e32 v252, vcc, 0x14a000, v72
	s_nop 1
	v_addc_co_u32_e32 v253, vcc, 0, v73, vcc
	global_load_dwordx4 v[214:217], v[252:253], off
	v_add_co_u32_e32 v250, vcc, 0x150000, v72
	s_nop 1
	v_addc_co_u32_e32 v251, vcc, 0, v73, vcc
	global_load_dwordx4 v[218:221], v[250:251], off
	v_add_co_u32_e32 v252, vcc, 0x156000, v72
	s_nop 1
	v_addc_co_u32_e32 v253, vcc, 0, v73, vcc
	global_load_dwordx4 v[222:225], v[252:253], off
	v_add_co_u32_e32 v250, vcc, 0x15c000, v72
	s_nop 1
	v_addc_co_u32_e32 v251, vcc, 0, v73, vcc
	global_load_dwordx4 v[226:229], v[250:251], off
	v_add_co_u32_e32 v252, vcc, 0x162000, v72
	s_nop 1
	v_addc_co_u32_e32 v253, vcc, 0, v73, vcc
	global_load_dwordx4 v[230:233], v[252:253], off
	v_add_co_u32_e32 v250, vcc, 0x168000, v72
	s_nop 1
	v_addc_co_u32_e32 v251, vcc, 0, v73, vcc
	global_load_dwordx4 v[234:237], v[250:251], off
	v_add_co_u32_e32 v252, vcc, 0x16e000, v72
	s_nop 1
	v_addc_co_u32_e32 v253, vcc, 0, v73, vcc
	global_load_dwordx4 v[238:241], v[252:253], off
	v_add_co_u32_e32 v250, vcc, 0x174000, v72
	s_nop 1
	v_addc_co_u32_e32 v251, vcc, 0, v73, vcc
	global_load_dwordx4 v[242:245], v[250:251], off
	v_add_co_u32_e32 v252, vcc, 0x17a000, v72
	s_nop 1
	v_addc_co_u32_e32 v253, vcc, 0, v73, vcc
	global_load_dwordx4 v[246:249], v[252:253], off
	s_waitcnt vmcnt(16)
	v_pk_mov_b32 v[38:39], v[122:123], v[122:123] op_sel:[0,1]
	v_pk_mov_b32 v[40:41], v[124:125], v[124:125] op_sel:[0,1]
	v_pk_mov_b32 v[42:43], v[126:127], v[126:127] op_sel:[0,1]
	v_pk_mov_b32 v[44:45], v[128:129], v[128:129] op_sel:[0,1]
	v_pk_mov_b32 v[74:75], v[130:131], v[130:131] op_sel:[0,1]
	v_pk_mov_b32 v[76:77], v[132:133], v[132:133] op_sel:[0,1]
	v_pk_mov_b32 v[102:103], v[134:135], v[134:135] op_sel:[0,1]
	v_pk_mov_b32 v[104:105], v[136:137], v[136:137] op_sel:[0,1]
	ds_read_b128 v[106:109], v56
	ds_read_b128 v[50:53], v56 offset:16
	s_waitcnt lgkmcnt(1)
	v_pk_mul_f32 v[48:49], v[44:45], v[106:107] op_sel:[0,1]
	v_pk_mul_f32 v[110:111], v[42:43], v[106:107] op_sel:[0,1]
	v_pk_fma_f32 v[48:49], v[40:41], v[106:107], v[48:49] op_sel_hi:[1,0,1]
	v_pk_fma_f32 v[106:107], v[38:39], v[106:107], v[110:111] op_sel_hi:[1,0,1]
	v_mov_b32_e32 v110, v109
	v_pk_mul_f32 v[112:113], v[104:105], v[110:111] op_sel_hi:[1,0]
	v_pk_mul_f32 v[110:111], v[102:103], v[110:111] op_sel_hi:[1,0]
	v_pk_fma_f32 v[112:113], v[76:77], v[108:109], v[112:113] op_sel_hi:[1,0,1]
	v_pk_fma_f32 v[108:109], v[74:75], v[108:109], v[110:111] op_sel_hi:[1,0,1]
	v_pk_add_f32 v[48:49], v[48:49], v[112:113]
	v_pk_add_f32 v[106:107], v[106:107], v[108:109]
	v_pk_add_f32 v[4:5], v[4:5], v[48:49]
	v_pk_add_f32 v[2:3], v[2:3], v[106:107]
	ds_read_b128 v[106:109], v56 offset:4096
	s_waitcnt lgkmcnt(0)
	v_pk_mul_f32 v[48:49], v[44:45], v[106:107] op_sel:[0,1]
	v_pk_mul_f32 v[110:111], v[42:43], v[106:107] op_sel:[0,1]
	v_pk_fma_f32 v[48:49], v[40:41], v[106:107], v[48:49] op_sel_hi:[1,0,1]
	v_pk_fma_f32 v[106:107], v[38:39], v[106:107], v[110:111] op_sel_hi:[1,0,1]
	v_mov_b32_e32 v110, v109
	v_pk_mul_f32 v[112:113], v[104:105], v[110:111] op_sel_hi:[1,0]
	v_pk_mul_f32 v[110:111], v[102:103], v[110:111] op_sel_hi:[1,0]
	v_pk_fma_f32 v[112:113], v[76:77], v[108:109], v[112:113] op_sel_hi:[1,0,1]
	v_pk_fma_f32 v[108:109], v[74:75], v[108:109], v[110:111] op_sel_hi:[1,0,1]
	v_pk_add_f32 v[48:49], v[48:49], v[112:113]
	v_pk_add_f32 v[106:107], v[106:107], v[108:109]
	v_pk_add_f32 v[8:9], v[8:9], v[48:49]
	v_pk_add_f32 v[6:7], v[6:7], v[106:107]
	ds_read_b128 v[106:109], v56 offset:8192
	s_waitcnt lgkmcnt(0)
	v_pk_mul_f32 v[48:49], v[44:45], v[106:107] op_sel:[0,1]
	v_pk_mul_f32 v[110:111], v[42:43], v[106:107] op_sel:[0,1]
	v_pk_fma_f32 v[48:49], v[40:41], v[106:107], v[48:49] op_sel_hi:[1,0,1]
	v_pk_fma_f32 v[106:107], v[38:39], v[106:107], v[110:111] op_sel_hi:[1,0,1]
	v_mov_b32_e32 v110, v109
	v_pk_mul_f32 v[112:113], v[104:105], v[110:111] op_sel_hi:[1,0]
	v_pk_mul_f32 v[110:111], v[102:103], v[110:111] op_sel_hi:[1,0]
	v_pk_fma_f32 v[112:113], v[76:77], v[108:109], v[112:113] op_sel_hi:[1,0,1]
	v_pk_fma_f32 v[108:109], v[74:75], v[108:109], v[110:111] op_sel_hi:[1,0,1]
	v_pk_add_f32 v[48:49], v[48:49], v[112:113]
	v_pk_add_f32 v[106:107], v[106:107], v[108:109]
	v_pk_add_f32 v[12:13], v[12:13], v[48:49]
	v_pk_add_f32 v[10:11], v[10:11], v[106:107]
	ds_read_b128 v[106:109], v56 offset:12288
	s_waitcnt lgkmcnt(0)
	v_pk_mul_f32 v[48:49], v[44:45], v[106:107] op_sel:[0,1]
	v_pk_mul_f32 v[110:111], v[42:43], v[106:107] op_sel:[0,1]
	v_pk_fma_f32 v[48:49], v[40:41], v[106:107], v[48:49] op_sel_hi:[1,0,1]
	v_pk_fma_f32 v[106:107], v[38:39], v[106:107], v[110:111] op_sel_hi:[1,0,1]
	v_mov_b32_e32 v110, v109
	v_pk_mul_f32 v[112:113], v[104:105], v[110:111] op_sel_hi:[1,0]
	v_pk_mul_f32 v[110:111], v[102:103], v[110:111] op_sel_hi:[1,0]
	v_pk_fma_f32 v[112:113], v[76:77], v[108:109], v[112:113] op_sel_hi:[1,0,1]
	v_pk_fma_f32 v[108:109], v[74:75], v[108:109], v[110:111] op_sel_hi:[1,0,1]
	v_pk_add_f32 v[48:49], v[48:49], v[112:113]
	v_pk_add_f32 v[106:107], v[106:107], v[108:109]
	v_pk_add_f32 v[16:17], v[16:17], v[48:49]
	v_pk_add_f32 v[14:15], v[14:15], v[106:107]
	ds_read_b128 v[106:109], v56 offset:16384
	s_waitcnt lgkmcnt(0)
	v_pk_mul_f32 v[48:49], v[44:45], v[106:107] op_sel:[0,1]
	v_pk_mul_f32 v[110:111], v[42:43], v[106:107] op_sel:[0,1]
	v_pk_fma_f32 v[48:49], v[40:41], v[106:107], v[48:49] op_sel_hi:[1,0,1]
	v_pk_fma_f32 v[106:107], v[38:39], v[106:107], v[110:111] op_sel_hi:[1,0,1]
	v_mov_b32_e32 v110, v109
	v_pk_mul_f32 v[112:113], v[104:105], v[110:111] op_sel_hi:[1,0]
	v_pk_mul_f32 v[110:111], v[102:103], v[110:111] op_sel_hi:[1,0]
	v_pk_fma_f32 v[112:113], v[76:77], v[108:109], v[112:113] op_sel_hi:[1,0,1]
	v_pk_fma_f32 v[108:109], v[74:75], v[108:109], v[110:111] op_sel_hi:[1,0,1]
	v_pk_add_f32 v[48:49], v[48:49], v[112:113]
	v_pk_add_f32 v[106:107], v[106:107], v[108:109]
	v_pk_add_f32 v[20:21], v[20:21], v[48:49]
	v_pk_add_f32 v[18:19], v[18:19], v[106:107]
	ds_read_b128 v[106:109], v56 offset:20480
	s_waitcnt lgkmcnt(0)
	v_pk_mul_f32 v[48:49], v[44:45], v[106:107] op_sel:[0,1]
	v_pk_mul_f32 v[110:111], v[42:43], v[106:107] op_sel:[0,1]
	v_pk_fma_f32 v[48:49], v[40:41], v[106:107], v[48:49] op_sel_hi:[1,0,1]
	v_pk_fma_f32 v[106:107], v[38:39], v[106:107], v[110:111] op_sel_hi:[1,0,1]
	v_mov_b32_e32 v110, v109
	v_pk_mul_f32 v[112:113], v[104:105], v[110:111] op_sel_hi:[1,0]
	v_pk_mul_f32 v[110:111], v[102:103], v[110:111] op_sel_hi:[1,0]
	v_pk_fma_f32 v[112:113], v[76:77], v[108:109], v[112:113] op_sel_hi:[1,0,1]
	v_pk_fma_f32 v[108:109], v[74:75], v[108:109], v[110:111] op_sel_hi:[1,0,1]
	v_pk_add_f32 v[48:49], v[48:49], v[112:113]
	v_pk_add_f32 v[106:107], v[106:107], v[108:109]
	v_pk_add_f32 v[24:25], v[24:25], v[48:49]
	v_pk_add_f32 v[22:23], v[22:23], v[106:107]
	ds_read_b128 v[106:109], v56 offset:24576
	s_waitcnt lgkmcnt(0)
	v_pk_mul_f32 v[48:49], v[44:45], v[106:107] op_sel:[0,1]
	v_pk_mul_f32 v[110:111], v[42:43], v[106:107] op_sel:[0,1]
	v_pk_fma_f32 v[48:49], v[40:41], v[106:107], v[48:49] op_sel_hi:[1,0,1]
	v_pk_fma_f32 v[106:107], v[38:39], v[106:107], v[110:111] op_sel_hi:[1,0,1]
	v_mov_b32_e32 v110, v109
	v_pk_mul_f32 v[112:113], v[104:105], v[110:111] op_sel_hi:[1,0]
	v_pk_mul_f32 v[110:111], v[102:103], v[110:111] op_sel_hi:[1,0]
	v_pk_fma_f32 v[112:113], v[76:77], v[108:109], v[112:113] op_sel_hi:[1,0,1]
	v_pk_fma_f32 v[108:109], v[74:75], v[108:109], v[110:111] op_sel_hi:[1,0,1]
	v_pk_add_f32 v[48:49], v[48:49], v[112:113]
	v_pk_add_f32 v[106:107], v[106:107], v[108:109]
	v_pk_add_f32 v[28:29], v[28:29], v[48:49]
	v_pk_add_f32 v[26:27], v[26:27], v[106:107]
	ds_read_b128 v[106:109], v56 offset:28672
	s_waitcnt lgkmcnt(0)
	v_pk_mul_f32 v[48:49], v[44:45], v[106:107] op_sel:[0,1]
	v_pk_mul_f32 v[110:111], v[42:43], v[106:107] op_sel:[0,1]
	v_pk_fma_f32 v[48:49], v[40:41], v[106:107], v[48:49] op_sel_hi:[1,0,1]
	v_pk_fma_f32 v[106:107], v[38:39], v[106:107], v[110:111] op_sel_hi:[1,0,1]
	v_mov_b32_e32 v110, v109
	v_pk_mul_f32 v[112:113], v[104:105], v[110:111] op_sel_hi:[1,0]
	v_pk_mul_f32 v[110:111], v[102:103], v[110:111] op_sel_hi:[1,0]
	v_pk_fma_f32 v[112:113], v[76:77], v[108:109], v[112:113] op_sel_hi:[1,0,1]
	v_pk_fma_f32 v[108:109], v[74:75], v[108:109], v[110:111] op_sel_hi:[1,0,1]
	v_pk_add_f32 v[48:49], v[48:49], v[112:113]
	v_pk_add_f32 v[106:107], v[106:107], v[108:109]
	v_pk_add_f32 v[32:33], v[32:33], v[48:49]
	v_pk_add_f32 v[30:31], v[30:31], v[106:107]
	ds_read_b128 v[106:109], v56 offset:32768
	s_waitcnt lgkmcnt(0)
	v_pk_mul_f32 v[42:43], v[42:43], v[106:107] op_sel:[0,1]
	v_pk_mul_f32 v[44:45], v[44:45], v[106:107] op_sel:[0,1]
	v_pk_fma_f32 v[38:39], v[38:39], v[106:107], v[42:43] op_sel_hi:[1,0,1]
	v_mov_b32_e32 v42, v109
	v_pk_fma_f32 v[40:41], v[40:41], v[106:107], v[44:45] op_sel_hi:[1,0,1]
	v_pk_mul_f32 v[44:45], v[104:105], v[42:43] op_sel_hi:[1,0]
	v_pk_mul_f32 v[42:43], v[102:103], v[42:43] op_sel_hi:[1,0]
	v_pk_fma_f32 v[44:45], v[76:77], v[108:109], v[44:45] op_sel_hi:[1,0,1]
	v_pk_fma_f32 v[42:43], v[74:75], v[108:109], v[42:43] op_sel_hi:[1,0,1]
	v_pk_add_f32 v[40:41], v[40:41], v[44:45]
	v_pk_add_f32 v[38:39], v[38:39], v[42:43]
	v_pk_add_f32 v[74:75], v[36:37], v[40:41]
	v_pk_add_f32 v[76:77], v[34:35], v[38:39]
	v_pk_mov_b32 v[34:35], v[138:139], v[138:139] op_sel:[0,1]
	v_pk_mov_b32 v[36:37], v[140:141], v[140:141] op_sel:[0,1]
	v_pk_mov_b32 v[38:39], v[142:143], v[142:143] op_sel:[0,1]
	v_pk_mov_b32 v[40:41], v[144:145], v[144:145] op_sel:[0,1]
	v_pk_mov_b32 v[42:43], v[146:147], v[146:147] op_sel:[0,1]
	v_pk_mov_b32 v[44:45], v[148:149], v[148:149] op_sel:[0,1]
	v_pk_mov_b32 v[46:47], v[150:151], v[150:151] op_sel:[0,1]
	v_pk_mov_b32 v[48:49], v[152:153], v[152:153] op_sel:[0,1]
	v_pk_mul_f32 v[102:103], v[40:41], v[50:51] op_sel:[0,1]
	v_pk_mul_f32 v[104:105], v[38:39], v[50:51] op_sel:[0,1]
	v_pk_fma_f32 v[102:103], v[36:37], v[50:51], v[102:103] op_sel_hi:[1,0,1]
	v_pk_fma_f32 v[50:51], v[34:35], v[50:51], v[104:105] op_sel_hi:[1,0,1]
	v_mov_b32_e32 v104, v53
	v_pk_mul_f32 v[106:107], v[48:49], v[104:105] op_sel_hi:[1,0]
	v_pk_mul_f32 v[104:105], v[46:47], v[104:105] op_sel_hi:[1,0]
	v_pk_fma_f32 v[106:107], v[44:45], v[52:53], v[106:107] op_sel_hi:[1,0,1]
	v_pk_fma_f32 v[52:53], v[42:43], v[52:53], v[104:105] op_sel_hi:[1,0,1]
	v_pk_add_f32 v[102:103], v[102:103], v[106:107]
	v_pk_add_f32 v[50:51], v[50:51], v[52:53]
	v_pk_add_f32 v[4:5], v[4:5], v[102:103]
	v_pk_add_f32 v[2:3], v[2:3], v[50:51]
	ds_read_b128 v[50:53], v56 offset:4112
	s_waitcnt lgkmcnt(0)
	v_pk_mul_f32 v[102:103], v[40:41], v[50:51] op_sel:[0,1]
	v_pk_mul_f32 v[104:105], v[38:39], v[50:51] op_sel:[0,1]
	v_pk_fma_f32 v[102:103], v[36:37], v[50:51], v[102:103] op_sel_hi:[1,0,1]
	v_pk_fma_f32 v[50:51], v[34:35], v[50:51], v[104:105] op_sel_hi:[1,0,1]
	v_mov_b32_e32 v104, v53
	v_pk_mul_f32 v[106:107], v[48:49], v[104:105] op_sel_hi:[1,0]
	v_pk_mul_f32 v[104:105], v[46:47], v[104:105] op_sel_hi:[1,0]
	v_pk_fma_f32 v[106:107], v[44:45], v[52:53], v[106:107] op_sel_hi:[1,0,1]
	v_pk_fma_f32 v[52:53], v[42:43], v[52:53], v[104:105] op_sel_hi:[1,0,1]
	v_pk_add_f32 v[102:103], v[102:103], v[106:107]
	v_pk_add_f32 v[50:51], v[50:51], v[52:53]
	v_pk_add_f32 v[8:9], v[8:9], v[102:103]
	v_pk_add_f32 v[6:7], v[6:7], v[50:51]
	ds_read_b128 v[50:53], v56 offset:8208
	s_waitcnt lgkmcnt(0)
	v_pk_mul_f32 v[102:103], v[40:41], v[50:51] op_sel:[0,1]
	v_pk_mul_f32 v[104:105], v[38:39], v[50:51] op_sel:[0,1]
	v_pk_fma_f32 v[102:103], v[36:37], v[50:51], v[102:103] op_sel_hi:[1,0,1]
	v_pk_fma_f32 v[50:51], v[34:35], v[50:51], v[104:105] op_sel_hi:[1,0,1]
	v_mov_b32_e32 v104, v53
	v_pk_mul_f32 v[106:107], v[48:49], v[104:105] op_sel_hi:[1,0]
	v_pk_mul_f32 v[104:105], v[46:47], v[104:105] op_sel_hi:[1,0]
	v_pk_fma_f32 v[106:107], v[44:45], v[52:53], v[106:107] op_sel_hi:[1,0,1]
	v_pk_fma_f32 v[52:53], v[42:43], v[52:53], v[104:105] op_sel_hi:[1,0,1]
	v_pk_add_f32 v[102:103], v[102:103], v[106:107]
	v_pk_add_f32 v[50:51], v[50:51], v[52:53]
	v_pk_add_f32 v[12:13], v[12:13], v[102:103]
	v_pk_add_f32 v[10:11], v[10:11], v[50:51]
	ds_read_b128 v[50:53], v56 offset:12304
	s_waitcnt lgkmcnt(0)
	v_pk_mul_f32 v[102:103], v[40:41], v[50:51] op_sel:[0,1]
	v_pk_mul_f32 v[104:105], v[38:39], v[50:51] op_sel:[0,1]
	v_pk_fma_f32 v[102:103], v[36:37], v[50:51], v[102:103] op_sel_hi:[1,0,1]
	v_pk_fma_f32 v[50:51], v[34:35], v[50:51], v[104:105] op_sel_hi:[1,0,1]
	v_mov_b32_e32 v104, v53
	v_pk_mul_f32 v[106:107], v[48:49], v[104:105] op_sel_hi:[1,0]
	v_pk_mul_f32 v[104:105], v[46:47], v[104:105] op_sel_hi:[1,0]
	v_pk_fma_f32 v[106:107], v[44:45], v[52:53], v[106:107] op_sel_hi:[1,0,1]
	v_pk_fma_f32 v[52:53], v[42:43], v[52:53], v[104:105] op_sel_hi:[1,0,1]
	v_pk_add_f32 v[102:103], v[102:103], v[106:107]
	v_pk_add_f32 v[50:51], v[50:51], v[52:53]
	v_pk_add_f32 v[16:17], v[16:17], v[102:103]
	v_pk_add_f32 v[14:15], v[14:15], v[50:51]
	ds_read_b128 v[50:53], v56 offset:16400
	s_waitcnt lgkmcnt(0)
	v_pk_mul_f32 v[102:103], v[40:41], v[50:51] op_sel:[0,1]
	v_pk_mul_f32 v[104:105], v[38:39], v[50:51] op_sel:[0,1]
	v_pk_fma_f32 v[102:103], v[36:37], v[50:51], v[102:103] op_sel_hi:[1,0,1]
	v_pk_fma_f32 v[50:51], v[34:35], v[50:51], v[104:105] op_sel_hi:[1,0,1]
	v_mov_b32_e32 v104, v53
	v_pk_mul_f32 v[106:107], v[48:49], v[104:105] op_sel_hi:[1,0]
	v_pk_mul_f32 v[104:105], v[46:47], v[104:105] op_sel_hi:[1,0]
	v_pk_fma_f32 v[106:107], v[44:45], v[52:53], v[106:107] op_sel_hi:[1,0,1]
	v_pk_fma_f32 v[52:53], v[42:43], v[52:53], v[104:105] op_sel_hi:[1,0,1]
	v_pk_add_f32 v[102:103], v[102:103], v[106:107]
	v_pk_add_f32 v[50:51], v[50:51], v[52:53]
	v_pk_add_f32 v[20:21], v[20:21], v[102:103]
	v_pk_add_f32 v[18:19], v[18:19], v[50:51]
	ds_read_b128 v[50:53], v56 offset:20496
	s_waitcnt lgkmcnt(0)
	v_pk_mul_f32 v[102:103], v[40:41], v[50:51] op_sel:[0,1]
	v_pk_mul_f32 v[104:105], v[38:39], v[50:51] op_sel:[0,1]
	v_pk_fma_f32 v[102:103], v[36:37], v[50:51], v[102:103] op_sel_hi:[1,0,1]
	v_pk_fma_f32 v[50:51], v[34:35], v[50:51], v[104:105] op_sel_hi:[1,0,1]
	v_mov_b32_e32 v104, v53
	v_pk_mul_f32 v[106:107], v[48:49], v[104:105] op_sel_hi:[1,0]
	v_pk_mul_f32 v[104:105], v[46:47], v[104:105] op_sel_hi:[1,0]
	v_pk_fma_f32 v[106:107], v[44:45], v[52:53], v[106:107] op_sel_hi:[1,0,1]
	v_pk_fma_f32 v[52:53], v[42:43], v[52:53], v[104:105] op_sel_hi:[1,0,1]
	v_pk_add_f32 v[102:103], v[102:103], v[106:107]
	v_pk_add_f32 v[50:51], v[50:51], v[52:53]
	v_pk_add_f32 v[24:25], v[24:25], v[102:103]
	v_pk_add_f32 v[22:23], v[22:23], v[50:51]
	ds_read_b128 v[50:53], v56 offset:24592
	s_waitcnt lgkmcnt(0)
	v_pk_mul_f32 v[102:103], v[40:41], v[50:51] op_sel:[0,1]
	v_pk_mul_f32 v[104:105], v[38:39], v[50:51] op_sel:[0,1]
	v_pk_fma_f32 v[102:103], v[36:37], v[50:51], v[102:103] op_sel_hi:[1,0,1]
	v_pk_fma_f32 v[50:51], v[34:35], v[50:51], v[104:105] op_sel_hi:[1,0,1]
	v_mov_b32_e32 v104, v53
	v_pk_mul_f32 v[106:107], v[48:49], v[104:105] op_sel_hi:[1,0]
	v_pk_mul_f32 v[104:105], v[46:47], v[104:105] op_sel_hi:[1,0]
	v_pk_fma_f32 v[106:107], v[44:45], v[52:53], v[106:107] op_sel_hi:[1,0,1]
	v_pk_fma_f32 v[52:53], v[42:43], v[52:53], v[104:105] op_sel_hi:[1,0,1]
	v_pk_add_f32 v[102:103], v[102:103], v[106:107]
	v_pk_add_f32 v[50:51], v[50:51], v[52:53]
	v_pk_add_f32 v[28:29], v[28:29], v[102:103]
	v_pk_add_f32 v[26:27], v[26:27], v[50:51]
	ds_read_b128 v[50:53], v56 offset:28688
	s_waitcnt lgkmcnt(0)
	v_pk_mul_f32 v[102:103], v[40:41], v[50:51] op_sel:[0,1]
	v_pk_mul_f32 v[104:105], v[38:39], v[50:51] op_sel:[0,1]
	v_pk_fma_f32 v[102:103], v[36:37], v[50:51], v[102:103] op_sel_hi:[1,0,1]
	v_pk_fma_f32 v[50:51], v[34:35], v[50:51], v[104:105] op_sel_hi:[1,0,1]
	v_mov_b32_e32 v104, v53
	v_pk_mul_f32 v[106:107], v[48:49], v[104:105] op_sel_hi:[1,0]
	v_pk_mul_f32 v[104:105], v[46:47], v[104:105] op_sel_hi:[1,0]
	v_pk_fma_f32 v[106:107], v[44:45], v[52:53], v[106:107] op_sel_hi:[1,0,1]
	v_pk_fma_f32 v[52:53], v[42:43], v[52:53], v[104:105] op_sel_hi:[1,0,1]
	v_pk_add_f32 v[102:103], v[102:103], v[106:107]
	v_pk_add_f32 v[50:51], v[50:51], v[52:53]
	v_pk_add_f32 v[32:33], v[32:33], v[102:103]
	v_pk_add_f32 v[30:31], v[30:31], v[50:51]
	ds_read_b128 v[50:53], v56 offset:32784
	v_add_u32_e32 v56, 32, v56
	s_waitcnt lgkmcnt(0)
	v_pk_mul_f32 v[38:39], v[38:39], v[50:51] op_sel:[0,1]
	v_pk_mul_f32 v[40:41], v[40:41], v[50:51] op_sel:[0,1]
	v_pk_fma_f32 v[34:35], v[34:35], v[50:51], v[38:39] op_sel_hi:[1,0,1]
	v_mov_b32_e32 v38, v53
	v_pk_fma_f32 v[36:37], v[36:37], v[50:51], v[40:41] op_sel_hi:[1,0,1]
	v_pk_mul_f32 v[40:41], v[48:49], v[38:39] op_sel_hi:[1,0]
	v_pk_mul_f32 v[38:39], v[46:47], v[38:39] op_sel_hi:[1,0]
	v_pk_fma_f32 v[40:41], v[44:45], v[52:53], v[40:41] op_sel_hi:[1,0,1]
	v_pk_fma_f32 v[38:39], v[42:43], v[52:53], v[38:39] op_sel_hi:[1,0,1]
	v_pk_add_f32 v[36:37], v[36:37], v[40:41]
	v_pk_add_f32 v[34:35], v[34:35], v[38:39]
	v_pk_add_f32 v[36:37], v[74:75], v[36:37]
	v_pk_add_f32 v[34:35], v[76:77], v[34:35]
	v_pk_mov_b32 v[38:39], v[154:155], v[154:155] op_sel:[0,1]
	v_pk_mov_b32 v[40:41], v[156:157], v[156:157] op_sel:[0,1]
	v_pk_mov_b32 v[42:43], v[158:159], v[158:159] op_sel:[0,1]
	v_pk_mov_b32 v[44:45], v[160:161], v[160:161] op_sel:[0,1]
	v_pk_mov_b32 v[74:75], v[162:163], v[162:163] op_sel:[0,1]
	v_pk_mov_b32 v[76:77], v[164:165], v[164:165] op_sel:[0,1]
	v_pk_mov_b32 v[102:103], v[166:167], v[166:167] op_sel:[0,1]
	v_pk_mov_b32 v[104:105], v[168:169], v[168:169] op_sel:[0,1]
	ds_read_b128 v[106:109], v56
	ds_read_b128 v[50:53], v56 offset:16
	s_waitcnt lgkmcnt(1)
	v_pk_mul_f32 v[48:49], v[44:45], v[106:107] op_sel:[0,1]
	v_pk_mul_f32 v[110:111], v[42:43], v[106:107] op_sel:[0,1]
	v_pk_fma_f32 v[48:49], v[40:41], v[106:107], v[48:49] op_sel_hi:[1,0,1]
	v_pk_fma_f32 v[106:107], v[38:39], v[106:107], v[110:111] op_sel_hi:[1,0,1]
	v_mov_b32_e32 v110, v109
	v_pk_mul_f32 v[112:113], v[104:105], v[110:111] op_sel_hi:[1,0]
	v_pk_mul_f32 v[110:111], v[102:103], v[110:111] op_sel_hi:[1,0]
	v_pk_fma_f32 v[112:113], v[76:77], v[108:109], v[112:113] op_sel_hi:[1,0,1]
	v_pk_fma_f32 v[108:109], v[74:75], v[108:109], v[110:111] op_sel_hi:[1,0,1]
	v_pk_add_f32 v[48:49], v[48:49], v[112:113]
	v_pk_add_f32 v[106:107], v[106:107], v[108:109]
	v_pk_add_f32 v[4:5], v[4:5], v[48:49]
	v_pk_add_f32 v[2:3], v[2:3], v[106:107]
	ds_read_b128 v[106:109], v56 offset:4096
	s_waitcnt lgkmcnt(0)
	v_pk_mul_f32 v[48:49], v[44:45], v[106:107] op_sel:[0,1]
	v_pk_mul_f32 v[110:111], v[42:43], v[106:107] op_sel:[0,1]
	v_pk_fma_f32 v[48:49], v[40:41], v[106:107], v[48:49] op_sel_hi:[1,0,1]
	v_pk_fma_f32 v[106:107], v[38:39], v[106:107], v[110:111] op_sel_hi:[1,0,1]
	v_mov_b32_e32 v110, v109
	v_pk_mul_f32 v[112:113], v[104:105], v[110:111] op_sel_hi:[1,0]
	v_pk_mul_f32 v[110:111], v[102:103], v[110:111] op_sel_hi:[1,0]
	v_pk_fma_f32 v[112:113], v[76:77], v[108:109], v[112:113] op_sel_hi:[1,0,1]
	v_pk_fma_f32 v[108:109], v[74:75], v[108:109], v[110:111] op_sel_hi:[1,0,1]
	v_pk_add_f32 v[48:49], v[48:49], v[112:113]
	v_pk_add_f32 v[106:107], v[106:107], v[108:109]
	v_pk_add_f32 v[8:9], v[8:9], v[48:49]
	v_pk_add_f32 v[6:7], v[6:7], v[106:107]
	ds_read_b128 v[106:109], v56 offset:8192
	s_waitcnt lgkmcnt(0)
	v_pk_mul_f32 v[48:49], v[44:45], v[106:107] op_sel:[0,1]
	v_pk_mul_f32 v[110:111], v[42:43], v[106:107] op_sel:[0,1]
	v_pk_fma_f32 v[48:49], v[40:41], v[106:107], v[48:49] op_sel_hi:[1,0,1]
	v_pk_fma_f32 v[106:107], v[38:39], v[106:107], v[110:111] op_sel_hi:[1,0,1]
	v_mov_b32_e32 v110, v109
	v_pk_mul_f32 v[112:113], v[104:105], v[110:111] op_sel_hi:[1,0]
	v_pk_mul_f32 v[110:111], v[102:103], v[110:111] op_sel_hi:[1,0]
	v_pk_fma_f32 v[112:113], v[76:77], v[108:109], v[112:113] op_sel_hi:[1,0,1]
	v_pk_fma_f32 v[108:109], v[74:75], v[108:109], v[110:111] op_sel_hi:[1,0,1]
	v_pk_add_f32 v[48:49], v[48:49], v[112:113]
	v_pk_add_f32 v[106:107], v[106:107], v[108:109]
	v_pk_add_f32 v[12:13], v[12:13], v[48:49]
	v_pk_add_f32 v[10:11], v[10:11], v[106:107]
	ds_read_b128 v[106:109], v56 offset:12288
	s_waitcnt lgkmcnt(0)
	v_pk_mul_f32 v[48:49], v[44:45], v[106:107] op_sel:[0,1]
	v_pk_mul_f32 v[110:111], v[42:43], v[106:107] op_sel:[0,1]
	v_pk_fma_f32 v[48:49], v[40:41], v[106:107], v[48:49] op_sel_hi:[1,0,1]
	v_pk_fma_f32 v[106:107], v[38:39], v[106:107], v[110:111] op_sel_hi:[1,0,1]
	v_mov_b32_e32 v110, v109
	v_pk_mul_f32 v[112:113], v[104:105], v[110:111] op_sel_hi:[1,0]
	v_pk_mul_f32 v[110:111], v[102:103], v[110:111] op_sel_hi:[1,0]
	v_pk_fma_f32 v[112:113], v[76:77], v[108:109], v[112:113] op_sel_hi:[1,0,1]
	v_pk_fma_f32 v[108:109], v[74:75], v[108:109], v[110:111] op_sel_hi:[1,0,1]
	v_pk_add_f32 v[48:49], v[48:49], v[112:113]
	v_pk_add_f32 v[106:107], v[106:107], v[108:109]
	v_pk_add_f32 v[16:17], v[16:17], v[48:49]
	v_pk_add_f32 v[14:15], v[14:15], v[106:107]
	ds_read_b128 v[106:109], v56 offset:16384
	s_waitcnt lgkmcnt(0)
	v_pk_mul_f32 v[48:49], v[44:45], v[106:107] op_sel:[0,1]
	v_pk_mul_f32 v[110:111], v[42:43], v[106:107] op_sel:[0,1]
	v_pk_fma_f32 v[48:49], v[40:41], v[106:107], v[48:49] op_sel_hi:[1,0,1]
	v_pk_fma_f32 v[106:107], v[38:39], v[106:107], v[110:111] op_sel_hi:[1,0,1]
	v_mov_b32_e32 v110, v109
	v_pk_mul_f32 v[112:113], v[104:105], v[110:111] op_sel_hi:[1,0]
	v_pk_mul_f32 v[110:111], v[102:103], v[110:111] op_sel_hi:[1,0]
	v_pk_fma_f32 v[112:113], v[76:77], v[108:109], v[112:113] op_sel_hi:[1,0,1]
	v_pk_fma_f32 v[108:109], v[74:75], v[108:109], v[110:111] op_sel_hi:[1,0,1]
	v_pk_add_f32 v[48:49], v[48:49], v[112:113]
	v_pk_add_f32 v[106:107], v[106:107], v[108:109]
	v_pk_add_f32 v[20:21], v[20:21], v[48:49]
	v_pk_add_f32 v[18:19], v[18:19], v[106:107]
	ds_read_b128 v[106:109], v56 offset:20480
	s_waitcnt lgkmcnt(0)
	v_pk_mul_f32 v[48:49], v[44:45], v[106:107] op_sel:[0,1]
	v_pk_mul_f32 v[110:111], v[42:43], v[106:107] op_sel:[0,1]
	v_pk_fma_f32 v[48:49], v[40:41], v[106:107], v[48:49] op_sel_hi:[1,0,1]
	v_pk_fma_f32 v[106:107], v[38:39], v[106:107], v[110:111] op_sel_hi:[1,0,1]
	v_mov_b32_e32 v110, v109
	v_pk_mul_f32 v[112:113], v[104:105], v[110:111] op_sel_hi:[1,0]
	v_pk_mul_f32 v[110:111], v[102:103], v[110:111] op_sel_hi:[1,0]
	v_pk_fma_f32 v[112:113], v[76:77], v[108:109], v[112:113] op_sel_hi:[1,0,1]
	v_pk_fma_f32 v[108:109], v[74:75], v[108:109], v[110:111] op_sel_hi:[1,0,1]
	v_pk_add_f32 v[48:49], v[48:49], v[112:113]
	v_pk_add_f32 v[106:107], v[106:107], v[108:109]
	v_pk_add_f32 v[24:25], v[24:25], v[48:49]
	v_pk_add_f32 v[22:23], v[22:23], v[106:107]
	ds_read_b128 v[106:109], v56 offset:24576
	s_waitcnt lgkmcnt(0)
	v_pk_mul_f32 v[48:49], v[44:45], v[106:107] op_sel:[0,1]
	v_pk_mul_f32 v[110:111], v[42:43], v[106:107] op_sel:[0,1]
	v_pk_fma_f32 v[48:49], v[40:41], v[106:107], v[48:49] op_sel_hi:[1,0,1]
	v_pk_fma_f32 v[106:107], v[38:39], v[106:107], v[110:111] op_sel_hi:[1,0,1]
	v_mov_b32_e32 v110, v109
	v_pk_mul_f32 v[112:113], v[104:105], v[110:111] op_sel_hi:[1,0]
	v_pk_mul_f32 v[110:111], v[102:103], v[110:111] op_sel_hi:[1,0]
	v_pk_fma_f32 v[112:113], v[76:77], v[108:109], v[112:113] op_sel_hi:[1,0,1]
	v_pk_fma_f32 v[108:109], v[74:75], v[108:109], v[110:111] op_sel_hi:[1,0,1]
	v_pk_add_f32 v[48:49], v[48:49], v[112:113]
	v_pk_add_f32 v[106:107], v[106:107], v[108:109]
	v_pk_add_f32 v[28:29], v[28:29], v[48:49]
	v_pk_add_f32 v[26:27], v[26:27], v[106:107]
	ds_read_b128 v[106:109], v56 offset:28672
	s_waitcnt lgkmcnt(0)
	v_pk_mul_f32 v[48:49], v[44:45], v[106:107] op_sel:[0,1]
	v_pk_mul_f32 v[110:111], v[42:43], v[106:107] op_sel:[0,1]
	v_pk_fma_f32 v[48:49], v[40:41], v[106:107], v[48:49] op_sel_hi:[1,0,1]
	v_pk_fma_f32 v[106:107], v[38:39], v[106:107], v[110:111] op_sel_hi:[1,0,1]
	v_mov_b32_e32 v110, v109
	v_pk_mul_f32 v[112:113], v[104:105], v[110:111] op_sel_hi:[1,0]
	v_pk_mul_f32 v[110:111], v[102:103], v[110:111] op_sel_hi:[1,0]
	v_pk_fma_f32 v[112:113], v[76:77], v[108:109], v[112:113] op_sel_hi:[1,0,1]
	v_pk_fma_f32 v[108:109], v[74:75], v[108:109], v[110:111] op_sel_hi:[1,0,1]
	v_pk_add_f32 v[48:49], v[48:49], v[112:113]
	v_pk_add_f32 v[106:107], v[106:107], v[108:109]
	v_pk_add_f32 v[32:33], v[32:33], v[48:49]
	v_pk_add_f32 v[30:31], v[30:31], v[106:107]
	ds_read_b128 v[106:109], v56 offset:32768
	s_waitcnt lgkmcnt(0)
	v_pk_mul_f32 v[42:43], v[42:43], v[106:107] op_sel:[0,1]
	v_pk_mul_f32 v[44:45], v[44:45], v[106:107] op_sel:[0,1]
	v_pk_fma_f32 v[38:39], v[38:39], v[106:107], v[42:43] op_sel_hi:[1,0,1]
	v_mov_b32_e32 v42, v109
	v_pk_fma_f32 v[40:41], v[40:41], v[106:107], v[44:45] op_sel_hi:[1,0,1]
	v_pk_mul_f32 v[44:45], v[104:105], v[42:43] op_sel_hi:[1,0]
	v_pk_mul_f32 v[42:43], v[102:103], v[42:43] op_sel_hi:[1,0]
	v_pk_fma_f32 v[44:45], v[76:77], v[108:109], v[44:45] op_sel_hi:[1,0,1]
	v_pk_fma_f32 v[42:43], v[74:75], v[108:109], v[42:43] op_sel_hi:[1,0,1]
	v_pk_add_f32 v[40:41], v[40:41], v[44:45]
	v_pk_add_f32 v[38:39], v[38:39], v[42:43]
	v_pk_add_f32 v[74:75], v[36:37], v[40:41]
	v_pk_add_f32 v[76:77], v[34:35], v[38:39]
	v_pk_mov_b32 v[34:35], v[170:171], v[170:171] op_sel:[0,1]
	v_pk_mov_b32 v[36:37], v[172:173], v[172:173] op_sel:[0,1]
	v_pk_mov_b32 v[38:39], v[174:175], v[174:175] op_sel:[0,1]
	v_pk_mov_b32 v[40:41], v[176:177], v[176:177] op_sel:[0,1]
	v_pk_mov_b32 v[42:43], v[178:179], v[178:179] op_sel:[0,1]
	v_pk_mov_b32 v[44:45], v[180:181], v[180:181] op_sel:[0,1]
	v_pk_mov_b32 v[46:47], v[182:183], v[182:183] op_sel:[0,1]
	v_pk_mov_b32 v[48:49], v[184:185], v[184:185] op_sel:[0,1]
	v_pk_mul_f32 v[102:103], v[40:41], v[50:51] op_sel:[0,1]
	v_pk_mul_f32 v[104:105], v[38:39], v[50:51] op_sel:[0,1]
	v_pk_fma_f32 v[102:103], v[36:37], v[50:51], v[102:103] op_sel_hi:[1,0,1]
	v_pk_fma_f32 v[50:51], v[34:35], v[50:51], v[104:105] op_sel_hi:[1,0,1]
	v_mov_b32_e32 v104, v53
	v_pk_mul_f32 v[106:107], v[48:49], v[104:105] op_sel_hi:[1,0]
	v_pk_mul_f32 v[104:105], v[46:47], v[104:105] op_sel_hi:[1,0]
	v_pk_fma_f32 v[106:107], v[44:45], v[52:53], v[106:107] op_sel_hi:[1,0,1]
	v_pk_fma_f32 v[52:53], v[42:43], v[52:53], v[104:105] op_sel_hi:[1,0,1]
	v_pk_add_f32 v[102:103], v[102:103], v[106:107]
	v_pk_add_f32 v[50:51], v[50:51], v[52:53]
	v_pk_add_f32 v[4:5], v[4:5], v[102:103]
	v_pk_add_f32 v[2:3], v[2:3], v[50:51]
	ds_read_b128 v[50:53], v56 offset:4112
	s_waitcnt lgkmcnt(0)
	v_pk_mul_f32 v[102:103], v[40:41], v[50:51] op_sel:[0,1]
	v_pk_mul_f32 v[104:105], v[38:39], v[50:51] op_sel:[0,1]
	v_pk_fma_f32 v[102:103], v[36:37], v[50:51], v[102:103] op_sel_hi:[1,0,1]
	v_pk_fma_f32 v[50:51], v[34:35], v[50:51], v[104:105] op_sel_hi:[1,0,1]
	v_mov_b32_e32 v104, v53
	v_pk_mul_f32 v[106:107], v[48:49], v[104:105] op_sel_hi:[1,0]
	v_pk_mul_f32 v[104:105], v[46:47], v[104:105] op_sel_hi:[1,0]
	v_pk_fma_f32 v[106:107], v[44:45], v[52:53], v[106:107] op_sel_hi:[1,0,1]
	v_pk_fma_f32 v[52:53], v[42:43], v[52:53], v[104:105] op_sel_hi:[1,0,1]
	v_pk_add_f32 v[102:103], v[102:103], v[106:107]
	v_pk_add_f32 v[50:51], v[50:51], v[52:53]
	v_pk_add_f32 v[8:9], v[8:9], v[102:103]
	v_pk_add_f32 v[6:7], v[6:7], v[50:51]
	ds_read_b128 v[50:53], v56 offset:8208
	s_waitcnt lgkmcnt(0)
	v_pk_mul_f32 v[102:103], v[40:41], v[50:51] op_sel:[0,1]
	v_pk_mul_f32 v[104:105], v[38:39], v[50:51] op_sel:[0,1]
	v_pk_fma_f32 v[102:103], v[36:37], v[50:51], v[102:103] op_sel_hi:[1,0,1]
	v_pk_fma_f32 v[50:51], v[34:35], v[50:51], v[104:105] op_sel_hi:[1,0,1]
	v_mov_b32_e32 v104, v53
	v_pk_mul_f32 v[106:107], v[48:49], v[104:105] op_sel_hi:[1,0]
	v_pk_mul_f32 v[104:105], v[46:47], v[104:105] op_sel_hi:[1,0]
	v_pk_fma_f32 v[106:107], v[44:45], v[52:53], v[106:107] op_sel_hi:[1,0,1]
	v_pk_fma_f32 v[52:53], v[42:43], v[52:53], v[104:105] op_sel_hi:[1,0,1]
	v_pk_add_f32 v[102:103], v[102:103], v[106:107]
	v_pk_add_f32 v[50:51], v[50:51], v[52:53]
	v_pk_add_f32 v[12:13], v[12:13], v[102:103]
	v_pk_add_f32 v[10:11], v[10:11], v[50:51]
	ds_read_b128 v[50:53], v56 offset:12304
	s_waitcnt lgkmcnt(0)
	v_pk_mul_f32 v[102:103], v[40:41], v[50:51] op_sel:[0,1]
	v_pk_mul_f32 v[104:105], v[38:39], v[50:51] op_sel:[0,1]
	v_pk_fma_f32 v[102:103], v[36:37], v[50:51], v[102:103] op_sel_hi:[1,0,1]
	v_pk_fma_f32 v[50:51], v[34:35], v[50:51], v[104:105] op_sel_hi:[1,0,1]
	v_mov_b32_e32 v104, v53
	v_pk_mul_f32 v[106:107], v[48:49], v[104:105] op_sel_hi:[1,0]
	v_pk_mul_f32 v[104:105], v[46:47], v[104:105] op_sel_hi:[1,0]
	v_pk_fma_f32 v[106:107], v[44:45], v[52:53], v[106:107] op_sel_hi:[1,0,1]
	v_pk_fma_f32 v[52:53], v[42:43], v[52:53], v[104:105] op_sel_hi:[1,0,1]
	v_pk_add_f32 v[102:103], v[102:103], v[106:107]
	v_pk_add_f32 v[50:51], v[50:51], v[52:53]
	v_pk_add_f32 v[16:17], v[16:17], v[102:103]
	v_pk_add_f32 v[14:15], v[14:15], v[50:51]
	ds_read_b128 v[50:53], v56 offset:16400
	s_waitcnt lgkmcnt(0)
	v_pk_mul_f32 v[102:103], v[40:41], v[50:51] op_sel:[0,1]
	v_pk_mul_f32 v[104:105], v[38:39], v[50:51] op_sel:[0,1]
	v_pk_fma_f32 v[102:103], v[36:37], v[50:51], v[102:103] op_sel_hi:[1,0,1]
	v_pk_fma_f32 v[50:51], v[34:35], v[50:51], v[104:105] op_sel_hi:[1,0,1]
	v_mov_b32_e32 v104, v53
	v_pk_mul_f32 v[106:107], v[48:49], v[104:105] op_sel_hi:[1,0]
	v_pk_mul_f32 v[104:105], v[46:47], v[104:105] op_sel_hi:[1,0]
	v_pk_fma_f32 v[106:107], v[44:45], v[52:53], v[106:107] op_sel_hi:[1,0,1]
	v_pk_fma_f32 v[52:53], v[42:43], v[52:53], v[104:105] op_sel_hi:[1,0,1]
	v_pk_add_f32 v[102:103], v[102:103], v[106:107]
	v_pk_add_f32 v[50:51], v[50:51], v[52:53]
	v_pk_add_f32 v[20:21], v[20:21], v[102:103]
	v_pk_add_f32 v[18:19], v[18:19], v[50:51]
	ds_read_b128 v[50:53], v56 offset:20496
	s_waitcnt lgkmcnt(0)
	v_pk_mul_f32 v[102:103], v[40:41], v[50:51] op_sel:[0,1]
	v_pk_mul_f32 v[104:105], v[38:39], v[50:51] op_sel:[0,1]
	v_pk_fma_f32 v[102:103], v[36:37], v[50:51], v[102:103] op_sel_hi:[1,0,1]
	v_pk_fma_f32 v[50:51], v[34:35], v[50:51], v[104:105] op_sel_hi:[1,0,1]
	v_mov_b32_e32 v104, v53
	v_pk_mul_f32 v[106:107], v[48:49], v[104:105] op_sel_hi:[1,0]
	v_pk_mul_f32 v[104:105], v[46:47], v[104:105] op_sel_hi:[1,0]
	v_pk_fma_f32 v[106:107], v[44:45], v[52:53], v[106:107] op_sel_hi:[1,0,1]
	v_pk_fma_f32 v[52:53], v[42:43], v[52:53], v[104:105] op_sel_hi:[1,0,1]
	v_pk_add_f32 v[102:103], v[102:103], v[106:107]
	v_pk_add_f32 v[50:51], v[50:51], v[52:53]
	v_pk_add_f32 v[24:25], v[24:25], v[102:103]
	v_pk_add_f32 v[22:23], v[22:23], v[50:51]
	ds_read_b128 v[50:53], v56 offset:24592
	s_waitcnt lgkmcnt(0)
	v_pk_mul_f32 v[102:103], v[40:41], v[50:51] op_sel:[0,1]
	v_pk_mul_f32 v[104:105], v[38:39], v[50:51] op_sel:[0,1]
	v_pk_fma_f32 v[102:103], v[36:37], v[50:51], v[102:103] op_sel_hi:[1,0,1]
	v_pk_fma_f32 v[50:51], v[34:35], v[50:51], v[104:105] op_sel_hi:[1,0,1]
	v_mov_b32_e32 v104, v53
	v_pk_mul_f32 v[106:107], v[48:49], v[104:105] op_sel_hi:[1,0]
	v_pk_mul_f32 v[104:105], v[46:47], v[104:105] op_sel_hi:[1,0]
	v_pk_fma_f32 v[106:107], v[44:45], v[52:53], v[106:107] op_sel_hi:[1,0,1]
	v_pk_fma_f32 v[52:53], v[42:43], v[52:53], v[104:105] op_sel_hi:[1,0,1]
	v_pk_add_f32 v[102:103], v[102:103], v[106:107]
	v_pk_add_f32 v[50:51], v[50:51], v[52:53]
	v_pk_add_f32 v[28:29], v[28:29], v[102:103]
	v_pk_add_f32 v[26:27], v[26:27], v[50:51]
	ds_read_b128 v[50:53], v56 offset:28688
	s_waitcnt lgkmcnt(0)
	v_pk_mul_f32 v[102:103], v[40:41], v[50:51] op_sel:[0,1]
	v_pk_mul_f32 v[104:105], v[38:39], v[50:51] op_sel:[0,1]
	v_pk_fma_f32 v[102:103], v[36:37], v[50:51], v[102:103] op_sel_hi:[1,0,1]
	v_pk_fma_f32 v[50:51], v[34:35], v[50:51], v[104:105] op_sel_hi:[1,0,1]
	v_mov_b32_e32 v104, v53
	v_pk_mul_f32 v[106:107], v[48:49], v[104:105] op_sel_hi:[1,0]
	v_pk_mul_f32 v[104:105], v[46:47], v[104:105] op_sel_hi:[1,0]
	v_pk_fma_f32 v[106:107], v[44:45], v[52:53], v[106:107] op_sel_hi:[1,0,1]
	v_pk_fma_f32 v[52:53], v[42:43], v[52:53], v[104:105] op_sel_hi:[1,0,1]
	v_pk_add_f32 v[102:103], v[102:103], v[106:107]
	v_pk_add_f32 v[50:51], v[50:51], v[52:53]
	v_pk_add_f32 v[32:33], v[32:33], v[102:103]
	v_pk_add_f32 v[30:31], v[30:31], v[50:51]
	ds_read_b128 v[50:53], v56 offset:32784
	v_add_u32_e32 v56, 32, v56
	s_waitcnt lgkmcnt(0)
	v_pk_mul_f32 v[38:39], v[38:39], v[50:51] op_sel:[0,1]
	v_pk_mul_f32 v[40:41], v[40:41], v[50:51] op_sel:[0,1]
	v_pk_fma_f32 v[34:35], v[34:35], v[50:51], v[38:39] op_sel_hi:[1,0,1]
	v_mov_b32_e32 v38, v53
	v_pk_fma_f32 v[36:37], v[36:37], v[50:51], v[40:41] op_sel_hi:[1,0,1]
	v_pk_mul_f32 v[40:41], v[48:49], v[38:39] op_sel_hi:[1,0]
	v_pk_mul_f32 v[38:39], v[46:47], v[38:39] op_sel_hi:[1,0]
	v_pk_fma_f32 v[40:41], v[44:45], v[52:53], v[40:41] op_sel_hi:[1,0,1]
	v_pk_fma_f32 v[38:39], v[42:43], v[52:53], v[38:39] op_sel_hi:[1,0,1]
	v_pk_add_f32 v[36:37], v[36:37], v[40:41]
	v_pk_add_f32 v[34:35], v[34:35], v[38:39]
	v_pk_add_f32 v[36:37], v[74:75], v[36:37]
	v_pk_add_f32 v[34:35], v[76:77], v[34:35]
	s_waitcnt vmcnt(0)
	v_pk_mov_b32 v[38:39], v[186:187], v[186:187] op_sel:[0,1]
	v_pk_mov_b32 v[40:41], v[188:189], v[188:189] op_sel:[0,1]
	v_pk_mov_b32 v[42:43], v[190:191], v[190:191] op_sel:[0,1]
	v_pk_mov_b32 v[44:45], v[192:193], v[192:193] op_sel:[0,1]
	v_pk_mov_b32 v[74:75], v[194:195], v[194:195] op_sel:[0,1]
	v_pk_mov_b32 v[76:77], v[196:197], v[196:197] op_sel:[0,1]
	v_pk_mov_b32 v[102:103], v[198:199], v[198:199] op_sel:[0,1]
	v_pk_mov_b32 v[104:105], v[200:201], v[200:201] op_sel:[0,1]
	ds_read_b128 v[106:109], v56
	ds_read_b128 v[50:53], v56 offset:16
	s_waitcnt lgkmcnt(1)
	v_pk_mul_f32 v[48:49], v[44:45], v[106:107] op_sel:[0,1]
	v_pk_mul_f32 v[110:111], v[42:43], v[106:107] op_sel:[0,1]
	v_pk_fma_f32 v[48:49], v[40:41], v[106:107], v[48:49] op_sel_hi:[1,0,1]
	v_pk_fma_f32 v[106:107], v[38:39], v[106:107], v[110:111] op_sel_hi:[1,0,1]
	v_mov_b32_e32 v110, v109
	v_pk_mul_f32 v[112:113], v[104:105], v[110:111] op_sel_hi:[1,0]
	v_pk_mul_f32 v[110:111], v[102:103], v[110:111] op_sel_hi:[1,0]
	v_pk_fma_f32 v[112:113], v[76:77], v[108:109], v[112:113] op_sel_hi:[1,0,1]
	v_pk_fma_f32 v[108:109], v[74:75], v[108:109], v[110:111] op_sel_hi:[1,0,1]
	v_pk_add_f32 v[48:49], v[48:49], v[112:113]
	v_pk_add_f32 v[106:107], v[106:107], v[108:109]
	v_pk_add_f32 v[4:5], v[4:5], v[48:49]
	v_pk_add_f32 v[2:3], v[2:3], v[106:107]
	ds_read_b128 v[106:109], v56 offset:4096
	s_waitcnt lgkmcnt(0)
	v_pk_mul_f32 v[48:49], v[44:45], v[106:107] op_sel:[0,1]
	v_pk_mul_f32 v[110:111], v[42:43], v[106:107] op_sel:[0,1]
	v_pk_fma_f32 v[48:49], v[40:41], v[106:107], v[48:49] op_sel_hi:[1,0,1]
	v_pk_fma_f32 v[106:107], v[38:39], v[106:107], v[110:111] op_sel_hi:[1,0,1]
	v_mov_b32_e32 v110, v109
	v_pk_mul_f32 v[112:113], v[104:105], v[110:111] op_sel_hi:[1,0]
	v_pk_mul_f32 v[110:111], v[102:103], v[110:111] op_sel_hi:[1,0]
	v_pk_fma_f32 v[112:113], v[76:77], v[108:109], v[112:113] op_sel_hi:[1,0,1]
	v_pk_fma_f32 v[108:109], v[74:75], v[108:109], v[110:111] op_sel_hi:[1,0,1]
	v_pk_add_f32 v[48:49], v[48:49], v[112:113]
	v_pk_add_f32 v[106:107], v[106:107], v[108:109]
	v_pk_add_f32 v[8:9], v[8:9], v[48:49]
	v_pk_add_f32 v[6:7], v[6:7], v[106:107]
	ds_read_b128 v[106:109], v56 offset:8192
	s_waitcnt lgkmcnt(0)
	v_pk_mul_f32 v[48:49], v[44:45], v[106:107] op_sel:[0,1]
	v_pk_mul_f32 v[110:111], v[42:43], v[106:107] op_sel:[0,1]
	v_pk_fma_f32 v[48:49], v[40:41], v[106:107], v[48:49] op_sel_hi:[1,0,1]
	v_pk_fma_f32 v[106:107], v[38:39], v[106:107], v[110:111] op_sel_hi:[1,0,1]
	v_mov_b32_e32 v110, v109
	v_pk_mul_f32 v[112:113], v[104:105], v[110:111] op_sel_hi:[1,0]
	v_pk_mul_f32 v[110:111], v[102:103], v[110:111] op_sel_hi:[1,0]
	v_pk_fma_f32 v[112:113], v[76:77], v[108:109], v[112:113] op_sel_hi:[1,0,1]
	v_pk_fma_f32 v[108:109], v[74:75], v[108:109], v[110:111] op_sel_hi:[1,0,1]
	v_pk_add_f32 v[48:49], v[48:49], v[112:113]
	v_pk_add_f32 v[106:107], v[106:107], v[108:109]
	v_pk_add_f32 v[12:13], v[12:13], v[48:49]
	v_pk_add_f32 v[10:11], v[10:11], v[106:107]
	ds_read_b128 v[106:109], v56 offset:12288
	s_waitcnt lgkmcnt(0)
	v_pk_mul_f32 v[48:49], v[44:45], v[106:107] op_sel:[0,1]
	v_pk_mul_f32 v[110:111], v[42:43], v[106:107] op_sel:[0,1]
	v_pk_fma_f32 v[48:49], v[40:41], v[106:107], v[48:49] op_sel_hi:[1,0,1]
	v_pk_fma_f32 v[106:107], v[38:39], v[106:107], v[110:111] op_sel_hi:[1,0,1]
	v_mov_b32_e32 v110, v109
	v_pk_mul_f32 v[112:113], v[104:105], v[110:111] op_sel_hi:[1,0]
	v_pk_mul_f32 v[110:111], v[102:103], v[110:111] op_sel_hi:[1,0]
	v_pk_fma_f32 v[112:113], v[76:77], v[108:109], v[112:113] op_sel_hi:[1,0,1]
	v_pk_fma_f32 v[108:109], v[74:75], v[108:109], v[110:111] op_sel_hi:[1,0,1]
	v_pk_add_f32 v[48:49], v[48:49], v[112:113]
	v_pk_add_f32 v[106:107], v[106:107], v[108:109]
	v_pk_add_f32 v[16:17], v[16:17], v[48:49]
	v_pk_add_f32 v[14:15], v[14:15], v[106:107]
	ds_read_b128 v[106:109], v56 offset:16384
	s_waitcnt lgkmcnt(0)
	v_pk_mul_f32 v[48:49], v[44:45], v[106:107] op_sel:[0,1]
	v_pk_mul_f32 v[110:111], v[42:43], v[106:107] op_sel:[0,1]
	v_pk_fma_f32 v[48:49], v[40:41], v[106:107], v[48:49] op_sel_hi:[1,0,1]
	v_pk_fma_f32 v[106:107], v[38:39], v[106:107], v[110:111] op_sel_hi:[1,0,1]
	v_mov_b32_e32 v110, v109
	v_pk_mul_f32 v[112:113], v[104:105], v[110:111] op_sel_hi:[1,0]
	v_pk_mul_f32 v[110:111], v[102:103], v[110:111] op_sel_hi:[1,0]
	v_pk_fma_f32 v[112:113], v[76:77], v[108:109], v[112:113] op_sel_hi:[1,0,1]
	v_pk_fma_f32 v[108:109], v[74:75], v[108:109], v[110:111] op_sel_hi:[1,0,1]
	v_pk_add_f32 v[48:49], v[48:49], v[112:113]
	v_pk_add_f32 v[106:107], v[106:107], v[108:109]
	v_pk_add_f32 v[20:21], v[20:21], v[48:49]
	v_pk_add_f32 v[18:19], v[18:19], v[106:107]
	ds_read_b128 v[106:109], v56 offset:20480
	s_waitcnt lgkmcnt(0)
	v_pk_mul_f32 v[48:49], v[44:45], v[106:107] op_sel:[0,1]
	v_pk_mul_f32 v[110:111], v[42:43], v[106:107] op_sel:[0,1]
	v_pk_fma_f32 v[48:49], v[40:41], v[106:107], v[48:49] op_sel_hi:[1,0,1]
	v_pk_fma_f32 v[106:107], v[38:39], v[106:107], v[110:111] op_sel_hi:[1,0,1]
	v_mov_b32_e32 v110, v109
	v_pk_mul_f32 v[112:113], v[104:105], v[110:111] op_sel_hi:[1,0]
	v_pk_mul_f32 v[110:111], v[102:103], v[110:111] op_sel_hi:[1,0]
	v_pk_fma_f32 v[112:113], v[76:77], v[108:109], v[112:113] op_sel_hi:[1,0,1]
	v_pk_fma_f32 v[108:109], v[74:75], v[108:109], v[110:111] op_sel_hi:[1,0,1]
	v_pk_add_f32 v[48:49], v[48:49], v[112:113]
	v_pk_add_f32 v[106:107], v[106:107], v[108:109]
	v_pk_add_f32 v[24:25], v[24:25], v[48:49]
	v_pk_add_f32 v[22:23], v[22:23], v[106:107]
	ds_read_b128 v[106:109], v56 offset:24576
	s_waitcnt lgkmcnt(0)
	v_pk_mul_f32 v[48:49], v[44:45], v[106:107] op_sel:[0,1]
	v_pk_mul_f32 v[110:111], v[42:43], v[106:107] op_sel:[0,1]
	v_pk_fma_f32 v[48:49], v[40:41], v[106:107], v[48:49] op_sel_hi:[1,0,1]
	v_pk_fma_f32 v[106:107], v[38:39], v[106:107], v[110:111] op_sel_hi:[1,0,1]
	v_mov_b32_e32 v110, v109
	v_pk_mul_f32 v[112:113], v[104:105], v[110:111] op_sel_hi:[1,0]
	v_pk_mul_f32 v[110:111], v[102:103], v[110:111] op_sel_hi:[1,0]
	v_pk_fma_f32 v[112:113], v[76:77], v[108:109], v[112:113] op_sel_hi:[1,0,1]
	v_pk_fma_f32 v[108:109], v[74:75], v[108:109], v[110:111] op_sel_hi:[1,0,1]
	v_pk_add_f32 v[48:49], v[48:49], v[112:113]
	v_pk_add_f32 v[106:107], v[106:107], v[108:109]
	v_pk_add_f32 v[28:29], v[28:29], v[48:49]
	v_pk_add_f32 v[26:27], v[26:27], v[106:107]
	ds_read_b128 v[106:109], v56 offset:28672
	s_waitcnt lgkmcnt(0)
	v_pk_mul_f32 v[48:49], v[44:45], v[106:107] op_sel:[0,1]
	v_pk_mul_f32 v[110:111], v[42:43], v[106:107] op_sel:[0,1]
	v_pk_fma_f32 v[48:49], v[40:41], v[106:107], v[48:49] op_sel_hi:[1,0,1]
	v_pk_fma_f32 v[106:107], v[38:39], v[106:107], v[110:111] op_sel_hi:[1,0,1]
	v_mov_b32_e32 v110, v109
	v_pk_mul_f32 v[112:113], v[104:105], v[110:111] op_sel_hi:[1,0]
	v_pk_mul_f32 v[110:111], v[102:103], v[110:111] op_sel_hi:[1,0]
	v_pk_fma_f32 v[112:113], v[76:77], v[108:109], v[112:113] op_sel_hi:[1,0,1]
	v_pk_fma_f32 v[108:109], v[74:75], v[108:109], v[110:111] op_sel_hi:[1,0,1]
	v_pk_add_f32 v[48:49], v[48:49], v[112:113]
	v_pk_add_f32 v[106:107], v[106:107], v[108:109]
	v_pk_add_f32 v[32:33], v[32:33], v[48:49]
	v_pk_add_f32 v[30:31], v[30:31], v[106:107]
	ds_read_b128 v[106:109], v56 offset:32768
	s_waitcnt lgkmcnt(0)
	v_pk_mul_f32 v[42:43], v[42:43], v[106:107] op_sel:[0,1]
	v_pk_mul_f32 v[44:45], v[44:45], v[106:107] op_sel:[0,1]
	v_pk_fma_f32 v[38:39], v[38:39], v[106:107], v[42:43] op_sel_hi:[1,0,1]
	v_mov_b32_e32 v42, v109
	v_pk_fma_f32 v[40:41], v[40:41], v[106:107], v[44:45] op_sel_hi:[1,0,1]
	v_pk_mul_f32 v[44:45], v[104:105], v[42:43] op_sel_hi:[1,0]
	v_pk_mul_f32 v[42:43], v[102:103], v[42:43] op_sel_hi:[1,0]
	v_pk_fma_f32 v[44:45], v[76:77], v[108:109], v[44:45] op_sel_hi:[1,0,1]
	v_pk_fma_f32 v[42:43], v[74:75], v[108:109], v[42:43] op_sel_hi:[1,0,1]
	v_pk_add_f32 v[40:41], v[40:41], v[44:45]
	v_pk_add_f32 v[38:39], v[38:39], v[42:43]
	v_pk_add_f32 v[74:75], v[36:37], v[40:41]
	v_pk_add_f32 v[76:77], v[34:35], v[38:39]
	v_pk_mov_b32 v[34:35], v[202:203], v[202:203] op_sel:[0,1]
	v_pk_mov_b32 v[36:37], v[204:205], v[204:205] op_sel:[0,1]
	v_pk_mov_b32 v[38:39], v[206:207], v[206:207] op_sel:[0,1]
	v_pk_mov_b32 v[40:41], v[208:209], v[208:209] op_sel:[0,1]
	v_pk_mov_b32 v[42:43], v[210:211], v[210:211] op_sel:[0,1]
	v_pk_mov_b32 v[44:45], v[212:213], v[212:213] op_sel:[0,1]
	v_pk_mov_b32 v[46:47], v[214:215], v[214:215] op_sel:[0,1]
	v_pk_mov_b32 v[48:49], v[216:217], v[216:217] op_sel:[0,1]
	v_pk_mul_f32 v[102:103], v[40:41], v[50:51] op_sel:[0,1]
	v_pk_mul_f32 v[104:105], v[38:39], v[50:51] op_sel:[0,1]
	v_pk_fma_f32 v[102:103], v[36:37], v[50:51], v[102:103] op_sel_hi:[1,0,1]
	v_pk_fma_f32 v[50:51], v[34:35], v[50:51], v[104:105] op_sel_hi:[1,0,1]
	v_mov_b32_e32 v104, v53
	v_pk_mul_f32 v[106:107], v[48:49], v[104:105] op_sel_hi:[1,0]
	v_pk_mul_f32 v[104:105], v[46:47], v[104:105] op_sel_hi:[1,0]
	v_pk_fma_f32 v[106:107], v[44:45], v[52:53], v[106:107] op_sel_hi:[1,0,1]
	v_pk_fma_f32 v[52:53], v[42:43], v[52:53], v[104:105] op_sel_hi:[1,0,1]
	v_pk_add_f32 v[102:103], v[102:103], v[106:107]
	v_pk_add_f32 v[50:51], v[50:51], v[52:53]
	v_pk_add_f32 v[4:5], v[4:5], v[102:103]
	v_pk_add_f32 v[2:3], v[2:3], v[50:51]
	ds_read_b128 v[50:53], v56 offset:4112
	s_waitcnt lgkmcnt(0)
	v_pk_mul_f32 v[102:103], v[40:41], v[50:51] op_sel:[0,1]
	v_pk_mul_f32 v[104:105], v[38:39], v[50:51] op_sel:[0,1]
	v_pk_fma_f32 v[102:103], v[36:37], v[50:51], v[102:103] op_sel_hi:[1,0,1]
	v_pk_fma_f32 v[50:51], v[34:35], v[50:51], v[104:105] op_sel_hi:[1,0,1]
	v_mov_b32_e32 v104, v53
	v_pk_mul_f32 v[106:107], v[48:49], v[104:105] op_sel_hi:[1,0]
	v_pk_mul_f32 v[104:105], v[46:47], v[104:105] op_sel_hi:[1,0]
	v_pk_fma_f32 v[106:107], v[44:45], v[52:53], v[106:107] op_sel_hi:[1,0,1]
	v_pk_fma_f32 v[52:53], v[42:43], v[52:53], v[104:105] op_sel_hi:[1,0,1]
	v_pk_add_f32 v[102:103], v[102:103], v[106:107]
	v_pk_add_f32 v[50:51], v[50:51], v[52:53]
	v_pk_add_f32 v[8:9], v[8:9], v[102:103]
	v_pk_add_f32 v[6:7], v[6:7], v[50:51]
	ds_read_b128 v[50:53], v56 offset:8208
	s_waitcnt lgkmcnt(0)
	v_pk_mul_f32 v[102:103], v[40:41], v[50:51] op_sel:[0,1]
	v_pk_mul_f32 v[104:105], v[38:39], v[50:51] op_sel:[0,1]
	v_pk_fma_f32 v[102:103], v[36:37], v[50:51], v[102:103] op_sel_hi:[1,0,1]
	v_pk_fma_f32 v[50:51], v[34:35], v[50:51], v[104:105] op_sel_hi:[1,0,1]
	v_mov_b32_e32 v104, v53
	v_pk_mul_f32 v[106:107], v[48:49], v[104:105] op_sel_hi:[1,0]
	v_pk_mul_f32 v[104:105], v[46:47], v[104:105] op_sel_hi:[1,0]
	v_pk_fma_f32 v[106:107], v[44:45], v[52:53], v[106:107] op_sel_hi:[1,0,1]
	v_pk_fma_f32 v[52:53], v[42:43], v[52:53], v[104:105] op_sel_hi:[1,0,1]
	v_pk_add_f32 v[102:103], v[102:103], v[106:107]
	v_pk_add_f32 v[50:51], v[50:51], v[52:53]
	v_pk_add_f32 v[12:13], v[12:13], v[102:103]
	v_pk_add_f32 v[10:11], v[10:11], v[50:51]
	ds_read_b128 v[50:53], v56 offset:12304
	s_waitcnt lgkmcnt(0)
	v_pk_mul_f32 v[102:103], v[40:41], v[50:51] op_sel:[0,1]
	v_pk_mul_f32 v[104:105], v[38:39], v[50:51] op_sel:[0,1]
	v_pk_fma_f32 v[102:103], v[36:37], v[50:51], v[102:103] op_sel_hi:[1,0,1]
	v_pk_fma_f32 v[50:51], v[34:35], v[50:51], v[104:105] op_sel_hi:[1,0,1]
	v_mov_b32_e32 v104, v53
	v_pk_mul_f32 v[106:107], v[48:49], v[104:105] op_sel_hi:[1,0]
	v_pk_mul_f32 v[104:105], v[46:47], v[104:105] op_sel_hi:[1,0]
	v_pk_fma_f32 v[106:107], v[44:45], v[52:53], v[106:107] op_sel_hi:[1,0,1]
	v_pk_fma_f32 v[52:53], v[42:43], v[52:53], v[104:105] op_sel_hi:[1,0,1]
	v_pk_add_f32 v[102:103], v[102:103], v[106:107]
	v_pk_add_f32 v[50:51], v[50:51], v[52:53]
	v_pk_add_f32 v[16:17], v[16:17], v[102:103]
	v_pk_add_f32 v[14:15], v[14:15], v[50:51]
	ds_read_b128 v[50:53], v56 offset:16400
	s_waitcnt lgkmcnt(0)
	v_pk_mul_f32 v[102:103], v[40:41], v[50:51] op_sel:[0,1]
	v_pk_mul_f32 v[104:105], v[38:39], v[50:51] op_sel:[0,1]
	v_pk_fma_f32 v[102:103], v[36:37], v[50:51], v[102:103] op_sel_hi:[1,0,1]
	v_pk_fma_f32 v[50:51], v[34:35], v[50:51], v[104:105] op_sel_hi:[1,0,1]
	v_mov_b32_e32 v104, v53
	v_pk_mul_f32 v[106:107], v[48:49], v[104:105] op_sel_hi:[1,0]
	v_pk_mul_f32 v[104:105], v[46:47], v[104:105] op_sel_hi:[1,0]
	v_pk_fma_f32 v[106:107], v[44:45], v[52:53], v[106:107] op_sel_hi:[1,0,1]
	v_pk_fma_f32 v[52:53], v[42:43], v[52:53], v[104:105] op_sel_hi:[1,0,1]
	v_pk_add_f32 v[102:103], v[102:103], v[106:107]
	v_pk_add_f32 v[50:51], v[50:51], v[52:53]
	v_pk_add_f32 v[20:21], v[20:21], v[102:103]
	v_pk_add_f32 v[18:19], v[18:19], v[50:51]
	ds_read_b128 v[50:53], v56 offset:20496
	s_waitcnt lgkmcnt(0)
	v_pk_mul_f32 v[102:103], v[40:41], v[50:51] op_sel:[0,1]
	v_pk_mul_f32 v[104:105], v[38:39], v[50:51] op_sel:[0,1]
	v_pk_fma_f32 v[102:103], v[36:37], v[50:51], v[102:103] op_sel_hi:[1,0,1]
	v_pk_fma_f32 v[50:51], v[34:35], v[50:51], v[104:105] op_sel_hi:[1,0,1]
	v_mov_b32_e32 v104, v53
	v_pk_mul_f32 v[106:107], v[48:49], v[104:105] op_sel_hi:[1,0]
	v_pk_mul_f32 v[104:105], v[46:47], v[104:105] op_sel_hi:[1,0]
	v_pk_fma_f32 v[106:107], v[44:45], v[52:53], v[106:107] op_sel_hi:[1,0,1]
	v_pk_fma_f32 v[52:53], v[42:43], v[52:53], v[104:105] op_sel_hi:[1,0,1]
	v_pk_add_f32 v[102:103], v[102:103], v[106:107]
	v_pk_add_f32 v[50:51], v[50:51], v[52:53]
	v_pk_add_f32 v[24:25], v[24:25], v[102:103]
	v_pk_add_f32 v[22:23], v[22:23], v[50:51]
	ds_read_b128 v[50:53], v56 offset:24592
	s_waitcnt lgkmcnt(0)
	v_pk_mul_f32 v[102:103], v[40:41], v[50:51] op_sel:[0,1]
	v_pk_mul_f32 v[104:105], v[38:39], v[50:51] op_sel:[0,1]
	v_pk_fma_f32 v[102:103], v[36:37], v[50:51], v[102:103] op_sel_hi:[1,0,1]
	v_pk_fma_f32 v[50:51], v[34:35], v[50:51], v[104:105] op_sel_hi:[1,0,1]
	v_mov_b32_e32 v104, v53
	v_pk_mul_f32 v[106:107], v[48:49], v[104:105] op_sel_hi:[1,0]
	v_pk_mul_f32 v[104:105], v[46:47], v[104:105] op_sel_hi:[1,0]
	v_pk_fma_f32 v[106:107], v[44:45], v[52:53], v[106:107] op_sel_hi:[1,0,1]
	v_pk_fma_f32 v[52:53], v[42:43], v[52:53], v[104:105] op_sel_hi:[1,0,1]
	v_pk_add_f32 v[102:103], v[102:103], v[106:107]
	v_pk_add_f32 v[50:51], v[50:51], v[52:53]
	v_pk_add_f32 v[28:29], v[28:29], v[102:103]
	v_pk_add_f32 v[26:27], v[26:27], v[50:51]
	ds_read_b128 v[50:53], v56 offset:28688
	s_waitcnt lgkmcnt(0)
	v_pk_mul_f32 v[102:103], v[40:41], v[50:51] op_sel:[0,1]
	v_pk_mul_f32 v[104:105], v[38:39], v[50:51] op_sel:[0,1]
	v_pk_fma_f32 v[102:103], v[36:37], v[50:51], v[102:103] op_sel_hi:[1,0,1]
	v_pk_fma_f32 v[50:51], v[34:35], v[50:51], v[104:105] op_sel_hi:[1,0,1]
	v_mov_b32_e32 v104, v53
	v_pk_mul_f32 v[106:107], v[48:49], v[104:105] op_sel_hi:[1,0]
	v_pk_mul_f32 v[104:105], v[46:47], v[104:105] op_sel_hi:[1,0]
	v_pk_fma_f32 v[106:107], v[44:45], v[52:53], v[106:107] op_sel_hi:[1,0,1]
	v_pk_fma_f32 v[52:53], v[42:43], v[52:53], v[104:105] op_sel_hi:[1,0,1]
	v_pk_add_f32 v[102:103], v[102:103], v[106:107]
	v_pk_add_f32 v[50:51], v[50:51], v[52:53]
	v_pk_add_f32 v[32:33], v[32:33], v[102:103]
	v_pk_add_f32 v[30:31], v[30:31], v[50:51]
	ds_read_b128 v[50:53], v56 offset:32784
	v_add_u32_e32 v56, 32, v56
	s_waitcnt lgkmcnt(0)
	v_pk_mul_f32 v[38:39], v[38:39], v[50:51] op_sel:[0,1]
	v_pk_mul_f32 v[40:41], v[40:41], v[50:51] op_sel:[0,1]
	v_pk_fma_f32 v[34:35], v[34:35], v[50:51], v[38:39] op_sel_hi:[1,0,1]
	v_mov_b32_e32 v38, v53
	v_pk_fma_f32 v[36:37], v[36:37], v[50:51], v[40:41] op_sel_hi:[1,0,1]
	v_pk_mul_f32 v[40:41], v[48:49], v[38:39] op_sel_hi:[1,0]
	v_pk_mul_f32 v[38:39], v[46:47], v[38:39] op_sel_hi:[1,0]
	v_pk_fma_f32 v[40:41], v[44:45], v[52:53], v[40:41] op_sel_hi:[1,0,1]
	v_pk_fma_f32 v[38:39], v[42:43], v[52:53], v[38:39] op_sel_hi:[1,0,1]
	v_pk_add_f32 v[36:37], v[36:37], v[40:41]
	v_pk_add_f32 v[34:35], v[34:35], v[38:39]
	v_pk_add_f32 v[36:37], v[74:75], v[36:37]
	v_pk_add_f32 v[34:35], v[76:77], v[34:35]
	v_pk_mov_b32 v[38:39], v[218:219], v[218:219] op_sel:[0,1]
	v_pk_mov_b32 v[40:41], v[220:221], v[220:221] op_sel:[0,1]
	v_pk_mov_b32 v[42:43], v[222:223], v[222:223] op_sel:[0,1]
	v_pk_mov_b32 v[44:45], v[224:225], v[224:225] op_sel:[0,1]
	v_pk_mov_b32 v[74:75], v[226:227], v[226:227] op_sel:[0,1]
	v_pk_mov_b32 v[76:77], v[228:229], v[228:229] op_sel:[0,1]
	v_pk_mov_b32 v[102:103], v[230:231], v[230:231] op_sel:[0,1]
	v_pk_mov_b32 v[104:105], v[232:233], v[232:233] op_sel:[0,1]
	ds_read_b128 v[106:109], v56
	ds_read_b128 v[50:53], v56 offset:16
	s_waitcnt lgkmcnt(1)
	v_pk_mul_f32 v[48:49], v[44:45], v[106:107] op_sel:[0,1]
	v_pk_mul_f32 v[110:111], v[42:43], v[106:107] op_sel:[0,1]
	v_pk_fma_f32 v[48:49], v[40:41], v[106:107], v[48:49] op_sel_hi:[1,0,1]
	v_pk_fma_f32 v[106:107], v[38:39], v[106:107], v[110:111] op_sel_hi:[1,0,1]
	v_mov_b32_e32 v110, v109
	v_pk_mul_f32 v[112:113], v[104:105], v[110:111] op_sel_hi:[1,0]
	v_pk_mul_f32 v[110:111], v[102:103], v[110:111] op_sel_hi:[1,0]
	v_pk_fma_f32 v[112:113], v[76:77], v[108:109], v[112:113] op_sel_hi:[1,0,1]
	v_pk_fma_f32 v[108:109], v[74:75], v[108:109], v[110:111] op_sel_hi:[1,0,1]
	v_pk_add_f32 v[48:49], v[48:49], v[112:113]
	v_pk_add_f32 v[106:107], v[106:107], v[108:109]
	v_pk_add_f32 v[4:5], v[4:5], v[48:49]
	v_pk_add_f32 v[2:3], v[2:3], v[106:107]
	ds_read_b128 v[106:109], v56 offset:4096
	s_waitcnt lgkmcnt(0)
	v_pk_mul_f32 v[48:49], v[44:45], v[106:107] op_sel:[0,1]
	v_pk_mul_f32 v[110:111], v[42:43], v[106:107] op_sel:[0,1]
	v_pk_fma_f32 v[48:49], v[40:41], v[106:107], v[48:49] op_sel_hi:[1,0,1]
	v_pk_fma_f32 v[106:107], v[38:39], v[106:107], v[110:111] op_sel_hi:[1,0,1]
	v_mov_b32_e32 v110, v109
	v_pk_mul_f32 v[112:113], v[104:105], v[110:111] op_sel_hi:[1,0]
	v_pk_mul_f32 v[110:111], v[102:103], v[110:111] op_sel_hi:[1,0]
	v_pk_fma_f32 v[112:113], v[76:77], v[108:109], v[112:113] op_sel_hi:[1,0,1]
	v_pk_fma_f32 v[108:109], v[74:75], v[108:109], v[110:111] op_sel_hi:[1,0,1]
	v_pk_add_f32 v[48:49], v[48:49], v[112:113]
	v_pk_add_f32 v[106:107], v[106:107], v[108:109]
	v_pk_add_f32 v[8:9], v[8:9], v[48:49]
	v_pk_add_f32 v[6:7], v[6:7], v[106:107]
	ds_read_b128 v[106:109], v56 offset:8192
	s_waitcnt lgkmcnt(0)
	v_pk_mul_f32 v[48:49], v[44:45], v[106:107] op_sel:[0,1]
	v_pk_mul_f32 v[110:111], v[42:43], v[106:107] op_sel:[0,1]
	v_pk_fma_f32 v[48:49], v[40:41], v[106:107], v[48:49] op_sel_hi:[1,0,1]
	v_pk_fma_f32 v[106:107], v[38:39], v[106:107], v[110:111] op_sel_hi:[1,0,1]
	v_mov_b32_e32 v110, v109
	v_pk_mul_f32 v[112:113], v[104:105], v[110:111] op_sel_hi:[1,0]
	v_pk_mul_f32 v[110:111], v[102:103], v[110:111] op_sel_hi:[1,0]
	v_pk_fma_f32 v[112:113], v[76:77], v[108:109], v[112:113] op_sel_hi:[1,0,1]
	v_pk_fma_f32 v[108:109], v[74:75], v[108:109], v[110:111] op_sel_hi:[1,0,1]
	v_pk_add_f32 v[48:49], v[48:49], v[112:113]
	v_pk_add_f32 v[106:107], v[106:107], v[108:109]
	v_pk_add_f32 v[12:13], v[12:13], v[48:49]
	v_pk_add_f32 v[10:11], v[10:11], v[106:107]
	ds_read_b128 v[106:109], v56 offset:12288
	s_waitcnt lgkmcnt(0)
	v_pk_mul_f32 v[48:49], v[44:45], v[106:107] op_sel:[0,1]
	v_pk_mul_f32 v[110:111], v[42:43], v[106:107] op_sel:[0,1]
	v_pk_fma_f32 v[48:49], v[40:41], v[106:107], v[48:49] op_sel_hi:[1,0,1]
	v_pk_fma_f32 v[106:107], v[38:39], v[106:107], v[110:111] op_sel_hi:[1,0,1]
	v_mov_b32_e32 v110, v109
	v_pk_mul_f32 v[112:113], v[104:105], v[110:111] op_sel_hi:[1,0]
	v_pk_mul_f32 v[110:111], v[102:103], v[110:111] op_sel_hi:[1,0]
	v_pk_fma_f32 v[112:113], v[76:77], v[108:109], v[112:113] op_sel_hi:[1,0,1]
	v_pk_fma_f32 v[108:109], v[74:75], v[108:109], v[110:111] op_sel_hi:[1,0,1]
	v_pk_add_f32 v[48:49], v[48:49], v[112:113]
	v_pk_add_f32 v[106:107], v[106:107], v[108:109]
	v_pk_add_f32 v[16:17], v[16:17], v[48:49]
	v_pk_add_f32 v[14:15], v[14:15], v[106:107]
	ds_read_b128 v[106:109], v56 offset:16384
	s_waitcnt lgkmcnt(0)
	v_pk_mul_f32 v[48:49], v[44:45], v[106:107] op_sel:[0,1]
	v_pk_mul_f32 v[110:111], v[42:43], v[106:107] op_sel:[0,1]
	v_pk_fma_f32 v[48:49], v[40:41], v[106:107], v[48:49] op_sel_hi:[1,0,1]
	v_pk_fma_f32 v[106:107], v[38:39], v[106:107], v[110:111] op_sel_hi:[1,0,1]
	v_mov_b32_e32 v110, v109
	v_pk_mul_f32 v[112:113], v[104:105], v[110:111] op_sel_hi:[1,0]
	v_pk_mul_f32 v[110:111], v[102:103], v[110:111] op_sel_hi:[1,0]
	v_pk_fma_f32 v[112:113], v[76:77], v[108:109], v[112:113] op_sel_hi:[1,0,1]
	v_pk_fma_f32 v[108:109], v[74:75], v[108:109], v[110:111] op_sel_hi:[1,0,1]
	v_pk_add_f32 v[48:49], v[48:49], v[112:113]
	v_pk_add_f32 v[106:107], v[106:107], v[108:109]
	v_pk_add_f32 v[20:21], v[20:21], v[48:49]
	v_pk_add_f32 v[18:19], v[18:19], v[106:107]
	ds_read_b128 v[106:109], v56 offset:20480
	s_waitcnt lgkmcnt(0)
	v_pk_mul_f32 v[48:49], v[44:45], v[106:107] op_sel:[0,1]
	v_pk_mul_f32 v[110:111], v[42:43], v[106:107] op_sel:[0,1]
	v_pk_fma_f32 v[48:49], v[40:41], v[106:107], v[48:49] op_sel_hi:[1,0,1]
	v_pk_fma_f32 v[106:107], v[38:39], v[106:107], v[110:111] op_sel_hi:[1,0,1]
	v_mov_b32_e32 v110, v109
	v_pk_mul_f32 v[112:113], v[104:105], v[110:111] op_sel_hi:[1,0]
	v_pk_mul_f32 v[110:111], v[102:103], v[110:111] op_sel_hi:[1,0]
	v_pk_fma_f32 v[112:113], v[76:77], v[108:109], v[112:113] op_sel_hi:[1,0,1]
	v_pk_fma_f32 v[108:109], v[74:75], v[108:109], v[110:111] op_sel_hi:[1,0,1]
	v_pk_add_f32 v[48:49], v[48:49], v[112:113]
	v_pk_add_f32 v[106:107], v[106:107], v[108:109]
	v_pk_add_f32 v[24:25], v[24:25], v[48:49]
	v_pk_add_f32 v[22:23], v[22:23], v[106:107]
	ds_read_b128 v[106:109], v56 offset:24576
	s_waitcnt lgkmcnt(0)
	v_pk_mul_f32 v[48:49], v[44:45], v[106:107] op_sel:[0,1]
	v_pk_mul_f32 v[110:111], v[42:43], v[106:107] op_sel:[0,1]
	v_pk_fma_f32 v[48:49], v[40:41], v[106:107], v[48:49] op_sel_hi:[1,0,1]
	v_pk_fma_f32 v[106:107], v[38:39], v[106:107], v[110:111] op_sel_hi:[1,0,1]
	v_mov_b32_e32 v110, v109
	v_pk_mul_f32 v[112:113], v[104:105], v[110:111] op_sel_hi:[1,0]
	v_pk_mul_f32 v[110:111], v[102:103], v[110:111] op_sel_hi:[1,0]
	v_pk_fma_f32 v[112:113], v[76:77], v[108:109], v[112:113] op_sel_hi:[1,0,1]
	v_pk_fma_f32 v[108:109], v[74:75], v[108:109], v[110:111] op_sel_hi:[1,0,1]
	v_pk_add_f32 v[48:49], v[48:49], v[112:113]
	v_pk_add_f32 v[106:107], v[106:107], v[108:109]
	v_pk_add_f32 v[28:29], v[28:29], v[48:49]
	v_pk_add_f32 v[26:27], v[26:27], v[106:107]
	ds_read_b128 v[106:109], v56 offset:28672
	s_waitcnt lgkmcnt(0)
	v_pk_mul_f32 v[48:49], v[44:45], v[106:107] op_sel:[0,1]
	v_pk_mul_f32 v[110:111], v[42:43], v[106:107] op_sel:[0,1]
	v_pk_fma_f32 v[48:49], v[40:41], v[106:107], v[48:49] op_sel_hi:[1,0,1]
	v_pk_fma_f32 v[106:107], v[38:39], v[106:107], v[110:111] op_sel_hi:[1,0,1]
	v_mov_b32_e32 v110, v109
	v_pk_mul_f32 v[112:113], v[104:105], v[110:111] op_sel_hi:[1,0]
	v_pk_mul_f32 v[110:111], v[102:103], v[110:111] op_sel_hi:[1,0]
	v_pk_fma_f32 v[112:113], v[76:77], v[108:109], v[112:113] op_sel_hi:[1,0,1]
	v_pk_fma_f32 v[108:109], v[74:75], v[108:109], v[110:111] op_sel_hi:[1,0,1]
	v_pk_add_f32 v[48:49], v[48:49], v[112:113]
	v_pk_add_f32 v[106:107], v[106:107], v[108:109]
	v_pk_add_f32 v[32:33], v[32:33], v[48:49]
	v_pk_add_f32 v[30:31], v[30:31], v[106:107]
	ds_read_b128 v[106:109], v56 offset:32768
	s_waitcnt lgkmcnt(0)
	v_pk_mul_f32 v[42:43], v[42:43], v[106:107] op_sel:[0,1]
	v_pk_mul_f32 v[44:45], v[44:45], v[106:107] op_sel:[0,1]
	v_pk_fma_f32 v[38:39], v[38:39], v[106:107], v[42:43] op_sel_hi:[1,0,1]
	v_mov_b32_e32 v42, v109
	v_pk_fma_f32 v[40:41], v[40:41], v[106:107], v[44:45] op_sel_hi:[1,0,1]
	v_pk_mul_f32 v[44:45], v[104:105], v[42:43] op_sel_hi:[1,0]
	v_pk_mul_f32 v[42:43], v[102:103], v[42:43] op_sel_hi:[1,0]
	v_pk_fma_f32 v[44:45], v[76:77], v[108:109], v[44:45] op_sel_hi:[1,0,1]
	v_pk_fma_f32 v[42:43], v[74:75], v[108:109], v[42:43] op_sel_hi:[1,0,1]
	v_pk_add_f32 v[40:41], v[40:41], v[44:45]
	v_pk_add_f32 v[38:39], v[38:39], v[42:43]
	v_pk_add_f32 v[74:75], v[36:37], v[40:41]
	v_pk_add_f32 v[76:77], v[34:35], v[38:39]
	v_pk_mov_b32 v[34:35], v[234:235], v[234:235] op_sel:[0,1]
	v_pk_mov_b32 v[36:37], v[236:237], v[236:237] op_sel:[0,1]
	v_pk_mov_b32 v[38:39], v[238:239], v[238:239] op_sel:[0,1]
	v_pk_mov_b32 v[40:41], v[240:241], v[240:241] op_sel:[0,1]
	v_pk_mov_b32 v[42:43], v[242:243], v[242:243] op_sel:[0,1]
	v_pk_mov_b32 v[44:45], v[244:245], v[244:245] op_sel:[0,1]
	v_pk_mov_b32 v[46:47], v[246:247], v[246:247] op_sel:[0,1]
	v_pk_mov_b32 v[48:49], v[248:249], v[248:249] op_sel:[0,1]
	v_pk_mul_f32 v[102:103], v[40:41], v[50:51] op_sel:[0,1]
	v_pk_mul_f32 v[104:105], v[38:39], v[50:51] op_sel:[0,1]
	v_pk_fma_f32 v[102:103], v[36:37], v[50:51], v[102:103] op_sel_hi:[1,0,1]
	v_pk_fma_f32 v[50:51], v[34:35], v[50:51], v[104:105] op_sel_hi:[1,0,1]
	v_mov_b32_e32 v104, v53
	v_pk_mul_f32 v[106:107], v[48:49], v[104:105] op_sel_hi:[1,0]
	v_pk_mul_f32 v[104:105], v[46:47], v[104:105] op_sel_hi:[1,0]
	v_pk_fma_f32 v[106:107], v[44:45], v[52:53], v[106:107] op_sel_hi:[1,0,1]
	v_pk_fma_f32 v[52:53], v[42:43], v[52:53], v[104:105] op_sel_hi:[1,0,1]
	v_pk_add_f32 v[102:103], v[102:103], v[106:107]
	v_pk_add_f32 v[50:51], v[50:51], v[52:53]
	v_pk_add_f32 v[4:5], v[4:5], v[102:103]
	v_pk_add_f32 v[2:3], v[2:3], v[50:51]
	ds_read_b128 v[50:53], v56 offset:4112
	s_waitcnt lgkmcnt(0)
	v_pk_mul_f32 v[102:103], v[40:41], v[50:51] op_sel:[0,1]
	v_pk_mul_f32 v[104:105], v[38:39], v[50:51] op_sel:[0,1]
	v_pk_fma_f32 v[102:103], v[36:37], v[50:51], v[102:103] op_sel_hi:[1,0,1]
	v_pk_fma_f32 v[50:51], v[34:35], v[50:51], v[104:105] op_sel_hi:[1,0,1]
	v_mov_b32_e32 v104, v53
	v_pk_mul_f32 v[106:107], v[48:49], v[104:105] op_sel_hi:[1,0]
	v_pk_mul_f32 v[104:105], v[46:47], v[104:105] op_sel_hi:[1,0]
	v_pk_fma_f32 v[106:107], v[44:45], v[52:53], v[106:107] op_sel_hi:[1,0,1]
	v_pk_fma_f32 v[52:53], v[42:43], v[52:53], v[104:105] op_sel_hi:[1,0,1]
	v_pk_add_f32 v[102:103], v[102:103], v[106:107]
	v_pk_add_f32 v[50:51], v[50:51], v[52:53]
	v_pk_add_f32 v[8:9], v[8:9], v[102:103]
	v_pk_add_f32 v[6:7], v[6:7], v[50:51]
	ds_read_b128 v[50:53], v56 offset:8208
	s_waitcnt lgkmcnt(0)
	v_pk_mul_f32 v[102:103], v[40:41], v[50:51] op_sel:[0,1]
	v_pk_mul_f32 v[104:105], v[38:39], v[50:51] op_sel:[0,1]
	v_pk_fma_f32 v[102:103], v[36:37], v[50:51], v[102:103] op_sel_hi:[1,0,1]
	v_pk_fma_f32 v[50:51], v[34:35], v[50:51], v[104:105] op_sel_hi:[1,0,1]
	v_mov_b32_e32 v104, v53
	v_pk_mul_f32 v[106:107], v[48:49], v[104:105] op_sel_hi:[1,0]
	v_pk_mul_f32 v[104:105], v[46:47], v[104:105] op_sel_hi:[1,0]
	v_pk_fma_f32 v[106:107], v[44:45], v[52:53], v[106:107] op_sel_hi:[1,0,1]
	v_pk_fma_f32 v[52:53], v[42:43], v[52:53], v[104:105] op_sel_hi:[1,0,1]
	v_pk_add_f32 v[102:103], v[102:103], v[106:107]
	v_pk_add_f32 v[50:51], v[50:51], v[52:53]
	v_pk_add_f32 v[12:13], v[12:13], v[102:103]
	v_pk_add_f32 v[10:11], v[10:11], v[50:51]
	ds_read_b128 v[50:53], v56 offset:12304
	s_waitcnt lgkmcnt(0)
	v_pk_mul_f32 v[102:103], v[40:41], v[50:51] op_sel:[0,1]
	v_pk_mul_f32 v[104:105], v[38:39], v[50:51] op_sel:[0,1]
	v_pk_fma_f32 v[102:103], v[36:37], v[50:51], v[102:103] op_sel_hi:[1,0,1]
	v_pk_fma_f32 v[50:51], v[34:35], v[50:51], v[104:105] op_sel_hi:[1,0,1]
	v_mov_b32_e32 v104, v53
	v_pk_mul_f32 v[106:107], v[48:49], v[104:105] op_sel_hi:[1,0]
	v_pk_mul_f32 v[104:105], v[46:47], v[104:105] op_sel_hi:[1,0]
	v_pk_fma_f32 v[106:107], v[44:45], v[52:53], v[106:107] op_sel_hi:[1,0,1]
	v_pk_fma_f32 v[52:53], v[42:43], v[52:53], v[104:105] op_sel_hi:[1,0,1]
	v_pk_add_f32 v[102:103], v[102:103], v[106:107]
	v_pk_add_f32 v[50:51], v[50:51], v[52:53]
	v_pk_add_f32 v[16:17], v[16:17], v[102:103]
	v_pk_add_f32 v[14:15], v[14:15], v[50:51]
	ds_read_b128 v[50:53], v56 offset:16400
	s_waitcnt lgkmcnt(0)
	v_pk_mul_f32 v[102:103], v[40:41], v[50:51] op_sel:[0,1]
	v_pk_mul_f32 v[104:105], v[38:39], v[50:51] op_sel:[0,1]
	v_pk_fma_f32 v[102:103], v[36:37], v[50:51], v[102:103] op_sel_hi:[1,0,1]
	v_pk_fma_f32 v[50:51], v[34:35], v[50:51], v[104:105] op_sel_hi:[1,0,1]
	v_mov_b32_e32 v104, v53
	v_pk_mul_f32 v[106:107], v[48:49], v[104:105] op_sel_hi:[1,0]
	v_pk_mul_f32 v[104:105], v[46:47], v[104:105] op_sel_hi:[1,0]
	v_pk_fma_f32 v[106:107], v[44:45], v[52:53], v[106:107] op_sel_hi:[1,0,1]
	v_pk_fma_f32 v[52:53], v[42:43], v[52:53], v[104:105] op_sel_hi:[1,0,1]
	v_pk_add_f32 v[102:103], v[102:103], v[106:107]
	v_pk_add_f32 v[50:51], v[50:51], v[52:53]
	v_pk_add_f32 v[20:21], v[20:21], v[102:103]
	v_pk_add_f32 v[18:19], v[18:19], v[50:51]
	ds_read_b128 v[50:53], v56 offset:20496
	s_waitcnt lgkmcnt(0)
	v_pk_mul_f32 v[102:103], v[40:41], v[50:51] op_sel:[0,1]
	v_pk_mul_f32 v[104:105], v[38:39], v[50:51] op_sel:[0,1]
	v_pk_fma_f32 v[102:103], v[36:37], v[50:51], v[102:103] op_sel_hi:[1,0,1]
	v_pk_fma_f32 v[50:51], v[34:35], v[50:51], v[104:105] op_sel_hi:[1,0,1]
	v_mov_b32_e32 v104, v53
	v_pk_mul_f32 v[106:107], v[48:49], v[104:105] op_sel_hi:[1,0]
	v_pk_mul_f32 v[104:105], v[46:47], v[104:105] op_sel_hi:[1,0]
	v_pk_fma_f32 v[106:107], v[44:45], v[52:53], v[106:107] op_sel_hi:[1,0,1]
	v_pk_fma_f32 v[52:53], v[42:43], v[52:53], v[104:105] op_sel_hi:[1,0,1]
	v_pk_add_f32 v[102:103], v[102:103], v[106:107]
	v_pk_add_f32 v[50:51], v[50:51], v[52:53]
	v_pk_add_f32 v[24:25], v[24:25], v[102:103]
	v_pk_add_f32 v[22:23], v[22:23], v[50:51]
	ds_read_b128 v[50:53], v56 offset:24592
	s_waitcnt lgkmcnt(0)
	v_pk_mul_f32 v[102:103], v[40:41], v[50:51] op_sel:[0,1]
	v_pk_mul_f32 v[104:105], v[38:39], v[50:51] op_sel:[0,1]
	v_pk_fma_f32 v[102:103], v[36:37], v[50:51], v[102:103] op_sel_hi:[1,0,1]
	v_pk_fma_f32 v[50:51], v[34:35], v[50:51], v[104:105] op_sel_hi:[1,0,1]
	v_mov_b32_e32 v104, v53
	v_pk_mul_f32 v[106:107], v[48:49], v[104:105] op_sel_hi:[1,0]
	v_pk_mul_f32 v[104:105], v[46:47], v[104:105] op_sel_hi:[1,0]
	v_pk_fma_f32 v[106:107], v[44:45], v[52:53], v[106:107] op_sel_hi:[1,0,1]
	v_pk_fma_f32 v[52:53], v[42:43], v[52:53], v[104:105] op_sel_hi:[1,0,1]
	v_pk_add_f32 v[102:103], v[102:103], v[106:107]
	v_pk_add_f32 v[50:51], v[50:51], v[52:53]
	v_pk_add_f32 v[28:29], v[28:29], v[102:103]
	v_pk_add_f32 v[26:27], v[26:27], v[50:51]
	ds_read_b128 v[50:53], v56 offset:28688
	s_waitcnt lgkmcnt(0)
	v_pk_mul_f32 v[102:103], v[40:41], v[50:51] op_sel:[0,1]
	v_pk_mul_f32 v[104:105], v[38:39], v[50:51] op_sel:[0,1]
	v_pk_fma_f32 v[102:103], v[36:37], v[50:51], v[102:103] op_sel_hi:[1,0,1]
	v_pk_fma_f32 v[50:51], v[34:35], v[50:51], v[104:105] op_sel_hi:[1,0,1]
	v_mov_b32_e32 v104, v53
	v_pk_mul_f32 v[106:107], v[48:49], v[104:105] op_sel_hi:[1,0]
	v_pk_mul_f32 v[104:105], v[46:47], v[104:105] op_sel_hi:[1,0]
	v_pk_fma_f32 v[106:107], v[44:45], v[52:53], v[106:107] op_sel_hi:[1,0,1]
	v_pk_fma_f32 v[52:53], v[42:43], v[52:53], v[104:105] op_sel_hi:[1,0,1]
	v_pk_add_f32 v[102:103], v[102:103], v[106:107]
	v_pk_add_f32 v[50:51], v[50:51], v[52:53]
	v_pk_add_f32 v[32:33], v[32:33], v[102:103]
	v_pk_add_f32 v[30:31], v[30:31], v[50:51]
	ds_read_b128 v[50:53], v56 offset:32784
	v_add_u32_e32 v56, 32, v56
	s_waitcnt lgkmcnt(0)
	v_pk_mul_f32 v[38:39], v[38:39], v[50:51] op_sel:[0,1]
	v_pk_mul_f32 v[40:41], v[40:41], v[50:51] op_sel:[0,1]
	v_pk_fma_f32 v[34:35], v[34:35], v[50:51], v[38:39] op_sel_hi:[1,0,1]
	v_mov_b32_e32 v38, v53
	v_pk_fma_f32 v[36:37], v[36:37], v[50:51], v[40:41] op_sel_hi:[1,0,1]
	v_pk_mul_f32 v[40:41], v[48:49], v[38:39] op_sel_hi:[1,0]
	v_pk_mul_f32 v[38:39], v[46:47], v[38:39] op_sel_hi:[1,0]
	v_pk_fma_f32 v[40:41], v[44:45], v[52:53], v[40:41] op_sel_hi:[1,0,1]
	v_pk_fma_f32 v[38:39], v[42:43], v[52:53], v[38:39] op_sel_hi:[1,0,1]
	v_pk_add_f32 v[36:37], v[36:37], v[40:41]
	v_pk_add_f32 v[34:35], v[34:35], v[38:39]
	v_pk_add_f32 v[36:37], v[74:75], v[36:37]
	v_pk_add_f32 v[34:35], v[76:77], v[34:35]
	s_mul_i32 s7, s38, 0x1800
	s_add_i32 s7, s7, s6
	ds_write_b128 v99, v[2:5] offset:36864
	ds_write_b128 v99, v[6:9] offset:37376
	ds_write_b128 v99, v[10:13] offset:37888
	ds_write_b128 v99, v[14:17] offset:38400
	ds_write_b128 v99, v[18:21] offset:38912
	ds_write_b128 v99, v[22:25] offset:39424
	ds_write_b128 v99, v[26:29] offset:39936
	ds_write_b128 v99, v[30:33] offset:40448
	ds_write_b128 v99, v[34:37] offset:40960
	v_or_b32_e32 v2, s7, v82
	v_mad_u64_u32 v[4:5], s[6:7], s38, 9, v[68:69]
	v_mov_b64_e32 v[6:7], s[78:79]
	v_ashrrev_i32_e32 v3, 31, v2
	v_mad_i64_i32 v[4:5], s[6:7], v4, s91, v[6:7]
	v_lshl_add_u64 v[2:3], v[2:3], 2, s[46:47]
	v_lshl_add_u64 v[4:5], v[66:67], 0, v[4:5]
	s_mov_b64 s[6:7], 0
	v_mov_b32_e32 v6, v97
	v_mov_b32_e32 v7, v95
	s_waitcnt lgkmcnt(0)
	s_barrier
